# scan inner loop: next-step LDS reads issued before the step's operand wait (wait moved to first consumer, counted lgkmcnt 7)
# speedup vs baseline: 1.0015x; 1.0015x over previous
.LBB0_985:
	s_and_saveexec_b64 s[24:25], s[16:17]
	s_cbranch_execz .LBB0_988
	ds_read_b128 v[30:33], v161 offset:8192
	ds_read_b128 v[34:37], v161 offset:16384
	ds_read_b128 v[46:49], v161 offset:24576
	ds_read_b64 v[80:81], v82 offset:40960
	ds_read_b128 v[38:41], v161
	ds_read_b128 v[42:45], v161 offset:32768
	ds_read_b128 v[84:87], v161 offset:8448
	ds_read_b128 v[88:91], v161 offset:16640
	ds_read_b128 v[100:103], v161 offset:24832
	ds_read_b64 v[104:105], v82 offset:41216
	ds_read_b128 v[92:95], v161 offset:256
	ds_read_b128 v[96:99], v161 offset:33024
	s_waitcnt lgkmcnt(6)
	v_pk_mul_f32 v[106:107], v[72:73], v[30:31]
	v_pk_mul_f32 v[108:109], v[76:77], v[30:31]
	v_pk_fma_f32 v[106:107], v[74:75], v[32:33], v[106:107]
	v_pk_fma_f32 v[108:109], v[78:79], v[32:33], v[108:109]
	v_add_f32_e32 v110, v106, v107
	v_add_f32_e32 v112, v108, v109
	s_nop 0
	v_add_f32_dpp v110, v110, v110 quad_perm:[1,0,3,2] row_mask:0xf bank_mask:0xf bound_ctrl:1
	v_add_f32_dpp v112, v112, v112 quad_perm:[1,0,3,2] row_mask:0xf bank_mask:0xf bound_ctrl:1
	s_nop 0
	v_add_f32_dpp v110, v110, v110 quad_perm:[2,3,0,1] row_mask:0xf bank_mask:0xf bound_ctrl:1
	v_add_f32_dpp v112, v112, v112 quad_perm:[2,3,0,1] row_mask:0xf bank_mask:0xf bound_ctrl:1
	s_nop 0
	v_add_f32_dpp v110, v110, v110 row_half_mirror row_mask:0xf bank_mask:0xf bound_ctrl:1
	v_add_f32_dpp v112, v112, v112 row_half_mirror row_mask:0xf bank_mask:0xf bound_ctrl:1
	s_nop 0
	v_add_f32_dpp v110, v110, v110 row_ror:8 row_mask:0xf bank_mask:0xf bound_ctrl:1
	v_add_f32_dpp v112, v112, v112 row_ror:8 row_mask:0xf bank_mask:0xf bound_ctrl:1
	v_pk_mul_f32 v[114:115], v[34:35], v[110:111] op_sel_hi:[1,0]
	v_pk_mul_f32 v[116:117], v[34:35], v[112:113] op_sel_hi:[1,0]
	v_pk_mul_f32 v[118:119], v[36:37], v[110:111] op_sel_hi:[1,0]
	v_pk_mul_f32 v[120:121], v[36:37], v[112:113] op_sel_hi:[1,0]
	v_pk_fma_f32 v[114:115], v[46:47], v[80:81], v[114:115] op_sel_hi:[1,0,1]
	v_pk_fma_f32 v[116:117], v[46:47], v[80:81], v[116:117] op_sel:[0,1,0]
	v_pk_fma_f32 v[118:119], v[48:49], v[80:81], v[118:119] op_sel_hi:[1,0,1]
	v_pk_fma_f32 v[120:121], v[48:49], v[80:81], v[120:121] op_sel:[0,1,0]
	v_pk_fma_f32 v[72:73], v[72:73], v[38:39], v[114:115]
	v_pk_fma_f32 v[76:77], v[76:77], v[38:39], v[116:117]
	v_pk_fma_f32 v[74:75], v[74:75], v[40:41], v[118:119]
	v_pk_fma_f32 v[78:79], v[78:79], v[40:41], v[120:121]
	v_pk_mul_f32 v[122:123], v[72:73], v[42:43]
	v_pk_mul_f32 v[124:125], v[76:77], v[42:43]
	v_pk_fma_f32 v[122:123], v[74:75], v[44:45], v[122:123]
	v_pk_fma_f32 v[124:125], v[78:79], v[44:45], v[124:125]
	v_add_f32_e32 v126, v122, v123
	v_add_f32_e32 v127, v124, v125
	ds_write_b64 v187, v[126:127]
	ds_read_b128 v[30:33], v161 offset:8704
	ds_read_b128 v[34:37], v161 offset:16896
	ds_read_b128 v[46:49], v161 offset:25088
	ds_read_b64 v[80:81], v82 offset:41472
	ds_read_b128 v[38:41], v161 offset:512
	ds_read_b128 v[42:45], v161 offset:33280
	s_waitcnt lgkmcnt(7)
	v_pk_mul_f32 v[106:107], v[72:73], v[84:85]
	v_pk_mul_f32 v[108:109], v[76:77], v[84:85]
	v_pk_fma_f32 v[106:107], v[74:75], v[86:87], v[106:107]
	v_pk_fma_f32 v[108:109], v[78:79], v[86:87], v[108:109]
	v_add_f32_e32 v110, v106, v107
	v_add_f32_e32 v112, v108, v109
	s_nop 0
	v_add_f32_dpp v110, v110, v110 quad_perm:[1,0,3,2] row_mask:0xf bank_mask:0xf bound_ctrl:1
	v_add_f32_dpp v112, v112, v112 quad_perm:[1,0,3,2] row_mask:0xf bank_mask:0xf bound_ctrl:1
	s_nop 0
	v_add_f32_dpp v110, v110, v110 quad_perm:[2,3,0,1] row_mask:0xf bank_mask:0xf bound_ctrl:1
	v_add_f32_dpp v112, v112, v112 quad_perm:[2,3,0,1] row_mask:0xf bank_mask:0xf bound_ctrl:1
	s_nop 0
	v_add_f32_dpp v110, v110, v110 row_half_mirror row_mask:0xf bank_mask:0xf bound_ctrl:1
	v_add_f32_dpp v112, v112, v112 row_half_mirror row_mask:0xf bank_mask:0xf bound_ctrl:1
	s_nop 0
	v_add_f32_dpp v110, v110, v110 row_ror:8 row_mask:0xf bank_mask:0xf bound_ctrl:1
	v_add_f32_dpp v112, v112, v112 row_ror:8 row_mask:0xf bank_mask:0xf bound_ctrl:1
	v_pk_mul_f32 v[114:115], v[88:89], v[110:111] op_sel_hi:[1,0]
	v_pk_mul_f32 v[116:117], v[88:89], v[112:113] op_sel_hi:[1,0]
	v_pk_mul_f32 v[118:119], v[90:91], v[110:111] op_sel_hi:[1,0]
	v_pk_mul_f32 v[120:121], v[90:91], v[112:113] op_sel_hi:[1,0]
	v_pk_fma_f32 v[114:115], v[100:101], v[104:105], v[114:115] op_sel_hi:[1,0,1]
	v_pk_fma_f32 v[116:117], v[100:101], v[104:105], v[116:117] op_sel:[0,1,0]
	v_pk_fma_f32 v[118:119], v[102:103], v[104:105], v[118:119] op_sel_hi:[1,0,1]
	v_pk_fma_f32 v[120:121], v[102:103], v[104:105], v[120:121] op_sel:[0,1,0]
	v_pk_fma_f32 v[72:73], v[72:73], v[92:93], v[114:115]
	v_pk_fma_f32 v[76:77], v[76:77], v[92:93], v[116:117]
	v_pk_fma_f32 v[74:75], v[74:75], v[94:95], v[118:119]
	v_pk_fma_f32 v[78:79], v[78:79], v[94:95], v[120:121]
	v_pk_mul_f32 v[122:123], v[72:73], v[96:97]
	v_pk_mul_f32 v[124:125], v[76:77], v[96:97]
	v_pk_fma_f32 v[122:123], v[74:75], v[98:99], v[122:123]
	v_pk_fma_f32 v[124:125], v[78:79], v[98:99], v[124:125]
	v_add_f32_e32 v126, v122, v123
	v_add_f32_e32 v127, v124, v125
	ds_write_b64 v187, v[126:127] offset:2048
	ds_read_b128 v[84:87], v161 offset:8960
	ds_read_b128 v[88:91], v161 offset:17152
	ds_read_b128 v[100:103], v161 offset:25344
	ds_read_b64 v[104:105], v82 offset:41728
	ds_read_b128 v[92:95], v161 offset:768
	ds_read_b128 v[96:99], v161 offset:33536
	s_waitcnt lgkmcnt(7)
	v_pk_mul_f32 v[106:107], v[72:73], v[30:31]
	v_pk_mul_f32 v[108:109], v[76:77], v[30:31]
	v_pk_fma_f32 v[106:107], v[74:75], v[32:33], v[106:107]
	v_pk_fma_f32 v[108:109], v[78:79], v[32:33], v[108:109]
	v_add_f32_e32 v110, v106, v107
	v_add_f32_e32 v112, v108, v109
	s_nop 0
	v_add_f32_dpp v110, v110, v110 quad_perm:[1,0,3,2] row_mask:0xf bank_mask:0xf bound_ctrl:1
	v_add_f32_dpp v112, v112, v112 quad_perm:[1,0,3,2] row_mask:0xf bank_mask:0xf bound_ctrl:1
	s_nop 0
	v_add_f32_dpp v110, v110, v110 quad_perm:[2,3,0,1] row_mask:0xf bank_mask:0xf bound_ctrl:1
	v_add_f32_dpp v112, v112, v112 quad_perm:[2,3,0,1] row_mask:0xf bank_mask:0xf bound_ctrl:1
	s_nop 0
	v_add_f32_dpp v110, v110, v110 row_half_mirror row_mask:0xf bank_mask:0xf bound_ctrl:1
	v_add_f32_dpp v112, v112, v112 row_half_mirror row_mask:0xf bank_mask:0xf bound_ctrl:1
	s_nop 0
	v_add_f32_dpp v110, v110, v110 row_ror:8 row_mask:0xf bank_mask:0xf bound_ctrl:1
	v_add_f32_dpp v112, v112, v112 row_ror:8 row_mask:0xf bank_mask:0xf bound_ctrl:1
	v_pk_mul_f32 v[114:115], v[34:35], v[110:111] op_sel_hi:[1,0]
	v_pk_mul_f32 v[116:117], v[34:35], v[112:113] op_sel_hi:[1,0]
	v_pk_mul_f32 v[118:119], v[36:37], v[110:111] op_sel_hi:[1,0]
	v_pk_mul_f32 v[120:121], v[36:37], v[112:113] op_sel_hi:[1,0]
	v_pk_fma_f32 v[114:115], v[46:47], v[80:81], v[114:115] op_sel_hi:[1,0,1]
	v_pk_fma_f32 v[116:117], v[46:47], v[80:81], v[116:117] op_sel:[0,1,0]
	v_pk_fma_f32 v[118:119], v[48:49], v[80:81], v[118:119] op_sel_hi:[1,0,1]
	v_pk_fma_f32 v[120:121], v[48:49], v[80:81], v[120:121] op_sel:[0,1,0]
	v_pk_fma_f32 v[72:73], v[72:73], v[38:39], v[114:115]
	v_pk_fma_f32 v[76:77], v[76:77], v[38:39], v[116:117]
	v_pk_fma_f32 v[74:75], v[74:75], v[40:41], v[118:119]
	v_pk_fma_f32 v[78:79], v[78:79], v[40:41], v[120:121]
	v_pk_mul_f32 v[122:123], v[72:73], v[42:43]
	v_pk_mul_f32 v[124:125], v[76:77], v[42:43]
	v_pk_fma_f32 v[122:123], v[74:75], v[44:45], v[122:123]
	v_pk_fma_f32 v[124:125], v[78:79], v[44:45], v[124:125]
	v_add_f32_e32 v126, v122, v123
	v_add_f32_e32 v127, v124, v125
	ds_write_b64 v187, v[126:127] offset:4096
	ds_read_b128 v[30:33], v161 offset:9216
	ds_read_b128 v[34:37], v161 offset:17408
	ds_read_b128 v[46:49], v161 offset:25600
	ds_read_b64 v[80:81], v82 offset:41984
	ds_read_b128 v[38:41], v161 offset:1024
	ds_read_b128 v[42:45], v161 offset:33792
	s_waitcnt lgkmcnt(7)
	v_pk_mul_f32 v[106:107], v[72:73], v[84:85]
	v_pk_mul_f32 v[108:109], v[76:77], v[84:85]
	v_pk_fma_f32 v[106:107], v[74:75], v[86:87], v[106:107]
	v_pk_fma_f32 v[108:109], v[78:79], v[86:87], v[108:109]
	v_add_f32_e32 v110, v106, v107
	v_add_f32_e32 v112, v108, v109
	s_nop 0
	v_add_f32_dpp v110, v110, v110 quad_perm:[1,0,3,2] row_mask:0xf bank_mask:0xf bound_ctrl:1
	v_add_f32_dpp v112, v112, v112 quad_perm:[1,0,3,2] row_mask:0xf bank_mask:0xf bound_ctrl:1
	s_nop 0
	v_add_f32_dpp v110, v110, v110 quad_perm:[2,3,0,1] row_mask:0xf bank_mask:0xf bound_ctrl:1
	v_add_f32_dpp v112, v112, v112 quad_perm:[2,3,0,1] row_mask:0xf bank_mask:0xf bound_ctrl:1
	s_nop 0
	v_add_f32_dpp v110, v110, v110 row_half_mirror row_mask:0xf bank_mask:0xf bound_ctrl:1
	v_add_f32_dpp v112, v112, v112 row_half_mirror row_mask:0xf bank_mask:0xf bound_ctrl:1
	s_nop 0
	v_add_f32_dpp v110, v110, v110 row_ror:8 row_mask:0xf bank_mask:0xf bound_ctrl:1
	v_add_f32_dpp v112, v112, v112 row_ror:8 row_mask:0xf bank_mask:0xf bound_ctrl:1
	v_pk_mul_f32 v[114:115], v[88:89], v[110:111] op_sel_hi:[1,0]
	v_pk_mul_f32 v[116:117], v[88:89], v[112:113] op_sel_hi:[1,0]
	v_pk_mul_f32 v[118:119], v[90:91], v[110:111] op_sel_hi:[1,0]
	v_pk_mul_f32 v[120:121], v[90:91], v[112:113] op_sel_hi:[1,0]
	v_pk_fma_f32 v[114:115], v[100:101], v[104:105], v[114:115] op_sel_hi:[1,0,1]
	v_pk_fma_f32 v[116:117], v[100:101], v[104:105], v[116:117] op_sel:[0,1,0]
	v_pk_fma_f32 v[118:119], v[102:103], v[104:105], v[118:119] op_sel_hi:[1,0,1]
	v_pk_fma_f32 v[120:121], v[102:103], v[104:105], v[120:121] op_sel:[0,1,0]
	v_pk_fma_f32 v[72:73], v[72:73], v[92:93], v[114:115]
	v_pk_fma_f32 v[76:77], v[76:77], v[92:93], v[116:117]
	v_pk_fma_f32 v[74:75], v[74:75], v[94:95], v[118:119]
	v_pk_fma_f32 v[78:79], v[78:79], v[94:95], v[120:121]
	v_pk_mul_f32 v[122:123], v[72:73], v[96:97]
	v_pk_mul_f32 v[124:125], v[76:77], v[96:97]
	v_pk_fma_f32 v[122:123], v[74:75], v[98:99], v[122:123]
	v_pk_fma_f32 v[124:125], v[78:79], v[98:99], v[124:125]
	v_add_f32_e32 v126, v122, v123
	v_add_f32_e32 v127, v124, v125
	ds_write_b64 v187, v[126:127] offset:6144
	ds_read_b128 v[84:87], v161 offset:9472
	ds_read_b128 v[88:91], v161 offset:17664
	ds_read_b128 v[100:103], v161 offset:25856
	ds_read_b64 v[104:105], v82 offset:42240
	ds_read_b128 v[92:95], v161 offset:1280
	ds_read_b128 v[96:99], v161 offset:34048
	s_waitcnt lgkmcnt(7)
	v_pk_mul_f32 v[106:107], v[72:73], v[30:31]
	v_pk_mul_f32 v[108:109], v[76:77], v[30:31]
	v_pk_fma_f32 v[106:107], v[74:75], v[32:33], v[106:107]
	v_pk_fma_f32 v[108:109], v[78:79], v[32:33], v[108:109]
	v_add_f32_e32 v110, v106, v107
	v_add_f32_e32 v112, v108, v109
	s_nop 0
	v_add_f32_dpp v110, v110, v110 quad_perm:[1,0,3,2] row_mask:0xf bank_mask:0xf bound_ctrl:1
	v_add_f32_dpp v112, v112, v112 quad_perm:[1,0,3,2] row_mask:0xf bank_mask:0xf bound_ctrl:1
	s_nop 0
	v_add_f32_dpp v110, v110, v110 quad_perm:[2,3,0,1] row_mask:0xf bank_mask:0xf bound_ctrl:1
	v_add_f32_dpp v112, v112, v112 quad_perm:[2,3,0,1] row_mask:0xf bank_mask:0xf bound_ctrl:1
	s_nop 0
	v_add_f32_dpp v110, v110, v110 row_half_mirror row_mask:0xf bank_mask:0xf bound_ctrl:1
	v_add_f32_dpp v112, v112, v112 row_half_mirror row_mask:0xf bank_mask:0xf bound_ctrl:1
	s_nop 0
	v_add_f32_dpp v110, v110, v110 row_ror:8 row_mask:0xf bank_mask:0xf bound_ctrl:1
	v_add_f32_dpp v112, v112, v112 row_ror:8 row_mask:0xf bank_mask:0xf bound_ctrl:1
	v_pk_mul_f32 v[114:115], v[34:35], v[110:111] op_sel_hi:[1,0]
	v_pk_mul_f32 v[116:117], v[34:35], v[112:113] op_sel_hi:[1,0]
	v_pk_mul_f32 v[118:119], v[36:37], v[110:111] op_sel_hi:[1,0]
	v_pk_mul_f32 v[120:121], v[36:37], v[112:113] op_sel_hi:[1,0]
	v_pk_fma_f32 v[114:115], v[46:47], v[80:81], v[114:115] op_sel_hi:[1,0,1]
	v_pk_fma_f32 v[116:117], v[46:47], v[80:81], v[116:117] op_sel:[0,1,0]
	v_pk_fma_f32 v[118:119], v[48:49], v[80:81], v[118:119] op_sel_hi:[1,0,1]
	v_pk_fma_f32 v[120:121], v[48:49], v[80:81], v[120:121] op_sel:[0,1,0]
	v_pk_fma_f32 v[72:73], v[72:73], v[38:39], v[114:115]
	v_pk_fma_f32 v[76:77], v[76:77], v[38:39], v[116:117]
	v_pk_fma_f32 v[74:75], v[74:75], v[40:41], v[118:119]
	v_pk_fma_f32 v[78:79], v[78:79], v[40:41], v[120:121]
	v_pk_mul_f32 v[122:123], v[72:73], v[42:43]
	v_pk_mul_f32 v[124:125], v[76:77], v[42:43]
	v_pk_fma_f32 v[122:123], v[74:75], v[44:45], v[122:123]
	v_pk_fma_f32 v[124:125], v[78:79], v[44:45], v[124:125]
	v_add_f32_e32 v126, v122, v123
	v_add_f32_e32 v127, v124, v125
	ds_write_b64 v187, v[126:127] offset:8192
	ds_read_b128 v[30:33], v161 offset:9728
	ds_read_b128 v[34:37], v161 offset:17920
	ds_read_b128 v[46:49], v161 offset:26112
	ds_read_b64 v[80:81], v82 offset:42496
	ds_read_b128 v[38:41], v161 offset:1536
	ds_read_b128 v[42:45], v161 offset:34304
	s_waitcnt lgkmcnt(7)
	v_pk_mul_f32 v[106:107], v[72:73], v[84:85]
	v_pk_mul_f32 v[108:109], v[76:77], v[84:85]
	v_pk_fma_f32 v[106:107], v[74:75], v[86:87], v[106:107]
	v_pk_fma_f32 v[108:109], v[78:79], v[86:87], v[108:109]
	v_add_f32_e32 v110, v106, v107
	v_add_f32_e32 v112, v108, v109
	s_nop 0
	v_add_f32_dpp v110, v110, v110 quad_perm:[1,0,3,2] row_mask:0xf bank_mask:0xf bound_ctrl:1
	v_add_f32_dpp v112, v112, v112 quad_perm:[1,0,3,2] row_mask:0xf bank_mask:0xf bound_ctrl:1
	s_nop 0
	v_add_f32_dpp v110, v110, v110 quad_perm:[2,3,0,1] row_mask:0xf bank_mask:0xf bound_ctrl:1
	v_add_f32_dpp v112, v112, v112 quad_perm:[2,3,0,1] row_mask:0xf bank_mask:0xf bound_ctrl:1
	s_nop 0
	v_add_f32_dpp v110, v110, v110 row_half_mirror row_mask:0xf bank_mask:0xf bound_ctrl:1
	v_add_f32_dpp v112, v112, v112 row_half_mirror row_mask:0xf bank_mask:0xf bound_ctrl:1
	s_nop 0
	v_add_f32_dpp v110, v110, v110 row_ror:8 row_mask:0xf bank_mask:0xf bound_ctrl:1
	v_add_f32_dpp v112, v112, v112 row_ror:8 row_mask:0xf bank_mask:0xf bound_ctrl:1
	v_pk_mul_f32 v[114:115], v[88:89], v[110:111] op_sel_hi:[1,0]
	v_pk_mul_f32 v[116:117], v[88:89], v[112:113] op_sel_hi:[1,0]
	v_pk_mul_f32 v[118:119], v[90:91], v[110:111] op_sel_hi:[1,0]
	v_pk_mul_f32 v[120:121], v[90:91], v[112:113] op_sel_hi:[1,0]
	v_pk_fma_f32 v[114:115], v[100:101], v[104:105], v[114:115] op_sel_hi:[1,0,1]
	v_pk_fma_f32 v[116:117], v[100:101], v[104:105], v[116:117] op_sel:[0,1,0]
	v_pk_fma_f32 v[118:119], v[102:103], v[104:105], v[118:119] op_sel_hi:[1,0,1]
	v_pk_fma_f32 v[120:121], v[102:103], v[104:105], v[120:121] op_sel:[0,1,0]
	v_pk_fma_f32 v[72:73], v[72:73], v[92:93], v[114:115]
	v_pk_fma_f32 v[76:77], v[76:77], v[92:93], v[116:117]
	v_pk_fma_f32 v[74:75], v[74:75], v[94:95], v[118:119]
	v_pk_fma_f32 v[78:79], v[78:79], v[94:95], v[120:121]
	v_pk_mul_f32 v[122:123], v[72:73], v[96:97]
	v_pk_mul_f32 v[124:125], v[76:77], v[96:97]
	v_pk_fma_f32 v[122:123], v[74:75], v[98:99], v[122:123]
	v_pk_fma_f32 v[124:125], v[78:79], v[98:99], v[124:125]
	v_add_f32_e32 v126, v122, v123
	v_add_f32_e32 v127, v124, v125
	ds_write_b64 v187, v[126:127] offset:10240
	ds_read_b128 v[84:87], v161 offset:9984
	ds_read_b128 v[88:91], v161 offset:18176
	ds_read_b128 v[100:103], v161 offset:26368
	ds_read_b64 v[104:105], v82 offset:42752
	ds_read_b128 v[92:95], v161 offset:1792
	ds_read_b128 v[96:99], v161 offset:34560
	s_waitcnt lgkmcnt(7)
	v_pk_mul_f32 v[106:107], v[72:73], v[30:31]
	v_pk_mul_f32 v[108:109], v[76:77], v[30:31]
	v_pk_fma_f32 v[106:107], v[74:75], v[32:33], v[106:107]
	v_pk_fma_f32 v[108:109], v[78:79], v[32:33], v[108:109]
	v_add_f32_e32 v110, v106, v107
	v_add_f32_e32 v112, v108, v109
	s_nop 0
	v_add_f32_dpp v110, v110, v110 quad_perm:[1,0,3,2] row_mask:0xf bank_mask:0xf bound_ctrl:1
	v_add_f32_dpp v112, v112, v112 quad_perm:[1,0,3,2] row_mask:0xf bank_mask:0xf bound_ctrl:1
	s_nop 0
	v_add_f32_dpp v110, v110, v110 quad_perm:[2,3,0,1] row_mask:0xf bank_mask:0xf bound_ctrl:1
	v_add_f32_dpp v112, v112, v112 quad_perm:[2,3,0,1] row_mask:0xf bank_mask:0xf bound_ctrl:1
	s_nop 0
	v_add_f32_dpp v110, v110, v110 row_half_mirror row_mask:0xf bank_mask:0xf bound_ctrl:1
	v_add_f32_dpp v112, v112, v112 row_half_mirror row_mask:0xf bank_mask:0xf bound_ctrl:1
	s_nop 0
	v_add_f32_dpp v110, v110, v110 row_ror:8 row_mask:0xf bank_mask:0xf bound_ctrl:1
	v_add_f32_dpp v112, v112, v112 row_ror:8 row_mask:0xf bank_mask:0xf bound_ctrl:1
	v_pk_mul_f32 v[114:115], v[34:35], v[110:111] op_sel_hi:[1,0]
	v_pk_mul_f32 v[116:117], v[34:35], v[112:113] op_sel_hi:[1,0]
	v_pk_mul_f32 v[118:119], v[36:37], v[110:111] op_sel_hi:[1,0]
	v_pk_mul_f32 v[120:121], v[36:37], v[112:113] op_sel_hi:[1,0]
	v_pk_fma_f32 v[114:115], v[46:47], v[80:81], v[114:115] op_sel_hi:[1,0,1]
	v_pk_fma_f32 v[116:117], v[46:47], v[80:81], v[116:117] op_sel:[0,1,0]
	v_pk_fma_f32 v[118:119], v[48:49], v[80:81], v[118:119] op_sel_hi:[1,0,1]
	v_pk_fma_f32 v[120:121], v[48:49], v[80:81], v[120:121] op_sel:[0,1,0]
	v_pk_fma_f32 v[72:73], v[72:73], v[38:39], v[114:115]
	v_pk_fma_f32 v[76:77], v[76:77], v[38:39], v[116:117]
	v_pk_fma_f32 v[74:75], v[74:75], v[40:41], v[118:119]
	v_pk_fma_f32 v[78:79], v[78:79], v[40:41], v[120:121]
	v_pk_mul_f32 v[122:123], v[72:73], v[42:43]
	v_pk_mul_f32 v[124:125], v[76:77], v[42:43]
	v_pk_fma_f32 v[122:123], v[74:75], v[44:45], v[122:123]
	v_pk_fma_f32 v[124:125], v[78:79], v[44:45], v[124:125]
	v_add_f32_e32 v126, v122, v123
	v_add_f32_e32 v127, v124, v125
	ds_write_b64 v187, v[126:127] offset:12288
	ds_read_b128 v[30:33], v161 offset:10240
	ds_read_b128 v[34:37], v161 offset:18432
	ds_read_b128 v[46:49], v161 offset:26624
	ds_read_b64 v[80:81], v82 offset:43008
	ds_read_b128 v[38:41], v161 offset:2048
	ds_read_b128 v[42:45], v161 offset:34816
	s_waitcnt lgkmcnt(7)
	v_pk_mul_f32 v[106:107], v[72:73], v[84:85]
	v_pk_mul_f32 v[108:109], v[76:77], v[84:85]
	v_pk_fma_f32 v[106:107], v[74:75], v[86:87], v[106:107]
	v_pk_fma_f32 v[108:109], v[78:79], v[86:87], v[108:109]
	v_add_f32_e32 v110, v106, v107
	v_add_f32_e32 v112, v108, v109
	s_nop 0
	v_add_f32_dpp v110, v110, v110 quad_perm:[1,0,3,2] row_mask:0xf bank_mask:0xf bound_ctrl:1
	v_add_f32_dpp v112, v112, v112 quad_perm:[1,0,3,2] row_mask:0xf bank_mask:0xf bound_ctrl:1
	s_nop 0
	v_add_f32_dpp v110, v110, v110 quad_perm:[2,3,0,1] row_mask:0xf bank_mask:0xf bound_ctrl:1
	v_add_f32_dpp v112, v112, v112 quad_perm:[2,3,0,1] row_mask:0xf bank_mask:0xf bound_ctrl:1
	s_nop 0
	v_add_f32_dpp v110, v110, v110 row_half_mirror row_mask:0xf bank_mask:0xf bound_ctrl:1
	v_add_f32_dpp v112, v112, v112 row_half_mirror row_mask:0xf bank_mask:0xf bound_ctrl:1
	s_nop 0
	v_add_f32_dpp v110, v110, v110 row_ror:8 row_mask:0xf bank_mask:0xf bound_ctrl:1
	v_add_f32_dpp v112, v112, v112 row_ror:8 row_mask:0xf bank_mask:0xf bound_ctrl:1
	v_pk_mul_f32 v[114:115], v[88:89], v[110:111] op_sel_hi:[1,0]
	v_pk_mul_f32 v[116:117], v[88:89], v[112:113] op_sel_hi:[1,0]
	v_pk_mul_f32 v[118:119], v[90:91], v[110:111] op_sel_hi:[1,0]
	v_pk_mul_f32 v[120:121], v[90:91], v[112:113] op_sel_hi:[1,0]
	v_pk_fma_f32 v[114:115], v[100:101], v[104:105], v[114:115] op_sel_hi:[1,0,1]
	v_pk_fma_f32 v[116:117], v[100:101], v[104:105], v[116:117] op_sel:[0,1,0]
	v_pk_fma_f32 v[118:119], v[102:103], v[104:105], v[118:119] op_sel_hi:[1,0,1]
	v_pk_fma_f32 v[120:121], v[102:103], v[104:105], v[120:121] op_sel:[0,1,0]
	v_pk_fma_f32 v[72:73], v[72:73], v[92:93], v[114:115]
	v_pk_fma_f32 v[76:77], v[76:77], v[92:93], v[116:117]
	v_pk_fma_f32 v[74:75], v[74:75], v[94:95], v[118:119]
	v_pk_fma_f32 v[78:79], v[78:79], v[94:95], v[120:121]
	v_pk_mul_f32 v[122:123], v[72:73], v[96:97]
	v_pk_mul_f32 v[124:125], v[76:77], v[96:97]
	v_pk_fma_f32 v[122:123], v[74:75], v[98:99], v[122:123]
	v_pk_fma_f32 v[124:125], v[78:79], v[98:99], v[124:125]
	v_add_f32_e32 v126, v122, v123
	v_add_f32_e32 v127, v124, v125
	ds_write_b64 v187, v[126:127] offset:14336
	ds_read_b128 v[84:87], v161 offset:10496
	ds_read_b128 v[88:91], v161 offset:18688
	ds_read_b128 v[100:103], v161 offset:26880
	ds_read_b64 v[104:105], v82 offset:43264
	ds_read_b128 v[92:95], v161 offset:2304
	ds_read_b128 v[96:99], v161 offset:35072
	s_waitcnt lgkmcnt(7)
	v_pk_mul_f32 v[106:107], v[72:73], v[30:31]
	v_pk_mul_f32 v[108:109], v[76:77], v[30:31]
	v_pk_fma_f32 v[106:107], v[74:75], v[32:33], v[106:107]
	v_pk_fma_f32 v[108:109], v[78:79], v[32:33], v[108:109]
	v_add_f32_e32 v110, v106, v107
	v_add_f32_e32 v112, v108, v109
	s_nop 0
	v_add_f32_dpp v110, v110, v110 quad_perm:[1,0,3,2] row_mask:0xf bank_mask:0xf bound_ctrl:1
	v_add_f32_dpp v112, v112, v112 quad_perm:[1,0,3,2] row_mask:0xf bank_mask:0xf bound_ctrl:1
	s_nop 0
	v_add_f32_dpp v110, v110, v110 quad_perm:[2,3,0,1] row_mask:0xf bank_mask:0xf bound_ctrl:1
	v_add_f32_dpp v112, v112, v112 quad_perm:[2,3,0,1] row_mask:0xf bank_mask:0xf bound_ctrl:1
	s_nop 0
	v_add_f32_dpp v110, v110, v110 row_half_mirror row_mask:0xf bank_mask:0xf bound_ctrl:1
	v_add_f32_dpp v112, v112, v112 row_half_mirror row_mask:0xf bank_mask:0xf bound_ctrl:1
	s_nop 0
	v_add_f32_dpp v110, v110, v110 row_ror:8 row_mask:0xf bank_mask:0xf bound_ctrl:1
	v_add_f32_dpp v112, v112, v112 row_ror:8 row_mask:0xf bank_mask:0xf bound_ctrl:1
	v_pk_mul_f32 v[114:115], v[34:35], v[110:111] op_sel_hi:[1,0]
	v_pk_mul_f32 v[116:117], v[34:35], v[112:113] op_sel_hi:[1,0]
	v_pk_mul_f32 v[118:119], v[36:37], v[110:111] op_sel_hi:[1,0]
	v_pk_mul_f32 v[120:121], v[36:37], v[112:113] op_sel_hi:[1,0]
	v_pk_fma_f32 v[114:115], v[46:47], v[80:81], v[114:115] op_sel_hi:[1,0,1]
	v_pk_fma_f32 v[116:117], v[46:47], v[80:81], v[116:117] op_sel:[0,1,0]
	v_pk_fma_f32 v[118:119], v[48:49], v[80:81], v[118:119] op_sel_hi:[1,0,1]
	v_pk_fma_f32 v[120:121], v[48:49], v[80:81], v[120:121] op_sel:[0,1,0]
	v_pk_fma_f32 v[72:73], v[72:73], v[38:39], v[114:115]
	v_pk_fma_f32 v[76:77], v[76:77], v[38:39], v[116:117]
	v_pk_fma_f32 v[74:75], v[74:75], v[40:41], v[118:119]
	v_pk_fma_f32 v[78:79], v[78:79], v[40:41], v[120:121]
	v_pk_mul_f32 v[122:123], v[72:73], v[42:43]
	v_pk_mul_f32 v[124:125], v[76:77], v[42:43]
	v_pk_fma_f32 v[122:123], v[74:75], v[44:45], v[122:123]
	v_pk_fma_f32 v[124:125], v[78:79], v[44:45], v[124:125]
	v_add_f32_e32 v126, v122, v123
	v_add_f32_e32 v127, v124, v125
	ds_write_b64 v187, v[126:127] offset:16384
	ds_read_b128 v[30:33], v161 offset:10752
	ds_read_b128 v[34:37], v161 offset:18944
	ds_read_b128 v[46:49], v161 offset:27136
	ds_read_b64 v[80:81], v82 offset:43520
	ds_read_b128 v[38:41], v161 offset:2560
	ds_read_b128 v[42:45], v161 offset:35328
	s_waitcnt lgkmcnt(7)
	v_pk_mul_f32 v[106:107], v[72:73], v[84:85]
	v_pk_mul_f32 v[108:109], v[76:77], v[84:85]
	v_pk_fma_f32 v[106:107], v[74:75], v[86:87], v[106:107]
	v_pk_fma_f32 v[108:109], v[78:79], v[86:87], v[108:109]
	v_add_f32_e32 v110, v106, v107
	v_add_f32_e32 v112, v108, v109
	s_nop 0
	v_add_f32_dpp v110, v110, v110 quad_perm:[1,0,3,2] row_mask:0xf bank_mask:0xf bound_ctrl:1
	v_add_f32_dpp v112, v112, v112 quad_perm:[1,0,3,2] row_mask:0xf bank_mask:0xf bound_ctrl:1
	s_nop 0
	v_add_f32_dpp v110, v110, v110 quad_perm:[2,3,0,1] row_mask:0xf bank_mask:0xf bound_ctrl:1
	v_add_f32_dpp v112, v112, v112 quad_perm:[2,3,0,1] row_mask:0xf bank_mask:0xf bound_ctrl:1
	s_nop 0
	v_add_f32_dpp v110, v110, v110 row_half_mirror row_mask:0xf bank_mask:0xf bound_ctrl:1
	v_add_f32_dpp v112, v112, v112 row_half_mirror row_mask:0xf bank_mask:0xf bound_ctrl:1
	s_nop 0
	v_add_f32_dpp v110, v110, v110 row_ror:8 row_mask:0xf bank_mask:0xf bound_ctrl:1
	v_add_f32_dpp v112, v112, v112 row_ror:8 row_mask:0xf bank_mask:0xf bound_ctrl:1
	v_pk_mul_f32 v[114:115], v[88:89], v[110:111] op_sel_hi:[1,0]
	v_pk_mul_f32 v[116:117], v[88:89], v[112:113] op_sel_hi:[1,0]
	v_pk_mul_f32 v[118:119], v[90:91], v[110:111] op_sel_hi:[1,0]
	v_pk_mul_f32 v[120:121], v[90:91], v[112:113] op_sel_hi:[1,0]
	v_pk_fma_f32 v[114:115], v[100:101], v[104:105], v[114:115] op_sel_hi:[1,0,1]
	v_pk_fma_f32 v[116:117], v[100:101], v[104:105], v[116:117] op_sel:[0,1,0]
	v_pk_fma_f32 v[118:119], v[102:103], v[104:105], v[118:119] op_sel_hi:[1,0,1]
	v_pk_fma_f32 v[120:121], v[102:103], v[104:105], v[120:121] op_sel:[0,1,0]
	v_pk_fma_f32 v[72:73], v[72:73], v[92:93], v[114:115]
	v_pk_fma_f32 v[76:77], v[76:77], v[92:93], v[116:117]
	v_pk_fma_f32 v[74:75], v[74:75], v[94:95], v[118:119]
	v_pk_fma_f32 v[78:79], v[78:79], v[94:95], v[120:121]
	v_pk_mul_f32 v[122:123], v[72:73], v[96:97]
	v_pk_mul_f32 v[124:125], v[76:77], v[96:97]
	v_pk_fma_f32 v[122:123], v[74:75], v[98:99], v[122:123]
	v_pk_fma_f32 v[124:125], v[78:79], v[98:99], v[124:125]
	v_add_f32_e32 v126, v122, v123
	v_add_f32_e32 v127, v124, v125
	ds_write_b64 v187, v[126:127] offset:18432
	ds_read_b128 v[84:87], v161 offset:11008
	ds_read_b128 v[88:91], v161 offset:19200
	ds_read_b128 v[100:103], v161 offset:27392
	ds_read_b64 v[104:105], v82 offset:43776
	ds_read_b128 v[92:95], v161 offset:2816
	ds_read_b128 v[96:99], v161 offset:35584
	s_waitcnt lgkmcnt(7)
	v_pk_mul_f32 v[106:107], v[72:73], v[30:31]
	v_pk_mul_f32 v[108:109], v[76:77], v[30:31]
	v_pk_fma_f32 v[106:107], v[74:75], v[32:33], v[106:107]
	v_pk_fma_f32 v[108:109], v[78:79], v[32:33], v[108:109]
	v_add_f32_e32 v110, v106, v107
	v_add_f32_e32 v112, v108, v109
	s_nop 0
	v_add_f32_dpp v110, v110, v110 quad_perm:[1,0,3,2] row_mask:0xf bank_mask:0xf bound_ctrl:1
	v_add_f32_dpp v112, v112, v112 quad_perm:[1,0,3,2] row_mask:0xf bank_mask:0xf bound_ctrl:1
	s_nop 0
	v_add_f32_dpp v110, v110, v110 quad_perm:[2,3,0,1] row_mask:0xf bank_mask:0xf bound_ctrl:1
	v_add_f32_dpp v112, v112, v112 quad_perm:[2,3,0,1] row_mask:0xf bank_mask:0xf bound_ctrl:1
	s_nop 0
	v_add_f32_dpp v110, v110, v110 row_half_mirror row_mask:0xf bank_mask:0xf bound_ctrl:1
	v_add_f32_dpp v112, v112, v112 row_half_mirror row_mask:0xf bank_mask:0xf bound_ctrl:1
	s_nop 0
	v_add_f32_dpp v110, v110, v110 row_ror:8 row_mask:0xf bank_mask:0xf bound_ctrl:1
	v_add_f32_dpp v112, v112, v112 row_ror:8 row_mask:0xf bank_mask:0xf bound_ctrl:1
	v_pk_mul_f32 v[114:115], v[34:35], v[110:111] op_sel_hi:[1,0]
	v_pk_mul_f32 v[116:117], v[34:35], v[112:113] op_sel_hi:[1,0]
	v_pk_mul_f32 v[118:119], v[36:37], v[110:111] op_sel_hi:[1,0]
	v_pk_mul_f32 v[120:121], v[36:37], v[112:113] op_sel_hi:[1,0]
	v_pk_fma_f32 v[114:115], v[46:47], v[80:81], v[114:115] op_sel_hi:[1,0,1]
	v_pk_fma_f32 v[116:117], v[46:47], v[80:81], v[116:117] op_sel:[0,1,0]
	v_pk_fma_f32 v[118:119], v[48:49], v[80:81], v[118:119] op_sel_hi:[1,0,1]
	v_pk_fma_f32 v[120:121], v[48:49], v[80:81], v[120:121] op_sel:[0,1,0]
	v_pk_fma_f32 v[72:73], v[72:73], v[38:39], v[114:115]
	v_pk_fma_f32 v[76:77], v[76:77], v[38:39], v[116:117]
	v_pk_fma_f32 v[74:75], v[74:75], v[40:41], v[118:119]
	v_pk_fma_f32 v[78:79], v[78:79], v[40:41], v[120:121]
	v_pk_mul_f32 v[122:123], v[72:73], v[42:43]
	v_pk_mul_f32 v[124:125], v[76:77], v[42:43]
	v_pk_fma_f32 v[122:123], v[74:75], v[44:45], v[122:123]
	v_pk_fma_f32 v[124:125], v[78:79], v[44:45], v[124:125]
	v_add_f32_e32 v126, v122, v123
	v_add_f32_e32 v127, v124, v125
	ds_write_b64 v187, v[126:127] offset:20480
	ds_read_b128 v[30:33], v161 offset:11264
	ds_read_b128 v[34:37], v161 offset:19456
	ds_read_b128 v[46:49], v161 offset:27648
	ds_read_b64 v[80:81], v82 offset:44032
	ds_read_b128 v[38:41], v161 offset:3072
	ds_read_b128 v[42:45], v161 offset:35840
	s_waitcnt lgkmcnt(7)
	v_pk_mul_f32 v[106:107], v[72:73], v[84:85]
	v_pk_mul_f32 v[108:109], v[76:77], v[84:85]
	v_pk_fma_f32 v[106:107], v[74:75], v[86:87], v[106:107]
	v_pk_fma_f32 v[108:109], v[78:79], v[86:87], v[108:109]
	v_add_f32_e32 v110, v106, v107
	v_add_f32_e32 v112, v108, v109
	s_nop 0
	v_add_f32_dpp v110, v110, v110 quad_perm:[1,0,3,2] row_mask:0xf bank_mask:0xf bound_ctrl:1
	v_add_f32_dpp v112, v112, v112 quad_perm:[1,0,3,2] row_mask:0xf bank_mask:0xf bound_ctrl:1
	s_nop 0
	v_add_f32_dpp v110, v110, v110 quad_perm:[2,3,0,1] row_mask:0xf bank_mask:0xf bound_ctrl:1
	v_add_f32_dpp v112, v112, v112 quad_perm:[2,3,0,1] row_mask:0xf bank_mask:0xf bound_ctrl:1
	s_nop 0
	v_add_f32_dpp v110, v110, v110 row_half_mirror row_mask:0xf bank_mask:0xf bound_ctrl:1
	v_add_f32_dpp v112, v112, v112 row_half_mirror row_mask:0xf bank_mask:0xf bound_ctrl:1
	s_nop 0
	v_add_f32_dpp v110, v110, v110 row_ror:8 row_mask:0xf bank_mask:0xf bound_ctrl:1
	v_add_f32_dpp v112, v112, v112 row_ror:8 row_mask:0xf bank_mask:0xf bound_ctrl:1
	v_pk_mul_f32 v[114:115], v[88:89], v[110:111] op_sel_hi:[1,0]
	v_pk_mul_f32 v[116:117], v[88:89], v[112:113] op_sel_hi:[1,0]
	v_pk_mul_f32 v[118:119], v[90:91], v[110:111] op_sel_hi:[1,0]
	v_pk_mul_f32 v[120:121], v[90:91], v[112:113] op_sel_hi:[1,0]
	v_pk_fma_f32 v[114:115], v[100:101], v[104:105], v[114:115] op_sel_hi:[1,0,1]
	v_pk_fma_f32 v[116:117], v[100:101], v[104:105], v[116:117] op_sel:[0,1,0]
	v_pk_fma_f32 v[118:119], v[102:103], v[104:105], v[118:119] op_sel_hi:[1,0,1]
	v_pk_fma_f32 v[120:121], v[102:103], v[104:105], v[120:121] op_sel:[0,1,0]
	v_pk_fma_f32 v[72:73], v[72:73], v[92:93], v[114:115]
	v_pk_fma_f32 v[76:77], v[76:77], v[92:93], v[116:117]
	v_pk_fma_f32 v[74:75], v[74:75], v[94:95], v[118:119]
	v_pk_fma_f32 v[78:79], v[78:79], v[94:95], v[120:121]
	v_pk_mul_f32 v[122:123], v[72:73], v[96:97]
	v_pk_mul_f32 v[124:125], v[76:77], v[96:97]
	v_pk_fma_f32 v[122:123], v[74:75], v[98:99], v[122:123]
	v_pk_fma_f32 v[124:125], v[78:79], v[98:99], v[124:125]
	v_add_f32_e32 v126, v122, v123
	v_add_f32_e32 v127, v124, v125
	ds_write_b64 v187, v[126:127] offset:22528
	ds_read_b128 v[84:87], v161 offset:11520
	ds_read_b128 v[88:91], v161 offset:19712
	ds_read_b128 v[100:103], v161 offset:27904
	ds_read_b64 v[104:105], v82 offset:44288
	ds_read_b128 v[92:95], v161 offset:3328
	ds_read_b128 v[96:99], v161 offset:36096
	s_waitcnt lgkmcnt(7)
	v_pk_mul_f32 v[106:107], v[72:73], v[30:31]
	v_pk_mul_f32 v[108:109], v[76:77], v[30:31]
	v_pk_fma_f32 v[106:107], v[74:75], v[32:33], v[106:107]
	v_pk_fma_f32 v[108:109], v[78:79], v[32:33], v[108:109]
	v_add_f32_e32 v110, v106, v107
	v_add_f32_e32 v112, v108, v109
	s_nop 0
	v_add_f32_dpp v110, v110, v110 quad_perm:[1,0,3,2] row_mask:0xf bank_mask:0xf bound_ctrl:1
	v_add_f32_dpp v112, v112, v112 quad_perm:[1,0,3,2] row_mask:0xf bank_mask:0xf bound_ctrl:1
	s_nop 0
	v_add_f32_dpp v110, v110, v110 quad_perm:[2,3,0,1] row_mask:0xf bank_mask:0xf bound_ctrl:1
	v_add_f32_dpp v112, v112, v112 quad_perm:[2,3,0,1] row_mask:0xf bank_mask:0xf bound_ctrl:1
	s_nop 0
	v_add_f32_dpp v110, v110, v110 row_half_mirror row_mask:0xf bank_mask:0xf bound_ctrl:1
	v_add_f32_dpp v112, v112, v112 row_half_mirror row_mask:0xf bank_mask:0xf bound_ctrl:1
	s_nop 0
	v_add_f32_dpp v110, v110, v110 row_ror:8 row_mask:0xf bank_mask:0xf bound_ctrl:1
	v_add_f32_dpp v112, v112, v112 row_ror:8 row_mask:0xf bank_mask:0xf bound_ctrl:1
	v_pk_mul_f32 v[114:115], v[34:35], v[110:111] op_sel_hi:[1,0]
	v_pk_mul_f32 v[116:117], v[34:35], v[112:113] op_sel_hi:[1,0]
	v_pk_mul_f32 v[118:119], v[36:37], v[110:111] op_sel_hi:[1,0]
	v_pk_mul_f32 v[120:121], v[36:37], v[112:113] op_sel_hi:[1,0]
	v_pk_fma_f32 v[114:115], v[46:47], v[80:81], v[114:115] op_sel_hi:[1,0,1]
	v_pk_fma_f32 v[116:117], v[46:47], v[80:81], v[116:117] op_sel:[0,1,0]
	v_pk_fma_f32 v[118:119], v[48:49], v[80:81], v[118:119] op_sel_hi:[1,0,1]
	v_pk_fma_f32 v[120:121], v[48:49], v[80:81], v[120:121] op_sel:[0,1,0]
	v_pk_fma_f32 v[72:73], v[72:73], v[38:39], v[114:115]
	v_pk_fma_f32 v[76:77], v[76:77], v[38:39], v[116:117]
	v_pk_fma_f32 v[74:75], v[74:75], v[40:41], v[118:119]
	v_pk_fma_f32 v[78:79], v[78:79], v[40:41], v[120:121]
	v_pk_mul_f32 v[122:123], v[72:73], v[42:43]
	v_pk_mul_f32 v[124:125], v[76:77], v[42:43]
	v_pk_fma_f32 v[122:123], v[74:75], v[44:45], v[122:123]
	v_pk_fma_f32 v[124:125], v[78:79], v[44:45], v[124:125]
	v_add_f32_e32 v126, v122, v123
	v_add_f32_e32 v127, v124, v125
	ds_write_b64 v187, v[126:127] offset:24576
	ds_read_b128 v[30:33], v161 offset:11776
	ds_read_b128 v[34:37], v161 offset:19968
	ds_read_b128 v[46:49], v161 offset:28160
	ds_read_b64 v[80:81], v82 offset:44544
	ds_read_b128 v[38:41], v161 offset:3584
	ds_read_b128 v[42:45], v161 offset:36352
	s_waitcnt lgkmcnt(7)
	v_pk_mul_f32 v[106:107], v[72:73], v[84:85]
	v_pk_mul_f32 v[108:109], v[76:77], v[84:85]
	v_pk_fma_f32 v[106:107], v[74:75], v[86:87], v[106:107]
	v_pk_fma_f32 v[108:109], v[78:79], v[86:87], v[108:109]
	v_add_f32_e32 v110, v106, v107
	v_add_f32_e32 v112, v108, v109
	s_nop 0
	v_add_f32_dpp v110, v110, v110 quad_perm:[1,0,3,2] row_mask:0xf bank_mask:0xf bound_ctrl:1
	v_add_f32_dpp v112, v112, v112 quad_perm:[1,0,3,2] row_mask:0xf bank_mask:0xf bound_ctrl:1
	s_nop 0
	v_add_f32_dpp v110, v110, v110 quad_perm:[2,3,0,1] row_mask:0xf bank_mask:0xf bound_ctrl:1
	v_add_f32_dpp v112, v112, v112 quad_perm:[2,3,0,1] row_mask:0xf bank_mask:0xf bound_ctrl:1
	s_nop 0
	v_add_f32_dpp v110, v110, v110 row_half_mirror row_mask:0xf bank_mask:0xf bound_ctrl:1
	v_add_f32_dpp v112, v112, v112 row_half_mirror row_mask:0xf bank_mask:0xf bound_ctrl:1
	s_nop 0
	v_add_f32_dpp v110, v110, v110 row_ror:8 row_mask:0xf bank_mask:0xf bound_ctrl:1
	v_add_f32_dpp v112, v112, v112 row_ror:8 row_mask:0xf bank_mask:0xf bound_ctrl:1
	v_pk_mul_f32 v[114:115], v[88:89], v[110:111] op_sel_hi:[1,0]
	v_pk_mul_f32 v[116:117], v[88:89], v[112:113] op_sel_hi:[1,0]
	v_pk_mul_f32 v[118:119], v[90:91], v[110:111] op_sel_hi:[1,0]
	v_pk_mul_f32 v[120:121], v[90:91], v[112:113] op_sel_hi:[1,0]
	v_pk_fma_f32 v[114:115], v[100:101], v[104:105], v[114:115] op_sel_hi:[1,0,1]
	v_pk_fma_f32 v[116:117], v[100:101], v[104:105], v[116:117] op_sel:[0,1,0]
	v_pk_fma_f32 v[118:119], v[102:103], v[104:105], v[118:119] op_sel_hi:[1,0,1]
	v_pk_fma_f32 v[120:121], v[102:103], v[104:105], v[120:121] op_sel:[0,1,0]
	v_pk_fma_f32 v[72:73], v[72:73], v[92:93], v[114:115]
	v_pk_fma_f32 v[76:77], v[76:77], v[92:93], v[116:117]
	v_pk_fma_f32 v[74:75], v[74:75], v[94:95], v[118:119]
	v_pk_fma_f32 v[78:79], v[78:79], v[94:95], v[120:121]
	v_pk_mul_f32 v[122:123], v[72:73], v[96:97]
	v_pk_mul_f32 v[124:125], v[76:77], v[96:97]
	v_pk_fma_f32 v[122:123], v[74:75], v[98:99], v[122:123]
	v_pk_fma_f32 v[124:125], v[78:79], v[98:99], v[124:125]
	v_add_f32_e32 v126, v122, v123
	v_add_f32_e32 v127, v124, v125
	ds_write_b64 v187, v[126:127] offset:26624
	ds_read_b128 v[84:87], v161 offset:12032
	ds_read_b128 v[88:91], v161 offset:20224
	ds_read_b128 v[100:103], v161 offset:28416
	ds_read_b64 v[104:105], v82 offset:44800
	ds_read_b128 v[92:95], v161 offset:3840
	ds_read_b128 v[96:99], v161 offset:36608
	s_waitcnt lgkmcnt(7)
	v_pk_mul_f32 v[106:107], v[72:73], v[30:31]
	v_pk_mul_f32 v[108:109], v[76:77], v[30:31]
	v_pk_fma_f32 v[106:107], v[74:75], v[32:33], v[106:107]
	v_pk_fma_f32 v[108:109], v[78:79], v[32:33], v[108:109]
	v_add_f32_e32 v110, v106, v107
	v_add_f32_e32 v112, v108, v109
	s_nop 0
	v_add_f32_dpp v110, v110, v110 quad_perm:[1,0,3,2] row_mask:0xf bank_mask:0xf bound_ctrl:1
	v_add_f32_dpp v112, v112, v112 quad_perm:[1,0,3,2] row_mask:0xf bank_mask:0xf bound_ctrl:1
	s_nop 0
	v_add_f32_dpp v110, v110, v110 quad_perm:[2,3,0,1] row_mask:0xf bank_mask:0xf bound_ctrl:1
	v_add_f32_dpp v112, v112, v112 quad_perm:[2,3,0,1] row_mask:0xf bank_mask:0xf bound_ctrl:1
	s_nop 0
	v_add_f32_dpp v110, v110, v110 row_half_mirror row_mask:0xf bank_mask:0xf bound_ctrl:1
	v_add_f32_dpp v112, v112, v112 row_half_mirror row_mask:0xf bank_mask:0xf bound_ctrl:1
	s_nop 0
	v_add_f32_dpp v110, v110, v110 row_ror:8 row_mask:0xf bank_mask:0xf bound_ctrl:1
	v_add_f32_dpp v112, v112, v112 row_ror:8 row_mask:0xf bank_mask:0xf bound_ctrl:1
	v_pk_mul_f32 v[114:115], v[34:35], v[110:111] op_sel_hi:[1,0]
	v_pk_mul_f32 v[116:117], v[34:35], v[112:113] op_sel_hi:[1,0]
	v_pk_mul_f32 v[118:119], v[36:37], v[110:111] op_sel_hi:[1,0]
	v_pk_mul_f32 v[120:121], v[36:37], v[112:113] op_sel_hi:[1,0]
	v_pk_fma_f32 v[114:115], v[46:47], v[80:81], v[114:115] op_sel_hi:[1,0,1]
	v_pk_fma_f32 v[116:117], v[46:47], v[80:81], v[116:117] op_sel:[0,1,0]
	v_pk_fma_f32 v[118:119], v[48:49], v[80:81], v[118:119] op_sel_hi:[1,0,1]
	v_pk_fma_f32 v[120:121], v[48:49], v[80:81], v[120:121] op_sel:[0,1,0]
	v_pk_fma_f32 v[72:73], v[72:73], v[38:39], v[114:115]
	v_pk_fma_f32 v[76:77], v[76:77], v[38:39], v[116:117]
	v_pk_fma_f32 v[74:75], v[74:75], v[40:41], v[118:119]
	v_pk_fma_f32 v[78:79], v[78:79], v[40:41], v[120:121]
	v_pk_mul_f32 v[122:123], v[72:73], v[42:43]
	v_pk_mul_f32 v[124:125], v[76:77], v[42:43]
	v_pk_fma_f32 v[122:123], v[74:75], v[44:45], v[122:123]
	v_pk_fma_f32 v[124:125], v[78:79], v[44:45], v[124:125]
	v_add_f32_e32 v126, v122, v123
	v_add_f32_e32 v127, v124, v125
	ds_write_b64 v187, v[126:127] offset:28672
	ds_read_b128 v[30:33], v161 offset:12288
	ds_read_b128 v[34:37], v161 offset:20480
	ds_read_b128 v[46:49], v161 offset:28672
	ds_read_b64 v[80:81], v82 offset:45056
	ds_read_b128 v[38:41], v161 offset:4096
	ds_read_b128 v[42:45], v161 offset:36864
	s_waitcnt lgkmcnt(7)
	v_pk_mul_f32 v[106:107], v[72:73], v[84:85]
	v_pk_mul_f32 v[108:109], v[76:77], v[84:85]
	v_pk_fma_f32 v[106:107], v[74:75], v[86:87], v[106:107]
	v_pk_fma_f32 v[108:109], v[78:79], v[86:87], v[108:109]
	v_add_f32_e32 v110, v106, v107
	v_add_f32_e32 v112, v108, v109
	s_nop 0
	v_add_f32_dpp v110, v110, v110 quad_perm:[1,0,3,2] row_mask:0xf bank_mask:0xf bound_ctrl:1
	v_add_f32_dpp v112, v112, v112 quad_perm:[1,0,3,2] row_mask:0xf bank_mask:0xf bound_ctrl:1
	s_nop 0
	v_add_f32_dpp v110, v110, v110 quad_perm:[2,3,0,1] row_mask:0xf bank_mask:0xf bound_ctrl:1
	v_add_f32_dpp v112, v112, v112 quad_perm:[2,3,0,1] row_mask:0xf bank_mask:0xf bound_ctrl:1
	s_nop 0
	v_add_f32_dpp v110, v110, v110 row_half_mirror row_mask:0xf bank_mask:0xf bound_ctrl:1
	v_add_f32_dpp v112, v112, v112 row_half_mirror row_mask:0xf bank_mask:0xf bound_ctrl:1
	s_nop 0
	v_add_f32_dpp v110, v110, v110 row_ror:8 row_mask:0xf bank_mask:0xf bound_ctrl:1
	v_add_f32_dpp v112, v112, v112 row_ror:8 row_mask:0xf bank_mask:0xf bound_ctrl:1
	v_pk_mul_f32 v[114:115], v[88:89], v[110:111] op_sel_hi:[1,0]
	v_pk_mul_f32 v[116:117], v[88:89], v[112:113] op_sel_hi:[1,0]
	v_pk_mul_f32 v[118:119], v[90:91], v[110:111] op_sel_hi:[1,0]
	v_pk_mul_f32 v[120:121], v[90:91], v[112:113] op_sel_hi:[1,0]
	v_pk_fma_f32 v[114:115], v[100:101], v[104:105], v[114:115] op_sel_hi:[1,0,1]
	v_pk_fma_f32 v[116:117], v[100:101], v[104:105], v[116:117] op_sel:[0,1,0]
	v_pk_fma_f32 v[118:119], v[102:103], v[104:105], v[118:119] op_sel_hi:[1,0,1]
	v_pk_fma_f32 v[120:121], v[102:103], v[104:105], v[120:121] op_sel:[0,1,0]
	v_pk_fma_f32 v[72:73], v[72:73], v[92:93], v[114:115]
	v_pk_fma_f32 v[76:77], v[76:77], v[92:93], v[116:117]
	v_pk_fma_f32 v[74:75], v[74:75], v[94:95], v[118:119]
	v_pk_fma_f32 v[78:79], v[78:79], v[94:95], v[120:121]
	v_pk_mul_f32 v[122:123], v[72:73], v[96:97]
	v_pk_mul_f32 v[124:125], v[76:77], v[96:97]
	v_pk_fma_f32 v[122:123], v[74:75], v[98:99], v[122:123]
	v_pk_fma_f32 v[124:125], v[78:79], v[98:99], v[124:125]
	v_add_f32_e32 v126, v122, v123
	v_add_f32_e32 v127, v124, v125
	ds_write_b64 v187, v[126:127] offset:30720
	ds_read_b128 v[84:87], v161 offset:12544
	ds_read_b128 v[88:91], v161 offset:20736
	ds_read_b128 v[100:103], v161 offset:28928
	ds_read_b64 v[104:105], v82 offset:45312
	ds_read_b128 v[92:95], v161 offset:4352
	ds_read_b128 v[96:99], v161 offset:37120
	s_waitcnt lgkmcnt(7)
	v_pk_mul_f32 v[106:107], v[72:73], v[30:31]
	v_pk_mul_f32 v[108:109], v[76:77], v[30:31]
	v_pk_fma_f32 v[106:107], v[74:75], v[32:33], v[106:107]
	v_pk_fma_f32 v[108:109], v[78:79], v[32:33], v[108:109]
	v_add_f32_e32 v110, v106, v107
	v_add_f32_e32 v112, v108, v109
	s_nop 0
	v_add_f32_dpp v110, v110, v110 quad_perm:[1,0,3,2] row_mask:0xf bank_mask:0xf bound_ctrl:1
	v_add_f32_dpp v112, v112, v112 quad_perm:[1,0,3,2] row_mask:0xf bank_mask:0xf bound_ctrl:1
	s_nop 0
	v_add_f32_dpp v110, v110, v110 quad_perm:[2,3,0,1] row_mask:0xf bank_mask:0xf bound_ctrl:1
	v_add_f32_dpp v112, v112, v112 quad_perm:[2,3,0,1] row_mask:0xf bank_mask:0xf bound_ctrl:1
	s_nop 0
	v_add_f32_dpp v110, v110, v110 row_half_mirror row_mask:0xf bank_mask:0xf bound_ctrl:1
	v_add_f32_dpp v112, v112, v112 row_half_mirror row_mask:0xf bank_mask:0xf bound_ctrl:1
	s_nop 0
	v_add_f32_dpp v110, v110, v110 row_ror:8 row_mask:0xf bank_mask:0xf bound_ctrl:1
	v_add_f32_dpp v112, v112, v112 row_ror:8 row_mask:0xf bank_mask:0xf bound_ctrl:1
	v_pk_mul_f32 v[114:115], v[34:35], v[110:111] op_sel_hi:[1,0]
	v_pk_mul_f32 v[116:117], v[34:35], v[112:113] op_sel_hi:[1,0]
	v_pk_mul_f32 v[118:119], v[36:37], v[110:111] op_sel_hi:[1,0]
	v_pk_mul_f32 v[120:121], v[36:37], v[112:113] op_sel_hi:[1,0]
	v_pk_fma_f32 v[114:115], v[46:47], v[80:81], v[114:115] op_sel_hi:[1,0,1]
	v_pk_fma_f32 v[116:117], v[46:47], v[80:81], v[116:117] op_sel:[0,1,0]
	v_pk_fma_f32 v[118:119], v[48:49], v[80:81], v[118:119] op_sel_hi:[1,0,1]
	v_pk_fma_f32 v[120:121], v[48:49], v[80:81], v[120:121] op_sel:[0,1,0]
	v_pk_fma_f32 v[72:73], v[72:73], v[38:39], v[114:115]
	v_pk_fma_f32 v[76:77], v[76:77], v[38:39], v[116:117]
	v_pk_fma_f32 v[74:75], v[74:75], v[40:41], v[118:119]
	v_pk_fma_f32 v[78:79], v[78:79], v[40:41], v[120:121]
	v_pk_mul_f32 v[122:123], v[72:73], v[42:43]
	v_pk_mul_f32 v[124:125], v[76:77], v[42:43]
	v_pk_fma_f32 v[122:123], v[74:75], v[44:45], v[122:123]
	v_pk_fma_f32 v[124:125], v[78:79], v[44:45], v[124:125]
	v_add_f32_e32 v126, v122, v123
	v_add_f32_e32 v127, v124, v125
	ds_write_b64 v187, v[126:127] offset:32768
	ds_read_b128 v[30:33], v161 offset:12800
	ds_read_b128 v[34:37], v161 offset:20992
	ds_read_b128 v[46:49], v161 offset:29184
	ds_read_b64 v[80:81], v82 offset:45568
	ds_read_b128 v[38:41], v161 offset:4608
	ds_read_b128 v[42:45], v161 offset:37376
	s_waitcnt lgkmcnt(7)
	v_pk_mul_f32 v[106:107], v[72:73], v[84:85]
	v_pk_mul_f32 v[108:109], v[76:77], v[84:85]
	v_pk_fma_f32 v[106:107], v[74:75], v[86:87], v[106:107]
	v_pk_fma_f32 v[108:109], v[78:79], v[86:87], v[108:109]
	v_add_f32_e32 v110, v106, v107
	v_add_f32_e32 v112, v108, v109
	s_nop 0
	v_add_f32_dpp v110, v110, v110 quad_perm:[1,0,3,2] row_mask:0xf bank_mask:0xf bound_ctrl:1
	v_add_f32_dpp v112, v112, v112 quad_perm:[1,0,3,2] row_mask:0xf bank_mask:0xf bound_ctrl:1
	s_nop 0
	v_add_f32_dpp v110, v110, v110 quad_perm:[2,3,0,1] row_mask:0xf bank_mask:0xf bound_ctrl:1
	v_add_f32_dpp v112, v112, v112 quad_perm:[2,3,0,1] row_mask:0xf bank_mask:0xf bound_ctrl:1
	s_nop 0
	v_add_f32_dpp v110, v110, v110 row_half_mirror row_mask:0xf bank_mask:0xf bound_ctrl:1
	v_add_f32_dpp v112, v112, v112 row_half_mirror row_mask:0xf bank_mask:0xf bound_ctrl:1
	s_nop 0
	v_add_f32_dpp v110, v110, v110 row_ror:8 row_mask:0xf bank_mask:0xf bound_ctrl:1
	v_add_f32_dpp v112, v112, v112 row_ror:8 row_mask:0xf bank_mask:0xf bound_ctrl:1
	v_pk_mul_f32 v[114:115], v[88:89], v[110:111] op_sel_hi:[1,0]
	v_pk_mul_f32 v[116:117], v[88:89], v[112:113] op_sel_hi:[1,0]
	v_pk_mul_f32 v[118:119], v[90:91], v[110:111] op_sel_hi:[1,0]
	v_pk_mul_f32 v[120:121], v[90:91], v[112:113] op_sel_hi:[1,0]
	v_pk_fma_f32 v[114:115], v[100:101], v[104:105], v[114:115] op_sel_hi:[1,0,1]
	v_pk_fma_f32 v[116:117], v[100:101], v[104:105], v[116:117] op_sel:[0,1,0]
	v_pk_fma_f32 v[118:119], v[102:103], v[104:105], v[118:119] op_sel_hi:[1,0,1]
	v_pk_fma_f32 v[120:121], v[102:103], v[104:105], v[120:121] op_sel:[0,1,0]
	v_pk_fma_f32 v[72:73], v[72:73], v[92:93], v[114:115]
	v_pk_fma_f32 v[76:77], v[76:77], v[92:93], v[116:117]
	v_pk_fma_f32 v[74:75], v[74:75], v[94:95], v[118:119]
	v_pk_fma_f32 v[78:79], v[78:79], v[94:95], v[120:121]
	v_pk_mul_f32 v[122:123], v[72:73], v[96:97]
	v_pk_mul_f32 v[124:125], v[76:77], v[96:97]
	v_pk_fma_f32 v[122:123], v[74:75], v[98:99], v[122:123]
	v_pk_fma_f32 v[124:125], v[78:79], v[98:99], v[124:125]
	v_add_f32_e32 v126, v122, v123
	v_add_f32_e32 v127, v124, v125
	ds_write_b64 v187, v[126:127] offset:34816
	ds_read_b128 v[84:87], v161 offset:13056
	ds_read_b128 v[88:91], v161 offset:21248
	ds_read_b128 v[100:103], v161 offset:29440
	ds_read_b64 v[104:105], v82 offset:45824
	ds_read_b128 v[92:95], v161 offset:4864
	ds_read_b128 v[96:99], v161 offset:37632
	s_waitcnt lgkmcnt(7)
	v_pk_mul_f32 v[106:107], v[72:73], v[30:31]
	v_pk_mul_f32 v[108:109], v[76:77], v[30:31]
	v_pk_fma_f32 v[106:107], v[74:75], v[32:33], v[106:107]
	v_pk_fma_f32 v[108:109], v[78:79], v[32:33], v[108:109]
	v_add_f32_e32 v110, v106, v107
	v_add_f32_e32 v112, v108, v109
	s_nop 0
	v_add_f32_dpp v110, v110, v110 quad_perm:[1,0,3,2] row_mask:0xf bank_mask:0xf bound_ctrl:1
	v_add_f32_dpp v112, v112, v112 quad_perm:[1,0,3,2] row_mask:0xf bank_mask:0xf bound_ctrl:1
	s_nop 0
	v_add_f32_dpp v110, v110, v110 quad_perm:[2,3,0,1] row_mask:0xf bank_mask:0xf bound_ctrl:1
	v_add_f32_dpp v112, v112, v112 quad_perm:[2,3,0,1] row_mask:0xf bank_mask:0xf bound_ctrl:1
	s_nop 0
	v_add_f32_dpp v110, v110, v110 row_half_mirror row_mask:0xf bank_mask:0xf bound_ctrl:1
	v_add_f32_dpp v112, v112, v112 row_half_mirror row_mask:0xf bank_mask:0xf bound_ctrl:1
	s_nop 0
	v_add_f32_dpp v110, v110, v110 row_ror:8 row_mask:0xf bank_mask:0xf bound_ctrl:1
	v_add_f32_dpp v112, v112, v112 row_ror:8 row_mask:0xf bank_mask:0xf bound_ctrl:1
	v_pk_mul_f32 v[114:115], v[34:35], v[110:111] op_sel_hi:[1,0]
	v_pk_mul_f32 v[116:117], v[34:35], v[112:113] op_sel_hi:[1,0]
	v_pk_mul_f32 v[118:119], v[36:37], v[110:111] op_sel_hi:[1,0]
	v_pk_mul_f32 v[120:121], v[36:37], v[112:113] op_sel_hi:[1,0]
	v_pk_fma_f32 v[114:115], v[46:47], v[80:81], v[114:115] op_sel_hi:[1,0,1]
	v_pk_fma_f32 v[116:117], v[46:47], v[80:81], v[116:117] op_sel:[0,1,0]
	v_pk_fma_f32 v[118:119], v[48:49], v[80:81], v[118:119] op_sel_hi:[1,0,1]
	v_pk_fma_f32 v[120:121], v[48:49], v[80:81], v[120:121] op_sel:[0,1,0]
	v_pk_fma_f32 v[72:73], v[72:73], v[38:39], v[114:115]
	v_pk_fma_f32 v[76:77], v[76:77], v[38:39], v[116:117]
	v_pk_fma_f32 v[74:75], v[74:75], v[40:41], v[118:119]
	v_pk_fma_f32 v[78:79], v[78:79], v[40:41], v[120:121]
	v_pk_mul_f32 v[122:123], v[72:73], v[42:43]
	v_pk_mul_f32 v[124:125], v[76:77], v[42:43]
	v_pk_fma_f32 v[122:123], v[74:75], v[44:45], v[122:123]
	v_pk_fma_f32 v[124:125], v[78:79], v[44:45], v[124:125]
	v_add_f32_e32 v126, v122, v123
	v_add_f32_e32 v127, v124, v125
	ds_write_b64 v187, v[126:127] offset:36864
	ds_read_b128 v[30:33], v161 offset:13312
	ds_read_b128 v[34:37], v161 offset:21504
	ds_read_b128 v[46:49], v161 offset:29696
	ds_read_b64 v[80:81], v82 offset:46080
	ds_read_b128 v[38:41], v161 offset:5120
	ds_read_b128 v[42:45], v161 offset:37888
	s_waitcnt lgkmcnt(7)
	v_pk_mul_f32 v[106:107], v[72:73], v[84:85]
	v_pk_mul_f32 v[108:109], v[76:77], v[84:85]
	v_pk_fma_f32 v[106:107], v[74:75], v[86:87], v[106:107]
	v_pk_fma_f32 v[108:109], v[78:79], v[86:87], v[108:109]
	v_add_f32_e32 v110, v106, v107
	v_add_f32_e32 v112, v108, v109
	s_nop 0
	v_add_f32_dpp v110, v110, v110 quad_perm:[1,0,3,2] row_mask:0xf bank_mask:0xf bound_ctrl:1
	v_add_f32_dpp v112, v112, v112 quad_perm:[1,0,3,2] row_mask:0xf bank_mask:0xf bound_ctrl:1
	s_nop 0
	v_add_f32_dpp v110, v110, v110 quad_perm:[2,3,0,1] row_mask:0xf bank_mask:0xf bound_ctrl:1
	v_add_f32_dpp v112, v112, v112 quad_perm:[2,3,0,1] row_mask:0xf bank_mask:0xf bound_ctrl:1
	s_nop 0
	v_add_f32_dpp v110, v110, v110 row_half_mirror row_mask:0xf bank_mask:0xf bound_ctrl:1
	v_add_f32_dpp v112, v112, v112 row_half_mirror row_mask:0xf bank_mask:0xf bound_ctrl:1
	s_nop 0
	v_add_f32_dpp v110, v110, v110 row_ror:8 row_mask:0xf bank_mask:0xf bound_ctrl:1
	v_add_f32_dpp v112, v112, v112 row_ror:8 row_mask:0xf bank_mask:0xf bound_ctrl:1
	v_pk_mul_f32 v[114:115], v[88:89], v[110:111] op_sel_hi:[1,0]
	v_pk_mul_f32 v[116:117], v[88:89], v[112:113] op_sel_hi:[1,0]
	v_pk_mul_f32 v[118:119], v[90:91], v[110:111] op_sel_hi:[1,0]
	v_pk_mul_f32 v[120:121], v[90:91], v[112:113] op_sel_hi:[1,0]
	v_pk_fma_f32 v[114:115], v[100:101], v[104:105], v[114:115] op_sel_hi:[1,0,1]
	v_pk_fma_f32 v[116:117], v[100:101], v[104:105], v[116:117] op_sel:[0,1,0]
	v_pk_fma_f32 v[118:119], v[102:103], v[104:105], v[118:119] op_sel_hi:[1,0,1]
	v_pk_fma_f32 v[120:121], v[102:103], v[104:105], v[120:121] op_sel:[0,1,0]
	v_pk_fma_f32 v[72:73], v[72:73], v[92:93], v[114:115]
	v_pk_fma_f32 v[76:77], v[76:77], v[92:93], v[116:117]
	v_pk_fma_f32 v[74:75], v[74:75], v[94:95], v[118:119]
	v_pk_fma_f32 v[78:79], v[78:79], v[94:95], v[120:121]
	v_pk_mul_f32 v[122:123], v[72:73], v[96:97]
	v_pk_mul_f32 v[124:125], v[76:77], v[96:97]
	v_pk_fma_f32 v[122:123], v[74:75], v[98:99], v[122:123]
	v_pk_fma_f32 v[124:125], v[78:79], v[98:99], v[124:125]
	v_add_f32_e32 v126, v122, v123
	v_add_f32_e32 v127, v124, v125
	ds_write_b64 v187, v[126:127] offset:38912
	ds_read_b128 v[84:87], v161 offset:13568
	ds_read_b128 v[88:91], v161 offset:21760
	ds_read_b128 v[100:103], v161 offset:29952
	ds_read_b64 v[104:105], v82 offset:46336
	ds_read_b128 v[92:95], v161 offset:5376
	ds_read_b128 v[96:99], v161 offset:38144
	s_waitcnt lgkmcnt(7)
	v_pk_mul_f32 v[106:107], v[72:73], v[30:31]
	v_pk_mul_f32 v[108:109], v[76:77], v[30:31]
	v_pk_fma_f32 v[106:107], v[74:75], v[32:33], v[106:107]
	v_pk_fma_f32 v[108:109], v[78:79], v[32:33], v[108:109]
	v_add_f32_e32 v110, v106, v107
	v_add_f32_e32 v112, v108, v109
	s_nop 0
	v_add_f32_dpp v110, v110, v110 quad_perm:[1,0,3,2] row_mask:0xf bank_mask:0xf bound_ctrl:1
	v_add_f32_dpp v112, v112, v112 quad_perm:[1,0,3,2] row_mask:0xf bank_mask:0xf bound_ctrl:1
	s_nop 0
	v_add_f32_dpp v110, v110, v110 quad_perm:[2,3,0,1] row_mask:0xf bank_mask:0xf bound_ctrl:1
	v_add_f32_dpp v112, v112, v112 quad_perm:[2,3,0,1] row_mask:0xf bank_mask:0xf bound_ctrl:1
	s_nop 0
	v_add_f32_dpp v110, v110, v110 row_half_mirror row_mask:0xf bank_mask:0xf bound_ctrl:1
	v_add_f32_dpp v112, v112, v112 row_half_mirror row_mask:0xf bank_mask:0xf bound_ctrl:1
	s_nop 0
	v_add_f32_dpp v110, v110, v110 row_ror:8 row_mask:0xf bank_mask:0xf bound_ctrl:1
	v_add_f32_dpp v112, v112, v112 row_ror:8 row_mask:0xf bank_mask:0xf bound_ctrl:1
	v_pk_mul_f32 v[114:115], v[34:35], v[110:111] op_sel_hi:[1,0]
	v_pk_mul_f32 v[116:117], v[34:35], v[112:113] op_sel_hi:[1,0]
	v_pk_mul_f32 v[118:119], v[36:37], v[110:111] op_sel_hi:[1,0]
	v_pk_mul_f32 v[120:121], v[36:37], v[112:113] op_sel_hi:[1,0]
	v_pk_fma_f32 v[114:115], v[46:47], v[80:81], v[114:115] op_sel_hi:[1,0,1]
	v_pk_fma_f32 v[116:117], v[46:47], v[80:81], v[116:117] op_sel:[0,1,0]
	v_pk_fma_f32 v[118:119], v[48:49], v[80:81], v[118:119] op_sel_hi:[1,0,1]
	v_pk_fma_f32 v[120:121], v[48:49], v[80:81], v[120:121] op_sel:[0,1,0]
	v_pk_fma_f32 v[72:73], v[72:73], v[38:39], v[114:115]
	v_pk_fma_f32 v[76:77], v[76:77], v[38:39], v[116:117]
	v_pk_fma_f32 v[74:75], v[74:75], v[40:41], v[118:119]
	v_pk_fma_f32 v[78:79], v[78:79], v[40:41], v[120:121]
	v_pk_mul_f32 v[122:123], v[72:73], v[42:43]
	v_pk_mul_f32 v[124:125], v[76:77], v[42:43]
	v_pk_fma_f32 v[122:123], v[74:75], v[44:45], v[122:123]
	v_pk_fma_f32 v[124:125], v[78:79], v[44:45], v[124:125]
	v_add_f32_e32 v126, v122, v123
	v_add_f32_e32 v127, v124, v125
	ds_write_b64 v187, v[126:127] offset:40960
	ds_read_b128 v[30:33], v161 offset:13824
	ds_read_b128 v[34:37], v161 offset:22016
	ds_read_b128 v[46:49], v161 offset:30208
	ds_read_b64 v[80:81], v82 offset:46592
	ds_read_b128 v[38:41], v161 offset:5632
	ds_read_b128 v[42:45], v161 offset:38400
	s_waitcnt lgkmcnt(7)
	v_pk_mul_f32 v[106:107], v[72:73], v[84:85]
	v_pk_mul_f32 v[108:109], v[76:77], v[84:85]
	v_pk_fma_f32 v[106:107], v[74:75], v[86:87], v[106:107]
	v_pk_fma_f32 v[108:109], v[78:79], v[86:87], v[108:109]
	v_add_f32_e32 v110, v106, v107
	v_add_f32_e32 v112, v108, v109
	s_nop 0
	v_add_f32_dpp v110, v110, v110 quad_perm:[1,0,3,2] row_mask:0xf bank_mask:0xf bound_ctrl:1
	v_add_f32_dpp v112, v112, v112 quad_perm:[1,0,3,2] row_mask:0xf bank_mask:0xf bound_ctrl:1
	s_nop 0
	v_add_f32_dpp v110, v110, v110 quad_perm:[2,3,0,1] row_mask:0xf bank_mask:0xf bound_ctrl:1
	v_add_f32_dpp v112, v112, v112 quad_perm:[2,3,0,1] row_mask:0xf bank_mask:0xf bound_ctrl:1
	s_nop 0
	v_add_f32_dpp v110, v110, v110 row_half_mirror row_mask:0xf bank_mask:0xf bound_ctrl:1
	v_add_f32_dpp v112, v112, v112 row_half_mirror row_mask:0xf bank_mask:0xf bound_ctrl:1
	s_nop 0
	v_add_f32_dpp v110, v110, v110 row_ror:8 row_mask:0xf bank_mask:0xf bound_ctrl:1
	v_add_f32_dpp v112, v112, v112 row_ror:8 row_mask:0xf bank_mask:0xf bound_ctrl:1
	v_pk_mul_f32 v[114:115], v[88:89], v[110:111] op_sel_hi:[1,0]
	v_pk_mul_f32 v[116:117], v[88:89], v[112:113] op_sel_hi:[1,0]
	v_pk_mul_f32 v[118:119], v[90:91], v[110:111] op_sel_hi:[1,0]
	v_pk_mul_f32 v[120:121], v[90:91], v[112:113] op_sel_hi:[1,0]
	v_pk_fma_f32 v[114:115], v[100:101], v[104:105], v[114:115] op_sel_hi:[1,0,1]
	v_pk_fma_f32 v[116:117], v[100:101], v[104:105], v[116:117] op_sel:[0,1,0]
	v_pk_fma_f32 v[118:119], v[102:103], v[104:105], v[118:119] op_sel_hi:[1,0,1]
	v_pk_fma_f32 v[120:121], v[102:103], v[104:105], v[120:121] op_sel:[0,1,0]
	v_pk_fma_f32 v[72:73], v[72:73], v[92:93], v[114:115]
	v_pk_fma_f32 v[76:77], v[76:77], v[92:93], v[116:117]
	v_pk_fma_f32 v[74:75], v[74:75], v[94:95], v[118:119]
	v_pk_fma_f32 v[78:79], v[78:79], v[94:95], v[120:121]
	v_pk_mul_f32 v[122:123], v[72:73], v[96:97]
	v_pk_mul_f32 v[124:125], v[76:77], v[96:97]
	v_pk_fma_f32 v[122:123], v[74:75], v[98:99], v[122:123]
	v_pk_fma_f32 v[124:125], v[78:79], v[98:99], v[124:125]
	v_add_f32_e32 v126, v122, v123
	v_add_f32_e32 v127, v124, v125
	ds_write_b64 v187, v[126:127] offset:43008
	ds_read_b128 v[84:87], v161 offset:14080
	ds_read_b128 v[88:91], v161 offset:22272
	ds_read_b128 v[100:103], v161 offset:30464
	ds_read_b64 v[104:105], v82 offset:46848
	ds_read_b128 v[92:95], v161 offset:5888
	ds_read_b128 v[96:99], v161 offset:38656
	s_waitcnt lgkmcnt(7)
	v_pk_mul_f32 v[106:107], v[72:73], v[30:31]
	v_pk_mul_f32 v[108:109], v[76:77], v[30:31]
	v_pk_fma_f32 v[106:107], v[74:75], v[32:33], v[106:107]
	v_pk_fma_f32 v[108:109], v[78:79], v[32:33], v[108:109]
	v_add_f32_e32 v110, v106, v107
	v_add_f32_e32 v112, v108, v109
	s_nop 0
	v_add_f32_dpp v110, v110, v110 quad_perm:[1,0,3,2] row_mask:0xf bank_mask:0xf bound_ctrl:1
	v_add_f32_dpp v112, v112, v112 quad_perm:[1,0,3,2] row_mask:0xf bank_mask:0xf bound_ctrl:1
	s_nop 0
	v_add_f32_dpp v110, v110, v110 quad_perm:[2,3,0,1] row_mask:0xf bank_mask:0xf bound_ctrl:1
	v_add_f32_dpp v112, v112, v112 quad_perm:[2,3,0,1] row_mask:0xf bank_mask:0xf bound_ctrl:1
	s_nop 0
	v_add_f32_dpp v110, v110, v110 row_half_mirror row_mask:0xf bank_mask:0xf bound_ctrl:1
	v_add_f32_dpp v112, v112, v112 row_half_mirror row_mask:0xf bank_mask:0xf bound_ctrl:1
	s_nop 0
	v_add_f32_dpp v110, v110, v110 row_ror:8 row_mask:0xf bank_mask:0xf bound_ctrl:1
	v_add_f32_dpp v112, v112, v112 row_ror:8 row_mask:0xf bank_mask:0xf bound_ctrl:1
	v_pk_mul_f32 v[114:115], v[34:35], v[110:111] op_sel_hi:[1,0]
	v_pk_mul_f32 v[116:117], v[34:35], v[112:113] op_sel_hi:[1,0]
	v_pk_mul_f32 v[118:119], v[36:37], v[110:111] op_sel_hi:[1,0]
	v_pk_mul_f32 v[120:121], v[36:37], v[112:113] op_sel_hi:[1,0]
	v_pk_fma_f32 v[114:115], v[46:47], v[80:81], v[114:115] op_sel_hi:[1,0,1]
	v_pk_fma_f32 v[116:117], v[46:47], v[80:81], v[116:117] op_sel:[0,1,0]
	v_pk_fma_f32 v[118:119], v[48:49], v[80:81], v[118:119] op_sel_hi:[1,0,1]
	v_pk_fma_f32 v[120:121], v[48:49], v[80:81], v[120:121] op_sel:[0,1,0]
	v_pk_fma_f32 v[72:73], v[72:73], v[38:39], v[114:115]
	v_pk_fma_f32 v[76:77], v[76:77], v[38:39], v[116:117]
	v_pk_fma_f32 v[74:75], v[74:75], v[40:41], v[118:119]
	v_pk_fma_f32 v[78:79], v[78:79], v[40:41], v[120:121]
	v_pk_mul_f32 v[122:123], v[72:73], v[42:43]
	v_pk_mul_f32 v[124:125], v[76:77], v[42:43]
	v_pk_fma_f32 v[122:123], v[74:75], v[44:45], v[122:123]
	v_pk_fma_f32 v[124:125], v[78:79], v[44:45], v[124:125]
	v_add_f32_e32 v126, v122, v123
	v_add_f32_e32 v127, v124, v125
	ds_write_b64 v187, v[126:127] offset:45056
	ds_read_b128 v[30:33], v161 offset:14336
	ds_read_b128 v[34:37], v161 offset:22528
	ds_read_b128 v[46:49], v161 offset:30720
	ds_read_b64 v[80:81], v82 offset:47104
	ds_read_b128 v[38:41], v161 offset:6144
	ds_read_b128 v[42:45], v161 offset:38912
	s_waitcnt lgkmcnt(7)
	v_pk_mul_f32 v[106:107], v[72:73], v[84:85]
	v_pk_mul_f32 v[108:109], v[76:77], v[84:85]
	v_pk_fma_f32 v[106:107], v[74:75], v[86:87], v[106:107]
	v_pk_fma_f32 v[108:109], v[78:79], v[86:87], v[108:109]
	v_add_f32_e32 v110, v106, v107
	v_add_f32_e32 v112, v108, v109
	s_nop 0
	v_add_f32_dpp v110, v110, v110 quad_perm:[1,0,3,2] row_mask:0xf bank_mask:0xf bound_ctrl:1
	v_add_f32_dpp v112, v112, v112 quad_perm:[1,0,3,2] row_mask:0xf bank_mask:0xf bound_ctrl:1
	s_nop 0
	v_add_f32_dpp v110, v110, v110 quad_perm:[2,3,0,1] row_mask:0xf bank_mask:0xf bound_ctrl:1
	v_add_f32_dpp v112, v112, v112 quad_perm:[2,3,0,1] row_mask:0xf bank_mask:0xf bound_ctrl:1
	s_nop 0
	v_add_f32_dpp v110, v110, v110 row_half_mirror row_mask:0xf bank_mask:0xf bound_ctrl:1
	v_add_f32_dpp v112, v112, v112 row_half_mirror row_mask:0xf bank_mask:0xf bound_ctrl:1
	s_nop 0
	v_add_f32_dpp v110, v110, v110 row_ror:8 row_mask:0xf bank_mask:0xf bound_ctrl:1
	v_add_f32_dpp v112, v112, v112 row_ror:8 row_mask:0xf bank_mask:0xf bound_ctrl:1
	v_pk_mul_f32 v[114:115], v[88:89], v[110:111] op_sel_hi:[1,0]
	v_pk_mul_f32 v[116:117], v[88:89], v[112:113] op_sel_hi:[1,0]
	v_pk_mul_f32 v[118:119], v[90:91], v[110:111] op_sel_hi:[1,0]
	v_pk_mul_f32 v[120:121], v[90:91], v[112:113] op_sel_hi:[1,0]
	v_pk_fma_f32 v[114:115], v[100:101], v[104:105], v[114:115] op_sel_hi:[1,0,1]
	v_pk_fma_f32 v[116:117], v[100:101], v[104:105], v[116:117] op_sel:[0,1,0]
	v_pk_fma_f32 v[118:119], v[102:103], v[104:105], v[118:119] op_sel_hi:[1,0,1]
	v_pk_fma_f32 v[120:121], v[102:103], v[104:105], v[120:121] op_sel:[0,1,0]
	v_pk_fma_f32 v[72:73], v[72:73], v[92:93], v[114:115]
	v_pk_fma_f32 v[76:77], v[76:77], v[92:93], v[116:117]
	v_pk_fma_f32 v[74:75], v[74:75], v[94:95], v[118:119]
	v_pk_fma_f32 v[78:79], v[78:79], v[94:95], v[120:121]
	v_pk_mul_f32 v[122:123], v[72:73], v[96:97]
	v_pk_mul_f32 v[124:125], v[76:77], v[96:97]
	v_pk_fma_f32 v[122:123], v[74:75], v[98:99], v[122:123]
	v_pk_fma_f32 v[124:125], v[78:79], v[98:99], v[124:125]
	v_add_f32_e32 v126, v122, v123
	v_add_f32_e32 v127, v124, v125
	ds_write_b64 v187, v[126:127] offset:47104
	ds_read_b128 v[84:87], v161 offset:14592
	ds_read_b128 v[88:91], v161 offset:22784
	ds_read_b128 v[100:103], v161 offset:30976
	ds_read_b64 v[104:105], v82 offset:47360
	ds_read_b128 v[92:95], v161 offset:6400
	ds_read_b128 v[96:99], v161 offset:39168
	s_waitcnt lgkmcnt(7)
	v_pk_mul_f32 v[106:107], v[72:73], v[30:31]
	v_pk_mul_f32 v[108:109], v[76:77], v[30:31]
	v_pk_fma_f32 v[106:107], v[74:75], v[32:33], v[106:107]
	v_pk_fma_f32 v[108:109], v[78:79], v[32:33], v[108:109]
	v_add_f32_e32 v110, v106, v107
	v_add_f32_e32 v112, v108, v109
	s_nop 0
	v_add_f32_dpp v110, v110, v110 quad_perm:[1,0,3,2] row_mask:0xf bank_mask:0xf bound_ctrl:1
	v_add_f32_dpp v112, v112, v112 quad_perm:[1,0,3,2] row_mask:0xf bank_mask:0xf bound_ctrl:1
	s_nop 0
	v_add_f32_dpp v110, v110, v110 quad_perm:[2,3,0,1] row_mask:0xf bank_mask:0xf bound_ctrl:1
	v_add_f32_dpp v112, v112, v112 quad_perm:[2,3,0,1] row_mask:0xf bank_mask:0xf bound_ctrl:1
	s_nop 0
	v_add_f32_dpp v110, v110, v110 row_half_mirror row_mask:0xf bank_mask:0xf bound_ctrl:1
	v_add_f32_dpp v112, v112, v112 row_half_mirror row_mask:0xf bank_mask:0xf bound_ctrl:1
	s_nop 0
	v_add_f32_dpp v110, v110, v110 row_ror:8 row_mask:0xf bank_mask:0xf bound_ctrl:1
	v_add_f32_dpp v112, v112, v112 row_ror:8 row_mask:0xf bank_mask:0xf bound_ctrl:1
	v_pk_mul_f32 v[114:115], v[34:35], v[110:111] op_sel_hi:[1,0]
	v_pk_mul_f32 v[116:117], v[34:35], v[112:113] op_sel_hi:[1,0]
	v_pk_mul_f32 v[118:119], v[36:37], v[110:111] op_sel_hi:[1,0]
	v_pk_mul_f32 v[120:121], v[36:37], v[112:113] op_sel_hi:[1,0]
	v_pk_fma_f32 v[114:115], v[46:47], v[80:81], v[114:115] op_sel_hi:[1,0,1]
	v_pk_fma_f32 v[116:117], v[46:47], v[80:81], v[116:117] op_sel:[0,1,0]
	v_pk_fma_f32 v[118:119], v[48:49], v[80:81], v[118:119] op_sel_hi:[1,0,1]
	v_pk_fma_f32 v[120:121], v[48:49], v[80:81], v[120:121] op_sel:[0,1,0]
	v_pk_fma_f32 v[72:73], v[72:73], v[38:39], v[114:115]
	v_pk_fma_f32 v[76:77], v[76:77], v[38:39], v[116:117]
	v_pk_fma_f32 v[74:75], v[74:75], v[40:41], v[118:119]
	v_pk_fma_f32 v[78:79], v[78:79], v[40:41], v[120:121]
	v_pk_mul_f32 v[122:123], v[72:73], v[42:43]
	v_pk_mul_f32 v[124:125], v[76:77], v[42:43]
	v_pk_fma_f32 v[122:123], v[74:75], v[44:45], v[122:123]
	v_pk_fma_f32 v[124:125], v[78:79], v[44:45], v[124:125]
	v_add_f32_e32 v126, v122, v123
	v_add_f32_e32 v127, v124, v125
	ds_write_b64 v187, v[126:127] offset:49152
	ds_read_b128 v[30:33], v161 offset:14848
	ds_read_b128 v[34:37], v161 offset:23040
	ds_read_b128 v[46:49], v161 offset:31232
	ds_read_b64 v[80:81], v82 offset:47616
	ds_read_b128 v[38:41], v161 offset:6656
	ds_read_b128 v[42:45], v161 offset:39424
	s_waitcnt lgkmcnt(7)
	v_pk_mul_f32 v[106:107], v[72:73], v[84:85]
	v_pk_mul_f32 v[108:109], v[76:77], v[84:85]
	v_pk_fma_f32 v[106:107], v[74:75], v[86:87], v[106:107]
	v_pk_fma_f32 v[108:109], v[78:79], v[86:87], v[108:109]
	v_add_f32_e32 v110, v106, v107
	v_add_f32_e32 v112, v108, v109
	s_nop 0
	v_add_f32_dpp v110, v110, v110 quad_perm:[1,0,3,2] row_mask:0xf bank_mask:0xf bound_ctrl:1
	v_add_f32_dpp v112, v112, v112 quad_perm:[1,0,3,2] row_mask:0xf bank_mask:0xf bound_ctrl:1
	s_nop 0
	v_add_f32_dpp v110, v110, v110 quad_perm:[2,3,0,1] row_mask:0xf bank_mask:0xf bound_ctrl:1
	v_add_f32_dpp v112, v112, v112 quad_perm:[2,3,0,1] row_mask:0xf bank_mask:0xf bound_ctrl:1
	s_nop 0
	v_add_f32_dpp v110, v110, v110 row_half_mirror row_mask:0xf bank_mask:0xf bound_ctrl:1
	v_add_f32_dpp v112, v112, v112 row_half_mirror row_mask:0xf bank_mask:0xf bound_ctrl:1
	s_nop 0
	v_add_f32_dpp v110, v110, v110 row_ror:8 row_mask:0xf bank_mask:0xf bound_ctrl:1
	v_add_f32_dpp v112, v112, v112 row_ror:8 row_mask:0xf bank_mask:0xf bound_ctrl:1
	v_pk_mul_f32 v[114:115], v[88:89], v[110:111] op_sel_hi:[1,0]
	v_pk_mul_f32 v[116:117], v[88:89], v[112:113] op_sel_hi:[1,0]
	v_pk_mul_f32 v[118:119], v[90:91], v[110:111] op_sel_hi:[1,0]
	v_pk_mul_f32 v[120:121], v[90:91], v[112:113] op_sel_hi:[1,0]
	v_pk_fma_f32 v[114:115], v[100:101], v[104:105], v[114:115] op_sel_hi:[1,0,1]
	v_pk_fma_f32 v[116:117], v[100:101], v[104:105], v[116:117] op_sel:[0,1,0]
	v_pk_fma_f32 v[118:119], v[102:103], v[104:105], v[118:119] op_sel_hi:[1,0,1]
	v_pk_fma_f32 v[120:121], v[102:103], v[104:105], v[120:121] op_sel:[0,1,0]
	v_pk_fma_f32 v[72:73], v[72:73], v[92:93], v[114:115]
	v_pk_fma_f32 v[76:77], v[76:77], v[92:93], v[116:117]
	v_pk_fma_f32 v[74:75], v[74:75], v[94:95], v[118:119]
	v_pk_fma_f32 v[78:79], v[78:79], v[94:95], v[120:121]
	v_pk_mul_f32 v[122:123], v[72:73], v[96:97]
	v_pk_mul_f32 v[124:125], v[76:77], v[96:97]
	v_pk_fma_f32 v[122:123], v[74:75], v[98:99], v[122:123]
	v_pk_fma_f32 v[124:125], v[78:79], v[98:99], v[124:125]
	v_add_f32_e32 v126, v122, v123
	v_add_f32_e32 v127, v124, v125
	ds_write_b64 v187, v[126:127] offset:51200
	ds_read_b128 v[84:87], v161 offset:15104
	ds_read_b128 v[88:91], v161 offset:23296
	ds_read_b128 v[100:103], v161 offset:31488
	ds_read_b64 v[104:105], v82 offset:47872
	ds_read_b128 v[92:95], v161 offset:6912
	ds_read_b128 v[96:99], v161 offset:39680
	s_waitcnt lgkmcnt(7)
	v_pk_mul_f32 v[106:107], v[72:73], v[30:31]
	v_pk_mul_f32 v[108:109], v[76:77], v[30:31]
	v_pk_fma_f32 v[106:107], v[74:75], v[32:33], v[106:107]
	v_pk_fma_f32 v[108:109], v[78:79], v[32:33], v[108:109]
	v_add_f32_e32 v110, v106, v107
	v_add_f32_e32 v112, v108, v109
	s_nop 0
	v_add_f32_dpp v110, v110, v110 quad_perm:[1,0,3,2] row_mask:0xf bank_mask:0xf bound_ctrl:1
	v_add_f32_dpp v112, v112, v112 quad_perm:[1,0,3,2] row_mask:0xf bank_mask:0xf bound_ctrl:1
	s_nop 0
	v_add_f32_dpp v110, v110, v110 quad_perm:[2,3,0,1] row_mask:0xf bank_mask:0xf bound_ctrl:1
	v_add_f32_dpp v112, v112, v112 quad_perm:[2,3,0,1] row_mask:0xf bank_mask:0xf bound_ctrl:1
	s_nop 0
	v_add_f32_dpp v110, v110, v110 row_half_mirror row_mask:0xf bank_mask:0xf bound_ctrl:1
	v_add_f32_dpp v112, v112, v112 row_half_mirror row_mask:0xf bank_mask:0xf bound_ctrl:1
	s_nop 0
	v_add_f32_dpp v110, v110, v110 row_ror:8 row_mask:0xf bank_mask:0xf bound_ctrl:1
	v_add_f32_dpp v112, v112, v112 row_ror:8 row_mask:0xf bank_mask:0xf bound_ctrl:1
	v_pk_mul_f32 v[114:115], v[34:35], v[110:111] op_sel_hi:[1,0]
	v_pk_mul_f32 v[116:117], v[34:35], v[112:113] op_sel_hi:[1,0]
	v_pk_mul_f32 v[118:119], v[36:37], v[110:111] op_sel_hi:[1,0]
	v_pk_mul_f32 v[120:121], v[36:37], v[112:113] op_sel_hi:[1,0]
	v_pk_fma_f32 v[114:115], v[46:47], v[80:81], v[114:115] op_sel_hi:[1,0,1]
	v_pk_fma_f32 v[116:117], v[46:47], v[80:81], v[116:117] op_sel:[0,1,0]
	v_pk_fma_f32 v[118:119], v[48:49], v[80:81], v[118:119] op_sel_hi:[1,0,1]
	v_pk_fma_f32 v[120:121], v[48:49], v[80:81], v[120:121] op_sel:[0,1,0]
	v_pk_fma_f32 v[72:73], v[72:73], v[38:39], v[114:115]
	v_pk_fma_f32 v[76:77], v[76:77], v[38:39], v[116:117]
	v_pk_fma_f32 v[74:75], v[74:75], v[40:41], v[118:119]
	v_pk_fma_f32 v[78:79], v[78:79], v[40:41], v[120:121]
	v_pk_mul_f32 v[122:123], v[72:73], v[42:43]
	v_pk_mul_f32 v[124:125], v[76:77], v[42:43]
	v_pk_fma_f32 v[122:123], v[74:75], v[44:45], v[122:123]
	v_pk_fma_f32 v[124:125], v[78:79], v[44:45], v[124:125]
	v_add_f32_e32 v126, v122, v123
	v_add_f32_e32 v127, v124, v125
	ds_write_b64 v187, v[126:127] offset:53248
	ds_read_b128 v[30:33], v161 offset:15360
	ds_read_b128 v[34:37], v161 offset:23552
	ds_read_b128 v[46:49], v161 offset:31744
	ds_read_b64 v[80:81], v82 offset:48128
	ds_read_b128 v[38:41], v161 offset:7168
	ds_read_b128 v[42:45], v161 offset:39936
	s_waitcnt lgkmcnt(7)
	v_pk_mul_f32 v[106:107], v[72:73], v[84:85]
	v_pk_mul_f32 v[108:109], v[76:77], v[84:85]
	v_pk_fma_f32 v[106:107], v[74:75], v[86:87], v[106:107]
	v_pk_fma_f32 v[108:109], v[78:79], v[86:87], v[108:109]
	v_add_f32_e32 v110, v106, v107
	v_add_f32_e32 v112, v108, v109
	s_nop 0
	v_add_f32_dpp v110, v110, v110 quad_perm:[1,0,3,2] row_mask:0xf bank_mask:0xf bound_ctrl:1
	v_add_f32_dpp v112, v112, v112 quad_perm:[1,0,3,2] row_mask:0xf bank_mask:0xf bound_ctrl:1
	s_nop 0
	v_add_f32_dpp v110, v110, v110 quad_perm:[2,3,0,1] row_mask:0xf bank_mask:0xf bound_ctrl:1
	v_add_f32_dpp v112, v112, v112 quad_perm:[2,3,0,1] row_mask:0xf bank_mask:0xf bound_ctrl:1
	s_nop 0
	v_add_f32_dpp v110, v110, v110 row_half_mirror row_mask:0xf bank_mask:0xf bound_ctrl:1
	v_add_f32_dpp v112, v112, v112 row_half_mirror row_mask:0xf bank_mask:0xf bound_ctrl:1
	s_nop 0
	v_add_f32_dpp v110, v110, v110 row_ror:8 row_mask:0xf bank_mask:0xf bound_ctrl:1
	v_add_f32_dpp v112, v112, v112 row_ror:8 row_mask:0xf bank_mask:0xf bound_ctrl:1
	v_pk_mul_f32 v[114:115], v[88:89], v[110:111] op_sel_hi:[1,0]
	v_pk_mul_f32 v[116:117], v[88:89], v[112:113] op_sel_hi:[1,0]
	v_pk_mul_f32 v[118:119], v[90:91], v[110:111] op_sel_hi:[1,0]
	v_pk_mul_f32 v[120:121], v[90:91], v[112:113] op_sel_hi:[1,0]
	v_pk_fma_f32 v[114:115], v[100:101], v[104:105], v[114:115] op_sel_hi:[1,0,1]
	v_pk_fma_f32 v[116:117], v[100:101], v[104:105], v[116:117] op_sel:[0,1,0]
	v_pk_fma_f32 v[118:119], v[102:103], v[104:105], v[118:119] op_sel_hi:[1,0,1]
	v_pk_fma_f32 v[120:121], v[102:103], v[104:105], v[120:121] op_sel:[0,1,0]
	v_pk_fma_f32 v[72:73], v[72:73], v[92:93], v[114:115]
	v_pk_fma_f32 v[76:77], v[76:77], v[92:93], v[116:117]
	v_pk_fma_f32 v[74:75], v[74:75], v[94:95], v[118:119]
	v_pk_fma_f32 v[78:79], v[78:79], v[94:95], v[120:121]
	v_pk_mul_f32 v[122:123], v[72:73], v[96:97]
	v_pk_mul_f32 v[124:125], v[76:77], v[96:97]
	v_pk_fma_f32 v[122:123], v[74:75], v[98:99], v[122:123]
	v_pk_fma_f32 v[124:125], v[78:79], v[98:99], v[124:125]
	v_add_f32_e32 v126, v122, v123
	v_add_f32_e32 v127, v124, v125
	ds_write_b64 v187, v[126:127] offset:55296
	ds_read_b128 v[84:87], v161 offset:15616
	ds_read_b128 v[88:91], v161 offset:23808
	ds_read_b128 v[100:103], v161 offset:32000
	ds_read_b64 v[104:105], v82 offset:48384
	ds_read_b128 v[92:95], v161 offset:7424
	ds_read_b128 v[96:99], v161 offset:40192
	s_waitcnt lgkmcnt(7)
	v_pk_mul_f32 v[106:107], v[72:73], v[30:31]
	v_pk_mul_f32 v[108:109], v[76:77], v[30:31]
	v_pk_fma_f32 v[106:107], v[74:75], v[32:33], v[106:107]
	v_pk_fma_f32 v[108:109], v[78:79], v[32:33], v[108:109]
	v_add_f32_e32 v110, v106, v107
	v_add_f32_e32 v112, v108, v109
	s_nop 0
	v_add_f32_dpp v110, v110, v110 quad_perm:[1,0,3,2] row_mask:0xf bank_mask:0xf bound_ctrl:1
	v_add_f32_dpp v112, v112, v112 quad_perm:[1,0,3,2] row_mask:0xf bank_mask:0xf bound_ctrl:1
	s_nop 0
	v_add_f32_dpp v110, v110, v110 quad_perm:[2,3,0,1] row_mask:0xf bank_mask:0xf bound_ctrl:1
	v_add_f32_dpp v112, v112, v112 quad_perm:[2,3,0,1] row_mask:0xf bank_mask:0xf bound_ctrl:1
	s_nop 0
	v_add_f32_dpp v110, v110, v110 row_half_mirror row_mask:0xf bank_mask:0xf bound_ctrl:1
	v_add_f32_dpp v112, v112, v112 row_half_mirror row_mask:0xf bank_mask:0xf bound_ctrl:1
	s_nop 0
	v_add_f32_dpp v110, v110, v110 row_ror:8 row_mask:0xf bank_mask:0xf bound_ctrl:1
	v_add_f32_dpp v112, v112, v112 row_ror:8 row_mask:0xf bank_mask:0xf bound_ctrl:1
	v_pk_mul_f32 v[114:115], v[34:35], v[110:111] op_sel_hi:[1,0]
	v_pk_mul_f32 v[116:117], v[34:35], v[112:113] op_sel_hi:[1,0]
	v_pk_mul_f32 v[118:119], v[36:37], v[110:111] op_sel_hi:[1,0]
	v_pk_mul_f32 v[120:121], v[36:37], v[112:113] op_sel_hi:[1,0]
	v_pk_fma_f32 v[114:115], v[46:47], v[80:81], v[114:115] op_sel_hi:[1,0,1]
	v_pk_fma_f32 v[116:117], v[46:47], v[80:81], v[116:117] op_sel:[0,1,0]
	v_pk_fma_f32 v[118:119], v[48:49], v[80:81], v[118:119] op_sel_hi:[1,0,1]
	v_pk_fma_f32 v[120:121], v[48:49], v[80:81], v[120:121] op_sel:[0,1,0]
	v_pk_fma_f32 v[72:73], v[72:73], v[38:39], v[114:115]
	v_pk_fma_f32 v[76:77], v[76:77], v[38:39], v[116:117]
	v_pk_fma_f32 v[74:75], v[74:75], v[40:41], v[118:119]
	v_pk_fma_f32 v[78:79], v[78:79], v[40:41], v[120:121]
	v_pk_mul_f32 v[122:123], v[72:73], v[42:43]
	v_pk_mul_f32 v[124:125], v[76:77], v[42:43]
	v_pk_fma_f32 v[122:123], v[74:75], v[44:45], v[122:123]
	v_pk_fma_f32 v[124:125], v[78:79], v[44:45], v[124:125]
	v_add_f32_e32 v126, v122, v123
	v_add_f32_e32 v127, v124, v125
	ds_write_b64 v187, v[126:127] offset:57344
	ds_read_b128 v[30:33], v161 offset:15872
	ds_read_b128 v[34:37], v161 offset:24064
	ds_read_b128 v[46:49], v161 offset:32256
	ds_read_b64 v[80:81], v82 offset:48640
	ds_read_b128 v[38:41], v161 offset:7680
	ds_read_b128 v[42:45], v161 offset:40448
	s_waitcnt lgkmcnt(7)
	v_pk_mul_f32 v[106:107], v[72:73], v[84:85]
	v_pk_mul_f32 v[108:109], v[76:77], v[84:85]
	v_pk_fma_f32 v[106:107], v[74:75], v[86:87], v[106:107]
	v_pk_fma_f32 v[108:109], v[78:79], v[86:87], v[108:109]
	v_add_f32_e32 v110, v106, v107
	v_add_f32_e32 v112, v108, v109
	s_nop 0
	v_add_f32_dpp v110, v110, v110 quad_perm:[1,0,3,2] row_mask:0xf bank_mask:0xf bound_ctrl:1
	v_add_f32_dpp v112, v112, v112 quad_perm:[1,0,3,2] row_mask:0xf bank_mask:0xf bound_ctrl:1
	s_nop 0
	v_add_f32_dpp v110, v110, v110 quad_perm:[2,3,0,1] row_mask:0xf bank_mask:0xf bound_ctrl:1
	v_add_f32_dpp v112, v112, v112 quad_perm:[2,3,0,1] row_mask:0xf bank_mask:0xf bound_ctrl:1
	s_nop 0
	v_add_f32_dpp v110, v110, v110 row_half_mirror row_mask:0xf bank_mask:0xf bound_ctrl:1
	v_add_f32_dpp v112, v112, v112 row_half_mirror row_mask:0xf bank_mask:0xf bound_ctrl:1
	s_nop 0
	v_add_f32_dpp v110, v110, v110 row_ror:8 row_mask:0xf bank_mask:0xf bound_ctrl:1
	v_add_f32_dpp v112, v112, v112 row_ror:8 row_mask:0xf bank_mask:0xf bound_ctrl:1
	v_pk_mul_f32 v[114:115], v[88:89], v[110:111] op_sel_hi:[1,0]
	v_pk_mul_f32 v[116:117], v[88:89], v[112:113] op_sel_hi:[1,0]
	v_pk_mul_f32 v[118:119], v[90:91], v[110:111] op_sel_hi:[1,0]
	v_pk_mul_f32 v[120:121], v[90:91], v[112:113] op_sel_hi:[1,0]
	v_pk_fma_f32 v[114:115], v[100:101], v[104:105], v[114:115] op_sel_hi:[1,0,1]
	v_pk_fma_f32 v[116:117], v[100:101], v[104:105], v[116:117] op_sel:[0,1,0]
	v_pk_fma_f32 v[118:119], v[102:103], v[104:105], v[118:119] op_sel_hi:[1,0,1]
	v_pk_fma_f32 v[120:121], v[102:103], v[104:105], v[120:121] op_sel:[0,1,0]
	v_pk_fma_f32 v[72:73], v[72:73], v[92:93], v[114:115]
	v_pk_fma_f32 v[76:77], v[76:77], v[92:93], v[116:117]
	v_pk_fma_f32 v[74:75], v[74:75], v[94:95], v[118:119]
	v_pk_fma_f32 v[78:79], v[78:79], v[94:95], v[120:121]
	v_pk_mul_f32 v[122:123], v[72:73], v[96:97]
	v_pk_mul_f32 v[124:125], v[76:77], v[96:97]
	v_pk_fma_f32 v[122:123], v[74:75], v[98:99], v[122:123]
	v_pk_fma_f32 v[124:125], v[78:79], v[98:99], v[124:125]
	v_add_f32_e32 v126, v122, v123
	v_add_f32_e32 v127, v124, v125
	ds_write_b64 v187, v[126:127] offset:59392
	ds_read_b128 v[84:87], v161 offset:16128
	ds_read_b128 v[88:91], v161 offset:24320
	ds_read_b128 v[100:103], v161 offset:32512
	ds_read_b64 v[104:105], v82 offset:48896
	ds_read_b128 v[92:95], v161 offset:7936
	ds_read_b128 v[96:99], v161 offset:40704
	s_waitcnt lgkmcnt(7)
	v_pk_mul_f32 v[106:107], v[72:73], v[30:31]
	v_pk_mul_f32 v[108:109], v[76:77], v[30:31]
	v_pk_fma_f32 v[106:107], v[74:75], v[32:33], v[106:107]
	v_pk_fma_f32 v[108:109], v[78:79], v[32:33], v[108:109]
	v_add_f32_e32 v110, v106, v107
	v_add_f32_e32 v112, v108, v109
	s_nop 0
	v_add_f32_dpp v110, v110, v110 quad_perm:[1,0,3,2] row_mask:0xf bank_mask:0xf bound_ctrl:1
	v_add_f32_dpp v112, v112, v112 quad_perm:[1,0,3,2] row_mask:0xf bank_mask:0xf bound_ctrl:1
	s_nop 0
	v_add_f32_dpp v110, v110, v110 quad_perm:[2,3,0,1] row_mask:0xf bank_mask:0xf bound_ctrl:1
	v_add_f32_dpp v112, v112, v112 quad_perm:[2,3,0,1] row_mask:0xf bank_mask:0xf bound_ctrl:1
	s_nop 0
	v_add_f32_dpp v110, v110, v110 row_half_mirror row_mask:0xf bank_mask:0xf bound_ctrl:1
	v_add_f32_dpp v112, v112, v112 row_half_mirror row_mask:0xf bank_mask:0xf bound_ctrl:1
	s_nop 0
	v_add_f32_dpp v110, v110, v110 row_ror:8 row_mask:0xf bank_mask:0xf bound_ctrl:1
	v_add_f32_dpp v112, v112, v112 row_ror:8 row_mask:0xf bank_mask:0xf bound_ctrl:1
	v_pk_mul_f32 v[114:115], v[34:35], v[110:111] op_sel_hi:[1,0]
	v_pk_mul_f32 v[116:117], v[34:35], v[112:113] op_sel_hi:[1,0]
	v_pk_mul_f32 v[118:119], v[36:37], v[110:111] op_sel_hi:[1,0]
	v_pk_mul_f32 v[120:121], v[36:37], v[112:113] op_sel_hi:[1,0]
	v_pk_fma_f32 v[114:115], v[46:47], v[80:81], v[114:115] op_sel_hi:[1,0,1]
	v_pk_fma_f32 v[116:117], v[46:47], v[80:81], v[116:117] op_sel:[0,1,0]
	v_pk_fma_f32 v[118:119], v[48:49], v[80:81], v[118:119] op_sel_hi:[1,0,1]
	v_pk_fma_f32 v[120:121], v[48:49], v[80:81], v[120:121] op_sel:[0,1,0]
	v_pk_fma_f32 v[72:73], v[72:73], v[38:39], v[114:115]
	v_pk_fma_f32 v[76:77], v[76:77], v[38:39], v[116:117]
	v_pk_fma_f32 v[74:75], v[74:75], v[40:41], v[118:119]
	v_pk_fma_f32 v[78:79], v[78:79], v[40:41], v[120:121]
	v_pk_mul_f32 v[122:123], v[72:73], v[42:43]
	v_pk_mul_f32 v[124:125], v[76:77], v[42:43]
	v_pk_fma_f32 v[122:123], v[74:75], v[44:45], v[122:123]
	v_pk_fma_f32 v[124:125], v[78:79], v[44:45], v[124:125]
	v_add_f32_e32 v126, v122, v123
	v_add_f32_e32 v127, v124, v125
	ds_write_b64 v187, v[126:127] offset:61440
	s_waitcnt lgkmcnt(1)
	v_pk_mul_f32 v[106:107], v[72:73], v[84:85]
	v_pk_mul_f32 v[108:109], v[76:77], v[84:85]
	v_pk_fma_f32 v[106:107], v[74:75], v[86:87], v[106:107]
	v_pk_fma_f32 v[108:109], v[78:79], v[86:87], v[108:109]
	v_add_f32_e32 v110, v106, v107
	v_add_f32_e32 v112, v108, v109
	s_nop 0
	v_add_f32_dpp v110, v110, v110 quad_perm:[1,0,3,2] row_mask:0xf bank_mask:0xf bound_ctrl:1
	v_add_f32_dpp v112, v112, v112 quad_perm:[1,0,3,2] row_mask:0xf bank_mask:0xf bound_ctrl:1
	s_nop 0
	v_add_f32_dpp v110, v110, v110 quad_perm:[2,3,0,1] row_mask:0xf bank_mask:0xf bound_ctrl:1
	v_add_f32_dpp v112, v112, v112 quad_perm:[2,3,0,1] row_mask:0xf bank_mask:0xf bound_ctrl:1
	s_nop 0
	v_add_f32_dpp v110, v110, v110 row_half_mirror row_mask:0xf bank_mask:0xf bound_ctrl:1
	v_add_f32_dpp v112, v112, v112 row_half_mirror row_mask:0xf bank_mask:0xf bound_ctrl:1
	s_nop 0
	v_add_f32_dpp v110, v110, v110 row_ror:8 row_mask:0xf bank_mask:0xf bound_ctrl:1
	v_add_f32_dpp v112, v112, v112 row_ror:8 row_mask:0xf bank_mask:0xf bound_ctrl:1
	v_pk_mul_f32 v[114:115], v[88:89], v[110:111] op_sel_hi:[1,0]
	v_pk_mul_f32 v[116:117], v[88:89], v[112:113] op_sel_hi:[1,0]
	v_pk_mul_f32 v[118:119], v[90:91], v[110:111] op_sel_hi:[1,0]
	v_pk_mul_f32 v[120:121], v[90:91], v[112:113] op_sel_hi:[1,0]
	v_pk_fma_f32 v[114:115], v[100:101], v[104:105], v[114:115] op_sel_hi:[1,0,1]
	v_pk_fma_f32 v[116:117], v[100:101], v[104:105], v[116:117] op_sel:[0,1,0]
	v_pk_fma_f32 v[118:119], v[102:103], v[104:105], v[118:119] op_sel_hi:[1,0,1]
	v_pk_fma_f32 v[120:121], v[102:103], v[104:105], v[120:121] op_sel:[0,1,0]
	v_pk_fma_f32 v[72:73], v[72:73], v[92:93], v[114:115]
	v_pk_fma_f32 v[76:77], v[76:77], v[92:93], v[116:117]
	v_pk_fma_f32 v[74:75], v[74:75], v[94:95], v[118:119]
	v_pk_fma_f32 v[78:79], v[78:79], v[94:95], v[120:121]
	v_pk_mul_f32 v[122:123], v[72:73], v[96:97]
	v_pk_mul_f32 v[124:125], v[76:77], v[96:97]
	v_pk_fma_f32 v[122:123], v[74:75], v[98:99], v[122:123]
	v_pk_fma_f32 v[124:125], v[78:79], v[98:99], v[124:125]
	v_add_f32_e32 v126, v122, v123
	v_add_f32_e32 v127, v124, v125
	ds_write_b64 v187, v[126:127] offset:63488

.LBB0_3086:
	s_and_saveexec_b64 s[30:31], s[22:23]
	s_cbranch_execz .LBB0_3089
	ds_read_b128 v[30:33], v161 offset:8192
	ds_read_b128 v[34:37], v161 offset:16384
	ds_read_b128 v[46:49], v161 offset:24576
	ds_read_b64 v[80:81], v82 offset:40960
	ds_read_b128 v[38:41], v161
	ds_read_b128 v[42:45], v161 offset:32768
	ds_read_b128 v[84:87], v161 offset:8448
	ds_read_b128 v[88:91], v161 offset:16640
	ds_read_b128 v[100:103], v161 offset:24832
	ds_read_b64 v[104:105], v82 offset:41216
	ds_read_b128 v[92:95], v161 offset:256
	ds_read_b128 v[96:99], v161 offset:33024
	s_waitcnt lgkmcnt(6)
	v_pk_mul_f32 v[106:107], v[72:73], v[30:31]
	v_pk_mul_f32 v[108:109], v[76:77], v[30:31]
	v_pk_fma_f32 v[106:107], v[74:75], v[32:33], v[106:107]
	v_pk_fma_f32 v[108:109], v[78:79], v[32:33], v[108:109]
	v_add_f32_e32 v110, v106, v107
	v_add_f32_e32 v112, v108, v109
	s_nop 0
	v_add_f32_dpp v110, v110, v110 quad_perm:[1,0,3,2] row_mask:0xf bank_mask:0xf bound_ctrl:1
	v_add_f32_dpp v112, v112, v112 quad_perm:[1,0,3,2] row_mask:0xf bank_mask:0xf bound_ctrl:1
	s_nop 0
	v_add_f32_dpp v110, v110, v110 quad_perm:[2,3,0,1] row_mask:0xf bank_mask:0xf bound_ctrl:1
	v_add_f32_dpp v112, v112, v112 quad_perm:[2,3,0,1] row_mask:0xf bank_mask:0xf bound_ctrl:1
	s_nop 0
	v_add_f32_dpp v110, v110, v110 row_half_mirror row_mask:0xf bank_mask:0xf bound_ctrl:1
	v_add_f32_dpp v112, v112, v112 row_half_mirror row_mask:0xf bank_mask:0xf bound_ctrl:1
	s_nop 0
	v_add_f32_dpp v110, v110, v110 row_ror:8 row_mask:0xf bank_mask:0xf bound_ctrl:1
	v_add_f32_dpp v112, v112, v112 row_ror:8 row_mask:0xf bank_mask:0xf bound_ctrl:1
	v_pk_mul_f32 v[114:115], v[34:35], v[110:111] op_sel_hi:[1,0]
	v_pk_mul_f32 v[116:117], v[34:35], v[112:113] op_sel_hi:[1,0]
	v_pk_mul_f32 v[118:119], v[36:37], v[110:111] op_sel_hi:[1,0]
	v_pk_mul_f32 v[120:121], v[36:37], v[112:113] op_sel_hi:[1,0]
	v_pk_fma_f32 v[114:115], v[46:47], v[80:81], v[114:115] op_sel_hi:[1,0,1]
	v_pk_fma_f32 v[116:117], v[46:47], v[80:81], v[116:117] op_sel:[0,1,0]
	v_pk_fma_f32 v[118:119], v[48:49], v[80:81], v[118:119] op_sel_hi:[1,0,1]
	v_pk_fma_f32 v[120:121], v[48:49], v[80:81], v[120:121] op_sel:[0,1,0]
	v_pk_fma_f32 v[72:73], v[72:73], v[38:39], v[114:115]
	v_pk_fma_f32 v[76:77], v[76:77], v[38:39], v[116:117]
	v_pk_fma_f32 v[74:75], v[74:75], v[40:41], v[118:119]
	v_pk_fma_f32 v[78:79], v[78:79], v[40:41], v[120:121]
	v_pk_mul_f32 v[122:123], v[72:73], v[42:43]
	v_pk_mul_f32 v[124:125], v[76:77], v[42:43]
	v_pk_fma_f32 v[122:123], v[74:75], v[44:45], v[122:123]
	v_pk_fma_f32 v[124:125], v[78:79], v[44:45], v[124:125]
	v_add_f32_e32 v126, v122, v123
	v_add_f32_e32 v127, v124, v125
	ds_write_b64 v187, v[126:127]
	ds_read_b128 v[30:33], v161 offset:8704
	ds_read_b128 v[34:37], v161 offset:16896
	ds_read_b128 v[46:49], v161 offset:25088
	ds_read_b64 v[80:81], v82 offset:41472
	ds_read_b128 v[38:41], v161 offset:512
	ds_read_b128 v[42:45], v161 offset:33280
	s_waitcnt lgkmcnt(7)
	v_pk_mul_f32 v[106:107], v[72:73], v[84:85]
	v_pk_mul_f32 v[108:109], v[76:77], v[84:85]
	v_pk_fma_f32 v[106:107], v[74:75], v[86:87], v[106:107]
	v_pk_fma_f32 v[108:109], v[78:79], v[86:87], v[108:109]
	v_add_f32_e32 v110, v106, v107
	v_add_f32_e32 v112, v108, v109
	s_nop 0
	v_add_f32_dpp v110, v110, v110 quad_perm:[1,0,3,2] row_mask:0xf bank_mask:0xf bound_ctrl:1
	v_add_f32_dpp v112, v112, v112 quad_perm:[1,0,3,2] row_mask:0xf bank_mask:0xf bound_ctrl:1
	s_nop 0
	v_add_f32_dpp v110, v110, v110 quad_perm:[2,3,0,1] row_mask:0xf bank_mask:0xf bound_ctrl:1
	v_add_f32_dpp v112, v112, v112 quad_perm:[2,3,0,1] row_mask:0xf bank_mask:0xf bound_ctrl:1
	s_nop 0
	v_add_f32_dpp v110, v110, v110 row_half_mirror row_mask:0xf bank_mask:0xf bound_ctrl:1
	v_add_f32_dpp v112, v112, v112 row_half_mirror row_mask:0xf bank_mask:0xf bound_ctrl:1
	s_nop 0
	v_add_f32_dpp v110, v110, v110 row_ror:8 row_mask:0xf bank_mask:0xf bound_ctrl:1
	v_add_f32_dpp v112, v112, v112 row_ror:8 row_mask:0xf bank_mask:0xf bound_ctrl:1
	v_pk_mul_f32 v[114:115], v[88:89], v[110:111] op_sel_hi:[1,0]
	v_pk_mul_f32 v[116:117], v[88:89], v[112:113] op_sel_hi:[1,0]
	v_pk_mul_f32 v[118:119], v[90:91], v[110:111] op_sel_hi:[1,0]
	v_pk_mul_f32 v[120:121], v[90:91], v[112:113] op_sel_hi:[1,0]
	v_pk_fma_f32 v[114:115], v[100:101], v[104:105], v[114:115] op_sel_hi:[1,0,1]
	v_pk_fma_f32 v[116:117], v[100:101], v[104:105], v[116:117] op_sel:[0,1,0]
	v_pk_fma_f32 v[118:119], v[102:103], v[104:105], v[118:119] op_sel_hi:[1,0,1]
	v_pk_fma_f32 v[120:121], v[102:103], v[104:105], v[120:121] op_sel:[0,1,0]
	v_pk_fma_f32 v[72:73], v[72:73], v[92:93], v[114:115]
	v_pk_fma_f32 v[76:77], v[76:77], v[92:93], v[116:117]
	v_pk_fma_f32 v[74:75], v[74:75], v[94:95], v[118:119]
	v_pk_fma_f32 v[78:79], v[78:79], v[94:95], v[120:121]
	v_pk_mul_f32 v[122:123], v[72:73], v[96:97]
	v_pk_mul_f32 v[124:125], v[76:77], v[96:97]
	v_pk_fma_f32 v[122:123], v[74:75], v[98:99], v[122:123]
	v_pk_fma_f32 v[124:125], v[78:79], v[98:99], v[124:125]
	v_add_f32_e32 v126, v122, v123
	v_add_f32_e32 v127, v124, v125
	ds_write_b64 v187, v[126:127] offset:2048
	ds_read_b128 v[84:87], v161 offset:8960
	ds_read_b128 v[88:91], v161 offset:17152
	ds_read_b128 v[100:103], v161 offset:25344
	ds_read_b64 v[104:105], v82 offset:41728
	ds_read_b128 v[92:95], v161 offset:768
	ds_read_b128 v[96:99], v161 offset:33536
	s_waitcnt lgkmcnt(7)
	v_pk_mul_f32 v[106:107], v[72:73], v[30:31]
	v_pk_mul_f32 v[108:109], v[76:77], v[30:31]
	v_pk_fma_f32 v[106:107], v[74:75], v[32:33], v[106:107]
	v_pk_fma_f32 v[108:109], v[78:79], v[32:33], v[108:109]
	v_add_f32_e32 v110, v106, v107
	v_add_f32_e32 v112, v108, v109
	s_nop 0
	v_add_f32_dpp v110, v110, v110 quad_perm:[1,0,3,2] row_mask:0xf bank_mask:0xf bound_ctrl:1
	v_add_f32_dpp v112, v112, v112 quad_perm:[1,0,3,2] row_mask:0xf bank_mask:0xf bound_ctrl:1
	s_nop 0
	v_add_f32_dpp v110, v110, v110 quad_perm:[2,3,0,1] row_mask:0xf bank_mask:0xf bound_ctrl:1
	v_add_f32_dpp v112, v112, v112 quad_perm:[2,3,0,1] row_mask:0xf bank_mask:0xf bound_ctrl:1
	s_nop 0
	v_add_f32_dpp v110, v110, v110 row_half_mirror row_mask:0xf bank_mask:0xf bound_ctrl:1
	v_add_f32_dpp v112, v112, v112 row_half_mirror row_mask:0xf bank_mask:0xf bound_ctrl:1
	s_nop 0
	v_add_f32_dpp v110, v110, v110 row_ror:8 row_mask:0xf bank_mask:0xf bound_ctrl:1
	v_add_f32_dpp v112, v112, v112 row_ror:8 row_mask:0xf bank_mask:0xf bound_ctrl:1
	v_pk_mul_f32 v[114:115], v[34:35], v[110:111] op_sel_hi:[1,0]
	v_pk_mul_f32 v[116:117], v[34:35], v[112:113] op_sel_hi:[1,0]
	v_pk_mul_f32 v[118:119], v[36:37], v[110:111] op_sel_hi:[1,0]
	v_pk_mul_f32 v[120:121], v[36:37], v[112:113] op_sel_hi:[1,0]
	v_pk_fma_f32 v[114:115], v[46:47], v[80:81], v[114:115] op_sel_hi:[1,0,1]
	v_pk_fma_f32 v[116:117], v[46:47], v[80:81], v[116:117] op_sel:[0,1,0]
	v_pk_fma_f32 v[118:119], v[48:49], v[80:81], v[118:119] op_sel_hi:[1,0,1]
	v_pk_fma_f32 v[120:121], v[48:49], v[80:81], v[120:121] op_sel:[0,1,0]
	v_pk_fma_f32 v[72:73], v[72:73], v[38:39], v[114:115]
	v_pk_fma_f32 v[76:77], v[76:77], v[38:39], v[116:117]
	v_pk_fma_f32 v[74:75], v[74:75], v[40:41], v[118:119]
	v_pk_fma_f32 v[78:79], v[78:79], v[40:41], v[120:121]
	v_pk_mul_f32 v[122:123], v[72:73], v[42:43]
	v_pk_mul_f32 v[124:125], v[76:77], v[42:43]
	v_pk_fma_f32 v[122:123], v[74:75], v[44:45], v[122:123]
	v_pk_fma_f32 v[124:125], v[78:79], v[44:45], v[124:125]
	v_add_f32_e32 v126, v122, v123
	v_add_f32_e32 v127, v124, v125
	ds_write_b64 v187, v[126:127] offset:4096
	ds_read_b128 v[30:33], v161 offset:9216
	ds_read_b128 v[34:37], v161 offset:17408
	ds_read_b128 v[46:49], v161 offset:25600
	ds_read_b64 v[80:81], v82 offset:41984
	ds_read_b128 v[38:41], v161 offset:1024
	ds_read_b128 v[42:45], v161 offset:33792
	s_waitcnt lgkmcnt(7)
	v_pk_mul_f32 v[106:107], v[72:73], v[84:85]
	v_pk_mul_f32 v[108:109], v[76:77], v[84:85]
	v_pk_fma_f32 v[106:107], v[74:75], v[86:87], v[106:107]
	v_pk_fma_f32 v[108:109], v[78:79], v[86:87], v[108:109]
	v_add_f32_e32 v110, v106, v107
	v_add_f32_e32 v112, v108, v109
	s_nop 0
	v_add_f32_dpp v110, v110, v110 quad_perm:[1,0,3,2] row_mask:0xf bank_mask:0xf bound_ctrl:1
	v_add_f32_dpp v112, v112, v112 quad_perm:[1,0,3,2] row_mask:0xf bank_mask:0xf bound_ctrl:1
	s_nop 0
	v_add_f32_dpp v110, v110, v110 quad_perm:[2,3,0,1] row_mask:0xf bank_mask:0xf bound_ctrl:1
	v_add_f32_dpp v112, v112, v112 quad_perm:[2,3,0,1] row_mask:0xf bank_mask:0xf bound_ctrl:1
	s_nop 0
	v_add_f32_dpp v110, v110, v110 row_half_mirror row_mask:0xf bank_mask:0xf bound_ctrl:1
	v_add_f32_dpp v112, v112, v112 row_half_mirror row_mask:0xf bank_mask:0xf bound_ctrl:1
	s_nop 0
	v_add_f32_dpp v110, v110, v110 row_ror:8 row_mask:0xf bank_mask:0xf bound_ctrl:1
	v_add_f32_dpp v112, v112, v112 row_ror:8 row_mask:0xf bank_mask:0xf bound_ctrl:1
	v_pk_mul_f32 v[114:115], v[88:89], v[110:111] op_sel_hi:[1,0]
	v_pk_mul_f32 v[116:117], v[88:89], v[112:113] op_sel_hi:[1,0]
	v_pk_mul_f32 v[118:119], v[90:91], v[110:111] op_sel_hi:[1,0]
	v_pk_mul_f32 v[120:121], v[90:91], v[112:113] op_sel_hi:[1,0]
	v_pk_fma_f32 v[114:115], v[100:101], v[104:105], v[114:115] op_sel_hi:[1,0,1]
	v_pk_fma_f32 v[116:117], v[100:101], v[104:105], v[116:117] op_sel:[0,1,0]
	v_pk_fma_f32 v[118:119], v[102:103], v[104:105], v[118:119] op_sel_hi:[1,0,1]
	v_pk_fma_f32 v[120:121], v[102:103], v[104:105], v[120:121] op_sel:[0,1,0]
	v_pk_fma_f32 v[72:73], v[72:73], v[92:93], v[114:115]
	v_pk_fma_f32 v[76:77], v[76:77], v[92:93], v[116:117]
	v_pk_fma_f32 v[74:75], v[74:75], v[94:95], v[118:119]
	v_pk_fma_f32 v[78:79], v[78:79], v[94:95], v[120:121]
	v_pk_mul_f32 v[122:123], v[72:73], v[96:97]
	v_pk_mul_f32 v[124:125], v[76:77], v[96:97]
	v_pk_fma_f32 v[122:123], v[74:75], v[98:99], v[122:123]
	v_pk_fma_f32 v[124:125], v[78:79], v[98:99], v[124:125]
	v_add_f32_e32 v126, v122, v123
	v_add_f32_e32 v127, v124, v125
	ds_write_b64 v187, v[126:127] offset:6144
	ds_read_b128 v[84:87], v161 offset:9472
	ds_read_b128 v[88:91], v161 offset:17664
	ds_read_b128 v[100:103], v161 offset:25856
	ds_read_b64 v[104:105], v82 offset:42240
	ds_read_b128 v[92:95], v161 offset:1280
	ds_read_b128 v[96:99], v161 offset:34048
	s_waitcnt lgkmcnt(7)
	v_pk_mul_f32 v[106:107], v[72:73], v[30:31]
	v_pk_mul_f32 v[108:109], v[76:77], v[30:31]
	v_pk_fma_f32 v[106:107], v[74:75], v[32:33], v[106:107]
	v_pk_fma_f32 v[108:109], v[78:79], v[32:33], v[108:109]
	v_add_f32_e32 v110, v106, v107
	v_add_f32_e32 v112, v108, v109
	s_nop 0
	v_add_f32_dpp v110, v110, v110 quad_perm:[1,0,3,2] row_mask:0xf bank_mask:0xf bound_ctrl:1
	v_add_f32_dpp v112, v112, v112 quad_perm:[1,0,3,2] row_mask:0xf bank_mask:0xf bound_ctrl:1
	s_nop 0
	v_add_f32_dpp v110, v110, v110 quad_perm:[2,3,0,1] row_mask:0xf bank_mask:0xf bound_ctrl:1
	v_add_f32_dpp v112, v112, v112 quad_perm:[2,3,0,1] row_mask:0xf bank_mask:0xf bound_ctrl:1
	s_nop 0
	v_add_f32_dpp v110, v110, v110 row_half_mirror row_mask:0xf bank_mask:0xf bound_ctrl:1
	v_add_f32_dpp v112, v112, v112 row_half_mirror row_mask:0xf bank_mask:0xf bound_ctrl:1
	s_nop 0
	v_add_f32_dpp v110, v110, v110 row_ror:8 row_mask:0xf bank_mask:0xf bound_ctrl:1
	v_add_f32_dpp v112, v112, v112 row_ror:8 row_mask:0xf bank_mask:0xf bound_ctrl:1
	v_pk_mul_f32 v[114:115], v[34:35], v[110:111] op_sel_hi:[1,0]
	v_pk_mul_f32 v[116:117], v[34:35], v[112:113] op_sel_hi:[1,0]
	v_pk_mul_f32 v[118:119], v[36:37], v[110:111] op_sel_hi:[1,0]
	v_pk_mul_f32 v[120:121], v[36:37], v[112:113] op_sel_hi:[1,0]
	v_pk_fma_f32 v[114:115], v[46:47], v[80:81], v[114:115] op_sel_hi:[1,0,1]
	v_pk_fma_f32 v[116:117], v[46:47], v[80:81], v[116:117] op_sel:[0,1,0]
	v_pk_fma_f32 v[118:119], v[48:49], v[80:81], v[118:119] op_sel_hi:[1,0,1]
	v_pk_fma_f32 v[120:121], v[48:49], v[80:81], v[120:121] op_sel:[0,1,0]
	v_pk_fma_f32 v[72:73], v[72:73], v[38:39], v[114:115]
	v_pk_fma_f32 v[76:77], v[76:77], v[38:39], v[116:117]
	v_pk_fma_f32 v[74:75], v[74:75], v[40:41], v[118:119]
	v_pk_fma_f32 v[78:79], v[78:79], v[40:41], v[120:121]
	v_pk_mul_f32 v[122:123], v[72:73], v[42:43]
	v_pk_mul_f32 v[124:125], v[76:77], v[42:43]
	v_pk_fma_f32 v[122:123], v[74:75], v[44:45], v[122:123]
	v_pk_fma_f32 v[124:125], v[78:79], v[44:45], v[124:125]
	v_add_f32_e32 v126, v122, v123
	v_add_f32_e32 v127, v124, v125
	ds_write_b64 v187, v[126:127] offset:8192
	ds_read_b128 v[30:33], v161 offset:9728
	ds_read_b128 v[34:37], v161 offset:17920
	ds_read_b128 v[46:49], v161 offset:26112
	ds_read_b64 v[80:81], v82 offset:42496
	ds_read_b128 v[38:41], v161 offset:1536
	ds_read_b128 v[42:45], v161 offset:34304
	s_waitcnt lgkmcnt(7)
	v_pk_mul_f32 v[106:107], v[72:73], v[84:85]
	v_pk_mul_f32 v[108:109], v[76:77], v[84:85]
	v_pk_fma_f32 v[106:107], v[74:75], v[86:87], v[106:107]
	v_pk_fma_f32 v[108:109], v[78:79], v[86:87], v[108:109]
	v_add_f32_e32 v110, v106, v107
	v_add_f32_e32 v112, v108, v109
	s_nop 0
	v_add_f32_dpp v110, v110, v110 quad_perm:[1,0,3,2] row_mask:0xf bank_mask:0xf bound_ctrl:1
	v_add_f32_dpp v112, v112, v112 quad_perm:[1,0,3,2] row_mask:0xf bank_mask:0xf bound_ctrl:1
	s_nop 0
	v_add_f32_dpp v110, v110, v110 quad_perm:[2,3,0,1] row_mask:0xf bank_mask:0xf bound_ctrl:1
	v_add_f32_dpp v112, v112, v112 quad_perm:[2,3,0,1] row_mask:0xf bank_mask:0xf bound_ctrl:1
	s_nop 0
	v_add_f32_dpp v110, v110, v110 row_half_mirror row_mask:0xf bank_mask:0xf bound_ctrl:1
	v_add_f32_dpp v112, v112, v112 row_half_mirror row_mask:0xf bank_mask:0xf bound_ctrl:1
	s_nop 0
	v_add_f32_dpp v110, v110, v110 row_ror:8 row_mask:0xf bank_mask:0xf bound_ctrl:1
	v_add_f32_dpp v112, v112, v112 row_ror:8 row_mask:0xf bank_mask:0xf bound_ctrl:1
	v_pk_mul_f32 v[114:115], v[88:89], v[110:111] op_sel_hi:[1,0]
	v_pk_mul_f32 v[116:117], v[88:89], v[112:113] op_sel_hi:[1,0]
	v_pk_mul_f32 v[118:119], v[90:91], v[110:111] op_sel_hi:[1,0]
	v_pk_mul_f32 v[120:121], v[90:91], v[112:113] op_sel_hi:[1,0]
	v_pk_fma_f32 v[114:115], v[100:101], v[104:105], v[114:115] op_sel_hi:[1,0,1]
	v_pk_fma_f32 v[116:117], v[100:101], v[104:105], v[116:117] op_sel:[0,1,0]
	v_pk_fma_f32 v[118:119], v[102:103], v[104:105], v[118:119] op_sel_hi:[1,0,1]
	v_pk_fma_f32 v[120:121], v[102:103], v[104:105], v[120:121] op_sel:[0,1,0]
	v_pk_fma_f32 v[72:73], v[72:73], v[92:93], v[114:115]
	v_pk_fma_f32 v[76:77], v[76:77], v[92:93], v[116:117]
	v_pk_fma_f32 v[74:75], v[74:75], v[94:95], v[118:119]
	v_pk_fma_f32 v[78:79], v[78:79], v[94:95], v[120:121]
	v_pk_mul_f32 v[122:123], v[72:73], v[96:97]
	v_pk_mul_f32 v[124:125], v[76:77], v[96:97]
	v_pk_fma_f32 v[122:123], v[74:75], v[98:99], v[122:123]
	v_pk_fma_f32 v[124:125], v[78:79], v[98:99], v[124:125]
	v_add_f32_e32 v126, v122, v123
	v_add_f32_e32 v127, v124, v125
	ds_write_b64 v187, v[126:127] offset:10240
	ds_read_b128 v[84:87], v161 offset:9984
	ds_read_b128 v[88:91], v161 offset:18176
	ds_read_b128 v[100:103], v161 offset:26368
	ds_read_b64 v[104:105], v82 offset:42752
	ds_read_b128 v[92:95], v161 offset:1792
	ds_read_b128 v[96:99], v161 offset:34560
	s_waitcnt lgkmcnt(7)
	v_pk_mul_f32 v[106:107], v[72:73], v[30:31]
	v_pk_mul_f32 v[108:109], v[76:77], v[30:31]
	v_pk_fma_f32 v[106:107], v[74:75], v[32:33], v[106:107]
	v_pk_fma_f32 v[108:109], v[78:79], v[32:33], v[108:109]
	v_add_f32_e32 v110, v106, v107
	v_add_f32_e32 v112, v108, v109
	s_nop 0
	v_add_f32_dpp v110, v110, v110 quad_perm:[1,0,3,2] row_mask:0xf bank_mask:0xf bound_ctrl:1
	v_add_f32_dpp v112, v112, v112 quad_perm:[1,0,3,2] row_mask:0xf bank_mask:0xf bound_ctrl:1
	s_nop 0
	v_add_f32_dpp v110, v110, v110 quad_perm:[2,3,0,1] row_mask:0xf bank_mask:0xf bound_ctrl:1
	v_add_f32_dpp v112, v112, v112 quad_perm:[2,3,0,1] row_mask:0xf bank_mask:0xf bound_ctrl:1
	s_nop 0
	v_add_f32_dpp v110, v110, v110 row_half_mirror row_mask:0xf bank_mask:0xf bound_ctrl:1
	v_add_f32_dpp v112, v112, v112 row_half_mirror row_mask:0xf bank_mask:0xf bound_ctrl:1
	s_nop 0
	v_add_f32_dpp v110, v110, v110 row_ror:8 row_mask:0xf bank_mask:0xf bound_ctrl:1
	v_add_f32_dpp v112, v112, v112 row_ror:8 row_mask:0xf bank_mask:0xf bound_ctrl:1
	v_pk_mul_f32 v[114:115], v[34:35], v[110:111] op_sel_hi:[1,0]
	v_pk_mul_f32 v[116:117], v[34:35], v[112:113] op_sel_hi:[1,0]
	v_pk_mul_f32 v[118:119], v[36:37], v[110:111] op_sel_hi:[1,0]
	v_pk_mul_f32 v[120:121], v[36:37], v[112:113] op_sel_hi:[1,0]
	v_pk_fma_f32 v[114:115], v[46:47], v[80:81], v[114:115] op_sel_hi:[1,0,1]
	v_pk_fma_f32 v[116:117], v[46:47], v[80:81], v[116:117] op_sel:[0,1,0]
	v_pk_fma_f32 v[118:119], v[48:49], v[80:81], v[118:119] op_sel_hi:[1,0,1]
	v_pk_fma_f32 v[120:121], v[48:49], v[80:81], v[120:121] op_sel:[0,1,0]
	v_pk_fma_f32 v[72:73], v[72:73], v[38:39], v[114:115]
	v_pk_fma_f32 v[76:77], v[76:77], v[38:39], v[116:117]
	v_pk_fma_f32 v[74:75], v[74:75], v[40:41], v[118:119]
	v_pk_fma_f32 v[78:79], v[78:79], v[40:41], v[120:121]
	v_pk_mul_f32 v[122:123], v[72:73], v[42:43]
	v_pk_mul_f32 v[124:125], v[76:77], v[42:43]
	v_pk_fma_f32 v[122:123], v[74:75], v[44:45], v[122:123]
	v_pk_fma_f32 v[124:125], v[78:79], v[44:45], v[124:125]
	v_add_f32_e32 v126, v122, v123
	v_add_f32_e32 v127, v124, v125
	ds_write_b64 v187, v[126:127] offset:12288
	ds_read_b128 v[30:33], v161 offset:10240
	ds_read_b128 v[34:37], v161 offset:18432
	ds_read_b128 v[46:49], v161 offset:26624
	ds_read_b64 v[80:81], v82 offset:43008
	ds_read_b128 v[38:41], v161 offset:2048
	ds_read_b128 v[42:45], v161 offset:34816
	s_waitcnt lgkmcnt(7)
	v_pk_mul_f32 v[106:107], v[72:73], v[84:85]
	v_pk_mul_f32 v[108:109], v[76:77], v[84:85]
	v_pk_fma_f32 v[106:107], v[74:75], v[86:87], v[106:107]
	v_pk_fma_f32 v[108:109], v[78:79], v[86:87], v[108:109]
	v_add_f32_e32 v110, v106, v107
	v_add_f32_e32 v112, v108, v109
	s_nop 0
	v_add_f32_dpp v110, v110, v110 quad_perm:[1,0,3,2] row_mask:0xf bank_mask:0xf bound_ctrl:1
	v_add_f32_dpp v112, v112, v112 quad_perm:[1,0,3,2] row_mask:0xf bank_mask:0xf bound_ctrl:1
	s_nop 0
	v_add_f32_dpp v110, v110, v110 quad_perm:[2,3,0,1] row_mask:0xf bank_mask:0xf bound_ctrl:1
	v_add_f32_dpp v112, v112, v112 quad_perm:[2,3,0,1] row_mask:0xf bank_mask:0xf bound_ctrl:1
	s_nop 0
	v_add_f32_dpp v110, v110, v110 row_half_mirror row_mask:0xf bank_mask:0xf bound_ctrl:1
	v_add_f32_dpp v112, v112, v112 row_half_mirror row_mask:0xf bank_mask:0xf bound_ctrl:1
	s_nop 0
	v_add_f32_dpp v110, v110, v110 row_ror:8 row_mask:0xf bank_mask:0xf bound_ctrl:1
	v_add_f32_dpp v112, v112, v112 row_ror:8 row_mask:0xf bank_mask:0xf bound_ctrl:1
	v_pk_mul_f32 v[114:115], v[88:89], v[110:111] op_sel_hi:[1,0]
	v_pk_mul_f32 v[116:117], v[88:89], v[112:113] op_sel_hi:[1,0]
	v_pk_mul_f32 v[118:119], v[90:91], v[110:111] op_sel_hi:[1,0]
	v_pk_mul_f32 v[120:121], v[90:91], v[112:113] op_sel_hi:[1,0]
	v_pk_fma_f32 v[114:115], v[100:101], v[104:105], v[114:115] op_sel_hi:[1,0,1]
	v_pk_fma_f32 v[116:117], v[100:101], v[104:105], v[116:117] op_sel:[0,1,0]
	v_pk_fma_f32 v[118:119], v[102:103], v[104:105], v[118:119] op_sel_hi:[1,0,1]
	v_pk_fma_f32 v[120:121], v[102:103], v[104:105], v[120:121] op_sel:[0,1,0]
	v_pk_fma_f32 v[72:73], v[72:73], v[92:93], v[114:115]
	v_pk_fma_f32 v[76:77], v[76:77], v[92:93], v[116:117]
	v_pk_fma_f32 v[74:75], v[74:75], v[94:95], v[118:119]
	v_pk_fma_f32 v[78:79], v[78:79], v[94:95], v[120:121]
	v_pk_mul_f32 v[122:123], v[72:73], v[96:97]
	v_pk_mul_f32 v[124:125], v[76:77], v[96:97]
	v_pk_fma_f32 v[122:123], v[74:75], v[98:99], v[122:123]
	v_pk_fma_f32 v[124:125], v[78:79], v[98:99], v[124:125]
	v_add_f32_e32 v126, v122, v123
	v_add_f32_e32 v127, v124, v125
	ds_write_b64 v187, v[126:127] offset:14336
	ds_read_b128 v[84:87], v161 offset:10496
	ds_read_b128 v[88:91], v161 offset:18688
	ds_read_b128 v[100:103], v161 offset:26880
	ds_read_b64 v[104:105], v82 offset:43264
	ds_read_b128 v[92:95], v161 offset:2304
	ds_read_b128 v[96:99], v161 offset:35072
	s_waitcnt lgkmcnt(7)
	v_pk_mul_f32 v[106:107], v[72:73], v[30:31]
	v_pk_mul_f32 v[108:109], v[76:77], v[30:31]
	v_pk_fma_f32 v[106:107], v[74:75], v[32:33], v[106:107]
	v_pk_fma_f32 v[108:109], v[78:79], v[32:33], v[108:109]
	v_add_f32_e32 v110, v106, v107
	v_add_f32_e32 v112, v108, v109
	s_nop 0
	v_add_f32_dpp v110, v110, v110 quad_perm:[1,0,3,2] row_mask:0xf bank_mask:0xf bound_ctrl:1
	v_add_f32_dpp v112, v112, v112 quad_perm:[1,0,3,2] row_mask:0xf bank_mask:0xf bound_ctrl:1
	s_nop 0
	v_add_f32_dpp v110, v110, v110 quad_perm:[2,3,0,1] row_mask:0xf bank_mask:0xf bound_ctrl:1
	v_add_f32_dpp v112, v112, v112 quad_perm:[2,3,0,1] row_mask:0xf bank_mask:0xf bound_ctrl:1
	s_nop 0
	v_add_f32_dpp v110, v110, v110 row_half_mirror row_mask:0xf bank_mask:0xf bound_ctrl:1
	v_add_f32_dpp v112, v112, v112 row_half_mirror row_mask:0xf bank_mask:0xf bound_ctrl:1
	s_nop 0
	v_add_f32_dpp v110, v110, v110 row_ror:8 row_mask:0xf bank_mask:0xf bound_ctrl:1
	v_add_f32_dpp v112, v112, v112 row_ror:8 row_mask:0xf bank_mask:0xf bound_ctrl:1
	v_pk_mul_f32 v[114:115], v[34:35], v[110:111] op_sel_hi:[1,0]
	v_pk_mul_f32 v[116:117], v[34:35], v[112:113] op_sel_hi:[1,0]
	v_pk_mul_f32 v[118:119], v[36:37], v[110:111] op_sel_hi:[1,0]
	v_pk_mul_f32 v[120:121], v[36:37], v[112:113] op_sel_hi:[1,0]
	v_pk_fma_f32 v[114:115], v[46:47], v[80:81], v[114:115] op_sel_hi:[1,0,1]
	v_pk_fma_f32 v[116:117], v[46:47], v[80:81], v[116:117] op_sel:[0,1,0]
	v_pk_fma_f32 v[118:119], v[48:49], v[80:81], v[118:119] op_sel_hi:[1,0,1]
	v_pk_fma_f32 v[120:121], v[48:49], v[80:81], v[120:121] op_sel:[0,1,0]
	v_pk_fma_f32 v[72:73], v[72:73], v[38:39], v[114:115]
	v_pk_fma_f32 v[76:77], v[76:77], v[38:39], v[116:117]
	v_pk_fma_f32 v[74:75], v[74:75], v[40:41], v[118:119]
	v_pk_fma_f32 v[78:79], v[78:79], v[40:41], v[120:121]
	v_pk_mul_f32 v[122:123], v[72:73], v[42:43]
	v_pk_mul_f32 v[124:125], v[76:77], v[42:43]
	v_pk_fma_f32 v[122:123], v[74:75], v[44:45], v[122:123]
	v_pk_fma_f32 v[124:125], v[78:79], v[44:45], v[124:125]
	v_add_f32_e32 v126, v122, v123
	v_add_f32_e32 v127, v124, v125
	ds_write_b64 v187, v[126:127] offset:16384
	ds_read_b128 v[30:33], v161 offset:10752
	ds_read_b128 v[34:37], v161 offset:18944
	ds_read_b128 v[46:49], v161 offset:27136
	ds_read_b64 v[80:81], v82 offset:43520
	ds_read_b128 v[38:41], v161 offset:2560
	ds_read_b128 v[42:45], v161 offset:35328
	s_waitcnt lgkmcnt(7)
	v_pk_mul_f32 v[106:107], v[72:73], v[84:85]
	v_pk_mul_f32 v[108:109], v[76:77], v[84:85]
	v_pk_fma_f32 v[106:107], v[74:75], v[86:87], v[106:107]
	v_pk_fma_f32 v[108:109], v[78:79], v[86:87], v[108:109]
	v_add_f32_e32 v110, v106, v107
	v_add_f32_e32 v112, v108, v109
	s_nop 0
	v_add_f32_dpp v110, v110, v110 quad_perm:[1,0,3,2] row_mask:0xf bank_mask:0xf bound_ctrl:1
	v_add_f32_dpp v112, v112, v112 quad_perm:[1,0,3,2] row_mask:0xf bank_mask:0xf bound_ctrl:1
	s_nop 0
	v_add_f32_dpp v110, v110, v110 quad_perm:[2,3,0,1] row_mask:0xf bank_mask:0xf bound_ctrl:1
	v_add_f32_dpp v112, v112, v112 quad_perm:[2,3,0,1] row_mask:0xf bank_mask:0xf bound_ctrl:1
	s_nop 0
	v_add_f32_dpp v110, v110, v110 row_half_mirror row_mask:0xf bank_mask:0xf bound_ctrl:1
	v_add_f32_dpp v112, v112, v112 row_half_mirror row_mask:0xf bank_mask:0xf bound_ctrl:1
	s_nop 0
	v_add_f32_dpp v110, v110, v110 row_ror:8 row_mask:0xf bank_mask:0xf bound_ctrl:1
	v_add_f32_dpp v112, v112, v112 row_ror:8 row_mask:0xf bank_mask:0xf bound_ctrl:1
	v_pk_mul_f32 v[114:115], v[88:89], v[110:111] op_sel_hi:[1,0]
	v_pk_mul_f32 v[116:117], v[88:89], v[112:113] op_sel_hi:[1,0]
	v_pk_mul_f32 v[118:119], v[90:91], v[110:111] op_sel_hi:[1,0]
	v_pk_mul_f32 v[120:121], v[90:91], v[112:113] op_sel_hi:[1,0]
	v_pk_fma_f32 v[114:115], v[100:101], v[104:105], v[114:115] op_sel_hi:[1,0,1]
	v_pk_fma_f32 v[116:117], v[100:101], v[104:105], v[116:117] op_sel:[0,1,0]
	v_pk_fma_f32 v[118:119], v[102:103], v[104:105], v[118:119] op_sel_hi:[1,0,1]
	v_pk_fma_f32 v[120:121], v[102:103], v[104:105], v[120:121] op_sel:[0,1,0]
	v_pk_fma_f32 v[72:73], v[72:73], v[92:93], v[114:115]
	v_pk_fma_f32 v[76:77], v[76:77], v[92:93], v[116:117]
	v_pk_fma_f32 v[74:75], v[74:75], v[94:95], v[118:119]
	v_pk_fma_f32 v[78:79], v[78:79], v[94:95], v[120:121]
	v_pk_mul_f32 v[122:123], v[72:73], v[96:97]
	v_pk_mul_f32 v[124:125], v[76:77], v[96:97]
	v_pk_fma_f32 v[122:123], v[74:75], v[98:99], v[122:123]
	v_pk_fma_f32 v[124:125], v[78:79], v[98:99], v[124:125]
	v_add_f32_e32 v126, v122, v123
	v_add_f32_e32 v127, v124, v125
	ds_write_b64 v187, v[126:127] offset:18432
	ds_read_b128 v[84:87], v161 offset:11008
	ds_read_b128 v[88:91], v161 offset:19200
	ds_read_b128 v[100:103], v161 offset:27392
	ds_read_b64 v[104:105], v82 offset:43776
	ds_read_b128 v[92:95], v161 offset:2816
	ds_read_b128 v[96:99], v161 offset:35584
	s_waitcnt lgkmcnt(7)
	v_pk_mul_f32 v[106:107], v[72:73], v[30:31]
	v_pk_mul_f32 v[108:109], v[76:77], v[30:31]
	v_pk_fma_f32 v[106:107], v[74:75], v[32:33], v[106:107]
	v_pk_fma_f32 v[108:109], v[78:79], v[32:33], v[108:109]
	v_add_f32_e32 v110, v106, v107
	v_add_f32_e32 v112, v108, v109
	s_nop 0
	v_add_f32_dpp v110, v110, v110 quad_perm:[1,0,3,2] row_mask:0xf bank_mask:0xf bound_ctrl:1
	v_add_f32_dpp v112, v112, v112 quad_perm:[1,0,3,2] row_mask:0xf bank_mask:0xf bound_ctrl:1
	s_nop 0
	v_add_f32_dpp v110, v110, v110 quad_perm:[2,3,0,1] row_mask:0xf bank_mask:0xf bound_ctrl:1
	v_add_f32_dpp v112, v112, v112 quad_perm:[2,3,0,1] row_mask:0xf bank_mask:0xf bound_ctrl:1
	s_nop 0
	v_add_f32_dpp v110, v110, v110 row_half_mirror row_mask:0xf bank_mask:0xf bound_ctrl:1
	v_add_f32_dpp v112, v112, v112 row_half_mirror row_mask:0xf bank_mask:0xf bound_ctrl:1
	s_nop 0
	v_add_f32_dpp v110, v110, v110 row_ror:8 row_mask:0xf bank_mask:0xf bound_ctrl:1
	v_add_f32_dpp v112, v112, v112 row_ror:8 row_mask:0xf bank_mask:0xf bound_ctrl:1
	v_pk_mul_f32 v[114:115], v[34:35], v[110:111] op_sel_hi:[1,0]
	v_pk_mul_f32 v[116:117], v[34:35], v[112:113] op_sel_hi:[1,0]
	v_pk_mul_f32 v[118:119], v[36:37], v[110:111] op_sel_hi:[1,0]
	v_pk_mul_f32 v[120:121], v[36:37], v[112:113] op_sel_hi:[1,0]
	v_pk_fma_f32 v[114:115], v[46:47], v[80:81], v[114:115] op_sel_hi:[1,0,1]
	v_pk_fma_f32 v[116:117], v[46:47], v[80:81], v[116:117] op_sel:[0,1,0]
	v_pk_fma_f32 v[118:119], v[48:49], v[80:81], v[118:119] op_sel_hi:[1,0,1]
	v_pk_fma_f32 v[120:121], v[48:49], v[80:81], v[120:121] op_sel:[0,1,0]
	v_pk_fma_f32 v[72:73], v[72:73], v[38:39], v[114:115]
	v_pk_fma_f32 v[76:77], v[76:77], v[38:39], v[116:117]
	v_pk_fma_f32 v[74:75], v[74:75], v[40:41], v[118:119]
	v_pk_fma_f32 v[78:79], v[78:79], v[40:41], v[120:121]
	v_pk_mul_f32 v[122:123], v[72:73], v[42:43]
	v_pk_mul_f32 v[124:125], v[76:77], v[42:43]
	v_pk_fma_f32 v[122:123], v[74:75], v[44:45], v[122:123]
	v_pk_fma_f32 v[124:125], v[78:79], v[44:45], v[124:125]
	v_add_f32_e32 v126, v122, v123
	v_add_f32_e32 v127, v124, v125
	ds_write_b64 v187, v[126:127] offset:20480
	ds_read_b128 v[30:33], v161 offset:11264
	ds_read_b128 v[34:37], v161 offset:19456
	ds_read_b128 v[46:49], v161 offset:27648
	ds_read_b64 v[80:81], v82 offset:44032
	ds_read_b128 v[38:41], v161 offset:3072
	ds_read_b128 v[42:45], v161 offset:35840
	s_waitcnt lgkmcnt(7)
	v_pk_mul_f32 v[106:107], v[72:73], v[84:85]
	v_pk_mul_f32 v[108:109], v[76:77], v[84:85]
	v_pk_fma_f32 v[106:107], v[74:75], v[86:87], v[106:107]
	v_pk_fma_f32 v[108:109], v[78:79], v[86:87], v[108:109]
	v_add_f32_e32 v110, v106, v107
	v_add_f32_e32 v112, v108, v109
	s_nop 0
	v_add_f32_dpp v110, v110, v110 quad_perm:[1,0,3,2] row_mask:0xf bank_mask:0xf bound_ctrl:1
	v_add_f32_dpp v112, v112, v112 quad_perm:[1,0,3,2] row_mask:0xf bank_mask:0xf bound_ctrl:1
	s_nop 0
	v_add_f32_dpp v110, v110, v110 quad_perm:[2,3,0,1] row_mask:0xf bank_mask:0xf bound_ctrl:1
	v_add_f32_dpp v112, v112, v112 quad_perm:[2,3,0,1] row_mask:0xf bank_mask:0xf bound_ctrl:1
	s_nop 0
	v_add_f32_dpp v110, v110, v110 row_half_mirror row_mask:0xf bank_mask:0xf bound_ctrl:1
	v_add_f32_dpp v112, v112, v112 row_half_mirror row_mask:0xf bank_mask:0xf bound_ctrl:1
	s_nop 0
	v_add_f32_dpp v110, v110, v110 row_ror:8 row_mask:0xf bank_mask:0xf bound_ctrl:1
	v_add_f32_dpp v112, v112, v112 row_ror:8 row_mask:0xf bank_mask:0xf bound_ctrl:1
	v_pk_mul_f32 v[114:115], v[88:89], v[110:111] op_sel_hi:[1,0]
	v_pk_mul_f32 v[116:117], v[88:89], v[112:113] op_sel_hi:[1,0]
	v_pk_mul_f32 v[118:119], v[90:91], v[110:111] op_sel_hi:[1,0]
	v_pk_mul_f32 v[120:121], v[90:91], v[112:113] op_sel_hi:[1,0]
	v_pk_fma_f32 v[114:115], v[100:101], v[104:105], v[114:115] op_sel_hi:[1,0,1]
	v_pk_fma_f32 v[116:117], v[100:101], v[104:105], v[116:117] op_sel:[0,1,0]
	v_pk_fma_f32 v[118:119], v[102:103], v[104:105], v[118:119] op_sel_hi:[1,0,1]
	v_pk_fma_f32 v[120:121], v[102:103], v[104:105], v[120:121] op_sel:[0,1,0]
	v_pk_fma_f32 v[72:73], v[72:73], v[92:93], v[114:115]
	v_pk_fma_f32 v[76:77], v[76:77], v[92:93], v[116:117]
	v_pk_fma_f32 v[74:75], v[74:75], v[94:95], v[118:119]
	v_pk_fma_f32 v[78:79], v[78:79], v[94:95], v[120:121]
	v_pk_mul_f32 v[122:123], v[72:73], v[96:97]
	v_pk_mul_f32 v[124:125], v[76:77], v[96:97]
	v_pk_fma_f32 v[122:123], v[74:75], v[98:99], v[122:123]
	v_pk_fma_f32 v[124:125], v[78:79], v[98:99], v[124:125]
	v_add_f32_e32 v126, v122, v123
	v_add_f32_e32 v127, v124, v125
	ds_write_b64 v187, v[126:127] offset:22528
	ds_read_b128 v[84:87], v161 offset:11520
	ds_read_b128 v[88:91], v161 offset:19712
	ds_read_b128 v[100:103], v161 offset:27904
	ds_read_b64 v[104:105], v82 offset:44288
	ds_read_b128 v[92:95], v161 offset:3328
	ds_read_b128 v[96:99], v161 offset:36096
	s_waitcnt lgkmcnt(7)
	v_pk_mul_f32 v[106:107], v[72:73], v[30:31]
	v_pk_mul_f32 v[108:109], v[76:77], v[30:31]
	v_pk_fma_f32 v[106:107], v[74:75], v[32:33], v[106:107]
	v_pk_fma_f32 v[108:109], v[78:79], v[32:33], v[108:109]
	v_add_f32_e32 v110, v106, v107
	v_add_f32_e32 v112, v108, v109
	s_nop 0
	v_add_f32_dpp v110, v110, v110 quad_perm:[1,0,3,2] row_mask:0xf bank_mask:0xf bound_ctrl:1
	v_add_f32_dpp v112, v112, v112 quad_perm:[1,0,3,2] row_mask:0xf bank_mask:0xf bound_ctrl:1
	s_nop 0
	v_add_f32_dpp v110, v110, v110 quad_perm:[2,3,0,1] row_mask:0xf bank_mask:0xf bound_ctrl:1
	v_add_f32_dpp v112, v112, v112 quad_perm:[2,3,0,1] row_mask:0xf bank_mask:0xf bound_ctrl:1
	s_nop 0
	v_add_f32_dpp v110, v110, v110 row_half_mirror row_mask:0xf bank_mask:0xf bound_ctrl:1
	v_add_f32_dpp v112, v112, v112 row_half_mirror row_mask:0xf bank_mask:0xf bound_ctrl:1
	s_nop 0
	v_add_f32_dpp v110, v110, v110 row_ror:8 row_mask:0xf bank_mask:0xf bound_ctrl:1
	v_add_f32_dpp v112, v112, v112 row_ror:8 row_mask:0xf bank_mask:0xf bound_ctrl:1
	v_pk_mul_f32 v[114:115], v[34:35], v[110:111] op_sel_hi:[1,0]
	v_pk_mul_f32 v[116:117], v[34:35], v[112:113] op_sel_hi:[1,0]
	v_pk_mul_f32 v[118:119], v[36:37], v[110:111] op_sel_hi:[1,0]
	v_pk_mul_f32 v[120:121], v[36:37], v[112:113] op_sel_hi:[1,0]
	v_pk_fma_f32 v[114:115], v[46:47], v[80:81], v[114:115] op_sel_hi:[1,0,1]
	v_pk_fma_f32 v[116:117], v[46:47], v[80:81], v[116:117] op_sel:[0,1,0]
	v_pk_fma_f32 v[118:119], v[48:49], v[80:81], v[118:119] op_sel_hi:[1,0,1]
	v_pk_fma_f32 v[120:121], v[48:49], v[80:81], v[120:121] op_sel:[0,1,0]
	v_pk_fma_f32 v[72:73], v[72:73], v[38:39], v[114:115]
	v_pk_fma_f32 v[76:77], v[76:77], v[38:39], v[116:117]
	v_pk_fma_f32 v[74:75], v[74:75], v[40:41], v[118:119]
	v_pk_fma_f32 v[78:79], v[78:79], v[40:41], v[120:121]
	v_pk_mul_f32 v[122:123], v[72:73], v[42:43]
	v_pk_mul_f32 v[124:125], v[76:77], v[42:43]
	v_pk_fma_f32 v[122:123], v[74:75], v[44:45], v[122:123]
	v_pk_fma_f32 v[124:125], v[78:79], v[44:45], v[124:125]
	v_add_f32_e32 v126, v122, v123
	v_add_f32_e32 v127, v124, v125
	ds_write_b64 v187, v[126:127] offset:24576
	ds_read_b128 v[30:33], v161 offset:11776
	ds_read_b128 v[34:37], v161 offset:19968
	ds_read_b128 v[46:49], v161 offset:28160
	ds_read_b64 v[80:81], v82 offset:44544
	ds_read_b128 v[38:41], v161 offset:3584
	ds_read_b128 v[42:45], v161 offset:36352
	s_waitcnt lgkmcnt(7)
	v_pk_mul_f32 v[106:107], v[72:73], v[84:85]
	v_pk_mul_f32 v[108:109], v[76:77], v[84:85]
	v_pk_fma_f32 v[106:107], v[74:75], v[86:87], v[106:107]
	v_pk_fma_f32 v[108:109], v[78:79], v[86:87], v[108:109]
	v_add_f32_e32 v110, v106, v107
	v_add_f32_e32 v112, v108, v109
	s_nop 0
	v_add_f32_dpp v110, v110, v110 quad_perm:[1,0,3,2] row_mask:0xf bank_mask:0xf bound_ctrl:1
	v_add_f32_dpp v112, v112, v112 quad_perm:[1,0,3,2] row_mask:0xf bank_mask:0xf bound_ctrl:1
	s_nop 0
	v_add_f32_dpp v110, v110, v110 quad_perm:[2,3,0,1] row_mask:0xf bank_mask:0xf bound_ctrl:1
	v_add_f32_dpp v112, v112, v112 quad_perm:[2,3,0,1] row_mask:0xf bank_mask:0xf bound_ctrl:1
	s_nop 0
	v_add_f32_dpp v110, v110, v110 row_half_mirror row_mask:0xf bank_mask:0xf bound_ctrl:1
	v_add_f32_dpp v112, v112, v112 row_half_mirror row_mask:0xf bank_mask:0xf bound_ctrl:1
	s_nop 0
	v_add_f32_dpp v110, v110, v110 row_ror:8 row_mask:0xf bank_mask:0xf bound_ctrl:1
	v_add_f32_dpp v112, v112, v112 row_ror:8 row_mask:0xf bank_mask:0xf bound_ctrl:1
	v_pk_mul_f32 v[114:115], v[88:89], v[110:111] op_sel_hi:[1,0]
	v_pk_mul_f32 v[116:117], v[88:89], v[112:113] op_sel_hi:[1,0]
	v_pk_mul_f32 v[118:119], v[90:91], v[110:111] op_sel_hi:[1,0]
	v_pk_mul_f32 v[120:121], v[90:91], v[112:113] op_sel_hi:[1,0]
	v_pk_fma_f32 v[114:115], v[100:101], v[104:105], v[114:115] op_sel_hi:[1,0,1]
	v_pk_fma_f32 v[116:117], v[100:101], v[104:105], v[116:117] op_sel:[0,1,0]
	v_pk_fma_f32 v[118:119], v[102:103], v[104:105], v[118:119] op_sel_hi:[1,0,1]
	v_pk_fma_f32 v[120:121], v[102:103], v[104:105], v[120:121] op_sel:[0,1,0]
	v_pk_fma_f32 v[72:73], v[72:73], v[92:93], v[114:115]
	v_pk_fma_f32 v[76:77], v[76:77], v[92:93], v[116:117]
	v_pk_fma_f32 v[74:75], v[74:75], v[94:95], v[118:119]
	v_pk_fma_f32 v[78:79], v[78:79], v[94:95], v[120:121]
	v_pk_mul_f32 v[122:123], v[72:73], v[96:97]
	v_pk_mul_f32 v[124:125], v[76:77], v[96:97]
	v_pk_fma_f32 v[122:123], v[74:75], v[98:99], v[122:123]
	v_pk_fma_f32 v[124:125], v[78:79], v[98:99], v[124:125]
	v_add_f32_e32 v126, v122, v123
	v_add_f32_e32 v127, v124, v125
	ds_write_b64 v187, v[126:127] offset:26624
	ds_read_b128 v[84:87], v161 offset:12032
	ds_read_b128 v[88:91], v161 offset:20224
	ds_read_b128 v[100:103], v161 offset:28416
	ds_read_b64 v[104:105], v82 offset:44800
	ds_read_b128 v[92:95], v161 offset:3840
	ds_read_b128 v[96:99], v161 offset:36608
	s_waitcnt lgkmcnt(7)
	v_pk_mul_f32 v[106:107], v[72:73], v[30:31]
	v_pk_mul_f32 v[108:109], v[76:77], v[30:31]
	v_pk_fma_f32 v[106:107], v[74:75], v[32:33], v[106:107]
	v_pk_fma_f32 v[108:109], v[78:79], v[32:33], v[108:109]
	v_add_f32_e32 v110, v106, v107
	v_add_f32_e32 v112, v108, v109
	s_nop 0
	v_add_f32_dpp v110, v110, v110 quad_perm:[1,0,3,2] row_mask:0xf bank_mask:0xf bound_ctrl:1
	v_add_f32_dpp v112, v112, v112 quad_perm:[1,0,3,2] row_mask:0xf bank_mask:0xf bound_ctrl:1
	s_nop 0
	v_add_f32_dpp v110, v110, v110 quad_perm:[2,3,0,1] row_mask:0xf bank_mask:0xf bound_ctrl:1
	v_add_f32_dpp v112, v112, v112 quad_perm:[2,3,0,1] row_mask:0xf bank_mask:0xf bound_ctrl:1
	s_nop 0
	v_add_f32_dpp v110, v110, v110 row_half_mirror row_mask:0xf bank_mask:0xf bound_ctrl:1
	v_add_f32_dpp v112, v112, v112 row_half_mirror row_mask:0xf bank_mask:0xf bound_ctrl:1
	s_nop 0
	v_add_f32_dpp v110, v110, v110 row_ror:8 row_mask:0xf bank_mask:0xf bound_ctrl:1
	v_add_f32_dpp v112, v112, v112 row_ror:8 row_mask:0xf bank_mask:0xf bound_ctrl:1
	v_pk_mul_f32 v[114:115], v[34:35], v[110:111] op_sel_hi:[1,0]
	v_pk_mul_f32 v[116:117], v[34:35], v[112:113] op_sel_hi:[1,0]
	v_pk_mul_f32 v[118:119], v[36:37], v[110:111] op_sel_hi:[1,0]
	v_pk_mul_f32 v[120:121], v[36:37], v[112:113] op_sel_hi:[1,0]
	v_pk_fma_f32 v[114:115], v[46:47], v[80:81], v[114:115] op_sel_hi:[1,0,1]
	v_pk_fma_f32 v[116:117], v[46:47], v[80:81], v[116:117] op_sel:[0,1,0]
	v_pk_fma_f32 v[118:119], v[48:49], v[80:81], v[118:119] op_sel_hi:[1,0,1]
	v_pk_fma_f32 v[120:121], v[48:49], v[80:81], v[120:121] op_sel:[0,1,0]
	v_pk_fma_f32 v[72:73], v[72:73], v[38:39], v[114:115]
	v_pk_fma_f32 v[76:77], v[76:77], v[38:39], v[116:117]
	v_pk_fma_f32 v[74:75], v[74:75], v[40:41], v[118:119]
	v_pk_fma_f32 v[78:79], v[78:79], v[40:41], v[120:121]
	v_pk_mul_f32 v[122:123], v[72:73], v[42:43]
	v_pk_mul_f32 v[124:125], v[76:77], v[42:43]
	v_pk_fma_f32 v[122:123], v[74:75], v[44:45], v[122:123]
	v_pk_fma_f32 v[124:125], v[78:79], v[44:45], v[124:125]
	v_add_f32_e32 v126, v122, v123
	v_add_f32_e32 v127, v124, v125
	ds_write_b64 v187, v[126:127] offset:28672
	ds_read_b128 v[30:33], v161 offset:12288
	ds_read_b128 v[34:37], v161 offset:20480
	ds_read_b128 v[46:49], v161 offset:28672
	ds_read_b64 v[80:81], v82 offset:45056
	ds_read_b128 v[38:41], v161 offset:4096
	ds_read_b128 v[42:45], v161 offset:36864
	s_waitcnt lgkmcnt(7)
	v_pk_mul_f32 v[106:107], v[72:73], v[84:85]
	v_pk_mul_f32 v[108:109], v[76:77], v[84:85]
	v_pk_fma_f32 v[106:107], v[74:75], v[86:87], v[106:107]
	v_pk_fma_f32 v[108:109], v[78:79], v[86:87], v[108:109]
	v_add_f32_e32 v110, v106, v107
	v_add_f32_e32 v112, v108, v109
	s_nop 0
	v_add_f32_dpp v110, v110, v110 quad_perm:[1,0,3,2] row_mask:0xf bank_mask:0xf bound_ctrl:1
	v_add_f32_dpp v112, v112, v112 quad_perm:[1,0,3,2] row_mask:0xf bank_mask:0xf bound_ctrl:1
	s_nop 0
	v_add_f32_dpp v110, v110, v110 quad_perm:[2,3,0,1] row_mask:0xf bank_mask:0xf bound_ctrl:1
	v_add_f32_dpp v112, v112, v112 quad_perm:[2,3,0,1] row_mask:0xf bank_mask:0xf bound_ctrl:1
	s_nop 0
	v_add_f32_dpp v110, v110, v110 row_half_mirror row_mask:0xf bank_mask:0xf bound_ctrl:1
	v_add_f32_dpp v112, v112, v112 row_half_mirror row_mask:0xf bank_mask:0xf bound_ctrl:1
	s_nop 0
	v_add_f32_dpp v110, v110, v110 row_ror:8 row_mask:0xf bank_mask:0xf bound_ctrl:1
	v_add_f32_dpp v112, v112, v112 row_ror:8 row_mask:0xf bank_mask:0xf bound_ctrl:1
	v_pk_mul_f32 v[114:115], v[88:89], v[110:111] op_sel_hi:[1,0]
	v_pk_mul_f32 v[116:117], v[88:89], v[112:113] op_sel_hi:[1,0]
	v_pk_mul_f32 v[118:119], v[90:91], v[110:111] op_sel_hi:[1,0]
	v_pk_mul_f32 v[120:121], v[90:91], v[112:113] op_sel_hi:[1,0]
	v_pk_fma_f32 v[114:115], v[100:101], v[104:105], v[114:115] op_sel_hi:[1,0,1]
	v_pk_fma_f32 v[116:117], v[100:101], v[104:105], v[116:117] op_sel:[0,1,0]
	v_pk_fma_f32 v[118:119], v[102:103], v[104:105], v[118:119] op_sel_hi:[1,0,1]
	v_pk_fma_f32 v[120:121], v[102:103], v[104:105], v[120:121] op_sel:[0,1,0]
	v_pk_fma_f32 v[72:73], v[72:73], v[92:93], v[114:115]
	v_pk_fma_f32 v[76:77], v[76:77], v[92:93], v[116:117]
	v_pk_fma_f32 v[74:75], v[74:75], v[94:95], v[118:119]
	v_pk_fma_f32 v[78:79], v[78:79], v[94:95], v[120:121]
	v_pk_mul_f32 v[122:123], v[72:73], v[96:97]
	v_pk_mul_f32 v[124:125], v[76:77], v[96:97]
	v_pk_fma_f32 v[122:123], v[74:75], v[98:99], v[122:123]
	v_pk_fma_f32 v[124:125], v[78:79], v[98:99], v[124:125]
	v_add_f32_e32 v126, v122, v123
	v_add_f32_e32 v127, v124, v125
	ds_write_b64 v187, v[126:127] offset:30720
	ds_read_b128 v[84:87], v161 offset:12544
	ds_read_b128 v[88:91], v161 offset:20736
	ds_read_b128 v[100:103], v161 offset:28928
	ds_read_b64 v[104:105], v82 offset:45312
	ds_read_b128 v[92:95], v161 offset:4352
	ds_read_b128 v[96:99], v161 offset:37120
	s_waitcnt lgkmcnt(7)
	v_pk_mul_f32 v[106:107], v[72:73], v[30:31]
	v_pk_mul_f32 v[108:109], v[76:77], v[30:31]
	v_pk_fma_f32 v[106:107], v[74:75], v[32:33], v[106:107]
	v_pk_fma_f32 v[108:109], v[78:79], v[32:33], v[108:109]
	v_add_f32_e32 v110, v106, v107
	v_add_f32_e32 v112, v108, v109
	s_nop 0
	v_add_f32_dpp v110, v110, v110 quad_perm:[1,0,3,2] row_mask:0xf bank_mask:0xf bound_ctrl:1
	v_add_f32_dpp v112, v112, v112 quad_perm:[1,0,3,2] row_mask:0xf bank_mask:0xf bound_ctrl:1
	s_nop 0
	v_add_f32_dpp v110, v110, v110 quad_perm:[2,3,0,1] row_mask:0xf bank_mask:0xf bound_ctrl:1
	v_add_f32_dpp v112, v112, v112 quad_perm:[2,3,0,1] row_mask:0xf bank_mask:0xf bound_ctrl:1
	s_nop 0
	v_add_f32_dpp v110, v110, v110 row_half_mirror row_mask:0xf bank_mask:0xf bound_ctrl:1
	v_add_f32_dpp v112, v112, v112 row_half_mirror row_mask:0xf bank_mask:0xf bound_ctrl:1
	s_nop 0
	v_add_f32_dpp v110, v110, v110 row_ror:8 row_mask:0xf bank_mask:0xf bound_ctrl:1
	v_add_f32_dpp v112, v112, v112 row_ror:8 row_mask:0xf bank_mask:0xf bound_ctrl:1
	v_pk_mul_f32 v[114:115], v[34:35], v[110:111] op_sel_hi:[1,0]
	v_pk_mul_f32 v[116:117], v[34:35], v[112:113] op_sel_hi:[1,0]
	v_pk_mul_f32 v[118:119], v[36:37], v[110:111] op_sel_hi:[1,0]
	v_pk_mul_f32 v[120:121], v[36:37], v[112:113] op_sel_hi:[1,0]
	v_pk_fma_f32 v[114:115], v[46:47], v[80:81], v[114:115] op_sel_hi:[1,0,1]
	v_pk_fma_f32 v[116:117], v[46:47], v[80:81], v[116:117] op_sel:[0,1,0]
	v_pk_fma_f32 v[118:119], v[48:49], v[80:81], v[118:119] op_sel_hi:[1,0,1]
	v_pk_fma_f32 v[120:121], v[48:49], v[80:81], v[120:121] op_sel:[0,1,0]
	v_pk_fma_f32 v[72:73], v[72:73], v[38:39], v[114:115]
	v_pk_fma_f32 v[76:77], v[76:77], v[38:39], v[116:117]
	v_pk_fma_f32 v[74:75], v[74:75], v[40:41], v[118:119]
	v_pk_fma_f32 v[78:79], v[78:79], v[40:41], v[120:121]
	v_pk_mul_f32 v[122:123], v[72:73], v[42:43]
	v_pk_mul_f32 v[124:125], v[76:77], v[42:43]
	v_pk_fma_f32 v[122:123], v[74:75], v[44:45], v[122:123]
	v_pk_fma_f32 v[124:125], v[78:79], v[44:45], v[124:125]
	v_add_f32_e32 v126, v122, v123
	v_add_f32_e32 v127, v124, v125
	ds_write_b64 v187, v[126:127] offset:32768
	ds_read_b128 v[30:33], v161 offset:12800
	ds_read_b128 v[34:37], v161 offset:20992
	ds_read_b128 v[46:49], v161 offset:29184
	ds_read_b64 v[80:81], v82 offset:45568
	ds_read_b128 v[38:41], v161 offset:4608
	ds_read_b128 v[42:45], v161 offset:37376
	s_waitcnt lgkmcnt(7)
	v_pk_mul_f32 v[106:107], v[72:73], v[84:85]
	v_pk_mul_f32 v[108:109], v[76:77], v[84:85]
	v_pk_fma_f32 v[106:107], v[74:75], v[86:87], v[106:107]
	v_pk_fma_f32 v[108:109], v[78:79], v[86:87], v[108:109]
	v_add_f32_e32 v110, v106, v107
	v_add_f32_e32 v112, v108, v109
	s_nop 0
	v_add_f32_dpp v110, v110, v110 quad_perm:[1,0,3,2] row_mask:0xf bank_mask:0xf bound_ctrl:1
	v_add_f32_dpp v112, v112, v112 quad_perm:[1,0,3,2] row_mask:0xf bank_mask:0xf bound_ctrl:1
	s_nop 0
	v_add_f32_dpp v110, v110, v110 quad_perm:[2,3,0,1] row_mask:0xf bank_mask:0xf bound_ctrl:1
	v_add_f32_dpp v112, v112, v112 quad_perm:[2,3,0,1] row_mask:0xf bank_mask:0xf bound_ctrl:1
	s_nop 0
	v_add_f32_dpp v110, v110, v110 row_half_mirror row_mask:0xf bank_mask:0xf bound_ctrl:1
	v_add_f32_dpp v112, v112, v112 row_half_mirror row_mask:0xf bank_mask:0xf bound_ctrl:1
	s_nop 0
	v_add_f32_dpp v110, v110, v110 row_ror:8 row_mask:0xf bank_mask:0xf bound_ctrl:1
	v_add_f32_dpp v112, v112, v112 row_ror:8 row_mask:0xf bank_mask:0xf bound_ctrl:1
	v_pk_mul_f32 v[114:115], v[88:89], v[110:111] op_sel_hi:[1,0]
	v_pk_mul_f32 v[116:117], v[88:89], v[112:113] op_sel_hi:[1,0]
	v_pk_mul_f32 v[118:119], v[90:91], v[110:111] op_sel_hi:[1,0]
	v_pk_mul_f32 v[120:121], v[90:91], v[112:113] op_sel_hi:[1,0]
	v_pk_fma_f32 v[114:115], v[100:101], v[104:105], v[114:115] op_sel_hi:[1,0,1]
	v_pk_fma_f32 v[116:117], v[100:101], v[104:105], v[116:117] op_sel:[0,1,0]
	v_pk_fma_f32 v[118:119], v[102:103], v[104:105], v[118:119] op_sel_hi:[1,0,1]
	v_pk_fma_f32 v[120:121], v[102:103], v[104:105], v[120:121] op_sel:[0,1,0]
	v_pk_fma_f32 v[72:73], v[72:73], v[92:93], v[114:115]
	v_pk_fma_f32 v[76:77], v[76:77], v[92:93], v[116:117]
	v_pk_fma_f32 v[74:75], v[74:75], v[94:95], v[118:119]
	v_pk_fma_f32 v[78:79], v[78:79], v[94:95], v[120:121]
	v_pk_mul_f32 v[122:123], v[72:73], v[96:97]
	v_pk_mul_f32 v[124:125], v[76:77], v[96:97]
	v_pk_fma_f32 v[122:123], v[74:75], v[98:99], v[122:123]
	v_pk_fma_f32 v[124:125], v[78:79], v[98:99], v[124:125]
	v_add_f32_e32 v126, v122, v123
	v_add_f32_e32 v127, v124, v125
	ds_write_b64 v187, v[126:127] offset:34816
	ds_read_b128 v[84:87], v161 offset:13056
	ds_read_b128 v[88:91], v161 offset:21248
	ds_read_b128 v[100:103], v161 offset:29440
	ds_read_b64 v[104:105], v82 offset:45824
	ds_read_b128 v[92:95], v161 offset:4864
	ds_read_b128 v[96:99], v161 offset:37632
	s_waitcnt lgkmcnt(7)
	v_pk_mul_f32 v[106:107], v[72:73], v[30:31]
	v_pk_mul_f32 v[108:109], v[76:77], v[30:31]
	v_pk_fma_f32 v[106:107], v[74:75], v[32:33], v[106:107]
	v_pk_fma_f32 v[108:109], v[78:79], v[32:33], v[108:109]
	v_add_f32_e32 v110, v106, v107
	v_add_f32_e32 v112, v108, v109
	s_nop 0
	v_add_f32_dpp v110, v110, v110 quad_perm:[1,0,3,2] row_mask:0xf bank_mask:0xf bound_ctrl:1
	v_add_f32_dpp v112, v112, v112 quad_perm:[1,0,3,2] row_mask:0xf bank_mask:0xf bound_ctrl:1
	s_nop 0
	v_add_f32_dpp v110, v110, v110 quad_perm:[2,3,0,1] row_mask:0xf bank_mask:0xf bound_ctrl:1
	v_add_f32_dpp v112, v112, v112 quad_perm:[2,3,0,1] row_mask:0xf bank_mask:0xf bound_ctrl:1
	s_nop 0
	v_add_f32_dpp v110, v110, v110 row_half_mirror row_mask:0xf bank_mask:0xf bound_ctrl:1
	v_add_f32_dpp v112, v112, v112 row_half_mirror row_mask:0xf bank_mask:0xf bound_ctrl:1
	s_nop 0
	v_add_f32_dpp v110, v110, v110 row_ror:8 row_mask:0xf bank_mask:0xf bound_ctrl:1
	v_add_f32_dpp v112, v112, v112 row_ror:8 row_mask:0xf bank_mask:0xf bound_ctrl:1
	v_pk_mul_f32 v[114:115], v[34:35], v[110:111] op_sel_hi:[1,0]
	v_pk_mul_f32 v[116:117], v[34:35], v[112:113] op_sel_hi:[1,0]
	v_pk_mul_f32 v[118:119], v[36:37], v[110:111] op_sel_hi:[1,0]
	v_pk_mul_f32 v[120:121], v[36:37], v[112:113] op_sel_hi:[1,0]
	v_pk_fma_f32 v[114:115], v[46:47], v[80:81], v[114:115] op_sel_hi:[1,0,1]
	v_pk_fma_f32 v[116:117], v[46:47], v[80:81], v[116:117] op_sel:[0,1,0]
	v_pk_fma_f32 v[118:119], v[48:49], v[80:81], v[118:119] op_sel_hi:[1,0,1]
	v_pk_fma_f32 v[120:121], v[48:49], v[80:81], v[120:121] op_sel:[0,1,0]
	v_pk_fma_f32 v[72:73], v[72:73], v[38:39], v[114:115]
	v_pk_fma_f32 v[76:77], v[76:77], v[38:39], v[116:117]
	v_pk_fma_f32 v[74:75], v[74:75], v[40:41], v[118:119]
	v_pk_fma_f32 v[78:79], v[78:79], v[40:41], v[120:121]
	v_pk_mul_f32 v[122:123], v[72:73], v[42:43]
	v_pk_mul_f32 v[124:125], v[76:77], v[42:43]
	v_pk_fma_f32 v[122:123], v[74:75], v[44:45], v[122:123]
	v_pk_fma_f32 v[124:125], v[78:79], v[44:45], v[124:125]
	v_add_f32_e32 v126, v122, v123
	v_add_f32_e32 v127, v124, v125
	ds_write_b64 v187, v[126:127] offset:36864
	ds_read_b128 v[30:33], v161 offset:13312
	ds_read_b128 v[34:37], v161 offset:21504
	ds_read_b128 v[46:49], v161 offset:29696
	ds_read_b64 v[80:81], v82 offset:46080
	ds_read_b128 v[38:41], v161 offset:5120
	ds_read_b128 v[42:45], v161 offset:37888
	s_waitcnt lgkmcnt(7)
	v_pk_mul_f32 v[106:107], v[72:73], v[84:85]
	v_pk_mul_f32 v[108:109], v[76:77], v[84:85]
	v_pk_fma_f32 v[106:107], v[74:75], v[86:87], v[106:107]
	v_pk_fma_f32 v[108:109], v[78:79], v[86:87], v[108:109]
	v_add_f32_e32 v110, v106, v107
	v_add_f32_e32 v112, v108, v109
	s_nop 0
	v_add_f32_dpp v110, v110, v110 quad_perm:[1,0,3,2] row_mask:0xf bank_mask:0xf bound_ctrl:1
	v_add_f32_dpp v112, v112, v112 quad_perm:[1,0,3,2] row_mask:0xf bank_mask:0xf bound_ctrl:1
	s_nop 0
	v_add_f32_dpp v110, v110, v110 quad_perm:[2,3,0,1] row_mask:0xf bank_mask:0xf bound_ctrl:1
	v_add_f32_dpp v112, v112, v112 quad_perm:[2,3,0,1] row_mask:0xf bank_mask:0xf bound_ctrl:1
	s_nop 0
	v_add_f32_dpp v110, v110, v110 row_half_mirror row_mask:0xf bank_mask:0xf bound_ctrl:1
	v_add_f32_dpp v112, v112, v112 row_half_mirror row_mask:0xf bank_mask:0xf bound_ctrl:1
	s_nop 0
	v_add_f32_dpp v110, v110, v110 row_ror:8 row_mask:0xf bank_mask:0xf bound_ctrl:1
	v_add_f32_dpp v112, v112, v112 row_ror:8 row_mask:0xf bank_mask:0xf bound_ctrl:1
	v_pk_mul_f32 v[114:115], v[88:89], v[110:111] op_sel_hi:[1,0]
	v_pk_mul_f32 v[116:117], v[88:89], v[112:113] op_sel_hi:[1,0]
	v_pk_mul_f32 v[118:119], v[90:91], v[110:111] op_sel_hi:[1,0]
	v_pk_mul_f32 v[120:121], v[90:91], v[112:113] op_sel_hi:[1,0]
	v_pk_fma_f32 v[114:115], v[100:101], v[104:105], v[114:115] op_sel_hi:[1,0,1]
	v_pk_fma_f32 v[116:117], v[100:101], v[104:105], v[116:117] op_sel:[0,1,0]
	v_pk_fma_f32 v[118:119], v[102:103], v[104:105], v[118:119] op_sel_hi:[1,0,1]
	v_pk_fma_f32 v[120:121], v[102:103], v[104:105], v[120:121] op_sel:[0,1,0]
	v_pk_fma_f32 v[72:73], v[72:73], v[92:93], v[114:115]
	v_pk_fma_f32 v[76:77], v[76:77], v[92:93], v[116:117]
	v_pk_fma_f32 v[74:75], v[74:75], v[94:95], v[118:119]
	v_pk_fma_f32 v[78:79], v[78:79], v[94:95], v[120:121]
	v_pk_mul_f32 v[122:123], v[72:73], v[96:97]
	v_pk_mul_f32 v[124:125], v[76:77], v[96:97]
	v_pk_fma_f32 v[122:123], v[74:75], v[98:99], v[122:123]
	v_pk_fma_f32 v[124:125], v[78:79], v[98:99], v[124:125]
	v_add_f32_e32 v126, v122, v123
	v_add_f32_e32 v127, v124, v125
	ds_write_b64 v187, v[126:127] offset:38912
	ds_read_b128 v[84:87], v161 offset:13568
	ds_read_b128 v[88:91], v161 offset:21760
	ds_read_b128 v[100:103], v161 offset:29952
	ds_read_b64 v[104:105], v82 offset:46336
	ds_read_b128 v[92:95], v161 offset:5376
	ds_read_b128 v[96:99], v161 offset:38144
	s_waitcnt lgkmcnt(7)
	v_pk_mul_f32 v[106:107], v[72:73], v[30:31]
	v_pk_mul_f32 v[108:109], v[76:77], v[30:31]
	v_pk_fma_f32 v[106:107], v[74:75], v[32:33], v[106:107]
	v_pk_fma_f32 v[108:109], v[78:79], v[32:33], v[108:109]
	v_add_f32_e32 v110, v106, v107
	v_add_f32_e32 v112, v108, v109
	s_nop 0
	v_add_f32_dpp v110, v110, v110 quad_perm:[1,0,3,2] row_mask:0xf bank_mask:0xf bound_ctrl:1
	v_add_f32_dpp v112, v112, v112 quad_perm:[1,0,3,2] row_mask:0xf bank_mask:0xf bound_ctrl:1
	s_nop 0
	v_add_f32_dpp v110, v110, v110 quad_perm:[2,3,0,1] row_mask:0xf bank_mask:0xf bound_ctrl:1
	v_add_f32_dpp v112, v112, v112 quad_perm:[2,3,0,1] row_mask:0xf bank_mask:0xf bound_ctrl:1
	s_nop 0
	v_add_f32_dpp v110, v110, v110 row_half_mirror row_mask:0xf bank_mask:0xf bound_ctrl:1
	v_add_f32_dpp v112, v112, v112 row_half_mirror row_mask:0xf bank_mask:0xf bound_ctrl:1
	s_nop 0
	v_add_f32_dpp v110, v110, v110 row_ror:8 row_mask:0xf bank_mask:0xf bound_ctrl:1
	v_add_f32_dpp v112, v112, v112 row_ror:8 row_mask:0xf bank_mask:0xf bound_ctrl:1
	v_pk_mul_f32 v[114:115], v[34:35], v[110:111] op_sel_hi:[1,0]
	v_pk_mul_f32 v[116:117], v[34:35], v[112:113] op_sel_hi:[1,0]
	v_pk_mul_f32 v[118:119], v[36:37], v[110:111] op_sel_hi:[1,0]
	v_pk_mul_f32 v[120:121], v[36:37], v[112:113] op_sel_hi:[1,0]
	v_pk_fma_f32 v[114:115], v[46:47], v[80:81], v[114:115] op_sel_hi:[1,0,1]
	v_pk_fma_f32 v[116:117], v[46:47], v[80:81], v[116:117] op_sel:[0,1,0]
	v_pk_fma_f32 v[118:119], v[48:49], v[80:81], v[118:119] op_sel_hi:[1,0,1]
	v_pk_fma_f32 v[120:121], v[48:49], v[80:81], v[120:121] op_sel:[0,1,0]
	v_pk_fma_f32 v[72:73], v[72:73], v[38:39], v[114:115]
	v_pk_fma_f32 v[76:77], v[76:77], v[38:39], v[116:117]
	v_pk_fma_f32 v[74:75], v[74:75], v[40:41], v[118:119]
	v_pk_fma_f32 v[78:79], v[78:79], v[40:41], v[120:121]
	v_pk_mul_f32 v[122:123], v[72:73], v[42:43]
	v_pk_mul_f32 v[124:125], v[76:77], v[42:43]
	v_pk_fma_f32 v[122:123], v[74:75], v[44:45], v[122:123]
	v_pk_fma_f32 v[124:125], v[78:79], v[44:45], v[124:125]
	v_add_f32_e32 v126, v122, v123
	v_add_f32_e32 v127, v124, v125
	ds_write_b64 v187, v[126:127] offset:40960
	ds_read_b128 v[30:33], v161 offset:13824
	ds_read_b128 v[34:37], v161 offset:22016
	ds_read_b128 v[46:49], v161 offset:30208
	ds_read_b64 v[80:81], v82 offset:46592
	ds_read_b128 v[38:41], v161 offset:5632
	ds_read_b128 v[42:45], v161 offset:38400
	s_waitcnt lgkmcnt(7)
	v_pk_mul_f32 v[106:107], v[72:73], v[84:85]
	v_pk_mul_f32 v[108:109], v[76:77], v[84:85]
	v_pk_fma_f32 v[106:107], v[74:75], v[86:87], v[106:107]
	v_pk_fma_f32 v[108:109], v[78:79], v[86:87], v[108:109]
	v_add_f32_e32 v110, v106, v107
	v_add_f32_e32 v112, v108, v109
	s_nop 0
	v_add_f32_dpp v110, v110, v110 quad_perm:[1,0,3,2] row_mask:0xf bank_mask:0xf bound_ctrl:1
	v_add_f32_dpp v112, v112, v112 quad_perm:[1,0,3,2] row_mask:0xf bank_mask:0xf bound_ctrl:1
	s_nop 0
	v_add_f32_dpp v110, v110, v110 quad_perm:[2,3,0,1] row_mask:0xf bank_mask:0xf bound_ctrl:1
	v_add_f32_dpp v112, v112, v112 quad_perm:[2,3,0,1] row_mask:0xf bank_mask:0xf bound_ctrl:1
	s_nop 0
	v_add_f32_dpp v110, v110, v110 row_half_mirror row_mask:0xf bank_mask:0xf bound_ctrl:1
	v_add_f32_dpp v112, v112, v112 row_half_mirror row_mask:0xf bank_mask:0xf bound_ctrl:1
	s_nop 0
	v_add_f32_dpp v110, v110, v110 row_ror:8 row_mask:0xf bank_mask:0xf bound_ctrl:1
	v_add_f32_dpp v112, v112, v112 row_ror:8 row_mask:0xf bank_mask:0xf bound_ctrl:1
	v_pk_mul_f32 v[114:115], v[88:89], v[110:111] op_sel_hi:[1,0]
	v_pk_mul_f32 v[116:117], v[88:89], v[112:113] op_sel_hi:[1,0]
	v_pk_mul_f32 v[118:119], v[90:91], v[110:111] op_sel_hi:[1,0]
	v_pk_mul_f32 v[120:121], v[90:91], v[112:113] op_sel_hi:[1,0]
	v_pk_fma_f32 v[114:115], v[100:101], v[104:105], v[114:115] op_sel_hi:[1,0,1]
	v_pk_fma_f32 v[116:117], v[100:101], v[104:105], v[116:117] op_sel:[0,1,0]
	v_pk_fma_f32 v[118:119], v[102:103], v[104:105], v[118:119] op_sel_hi:[1,0,1]
	v_pk_fma_f32 v[120:121], v[102:103], v[104:105], v[120:121] op_sel:[0,1,0]
	v_pk_fma_f32 v[72:73], v[72:73], v[92:93], v[114:115]
	v_pk_fma_f32 v[76:77], v[76:77], v[92:93], v[116:117]
	v_pk_fma_f32 v[74:75], v[74:75], v[94:95], v[118:119]
	v_pk_fma_f32 v[78:79], v[78:79], v[94:95], v[120:121]
	v_pk_mul_f32 v[122:123], v[72:73], v[96:97]
	v_pk_mul_f32 v[124:125], v[76:77], v[96:97]
	v_pk_fma_f32 v[122:123], v[74:75], v[98:99], v[122:123]
	v_pk_fma_f32 v[124:125], v[78:79], v[98:99], v[124:125]
	v_add_f32_e32 v126, v122, v123
	v_add_f32_e32 v127, v124, v125
	ds_write_b64 v187, v[126:127] offset:43008
	ds_read_b128 v[84:87], v161 offset:14080
	ds_read_b128 v[88:91], v161 offset:22272
	ds_read_b128 v[100:103], v161 offset:30464
	ds_read_b64 v[104:105], v82 offset:46848
	ds_read_b128 v[92:95], v161 offset:5888
	ds_read_b128 v[96:99], v161 offset:38656
	s_waitcnt lgkmcnt(7)
	v_pk_mul_f32 v[106:107], v[72:73], v[30:31]
	v_pk_mul_f32 v[108:109], v[76:77], v[30:31]
	v_pk_fma_f32 v[106:107], v[74:75], v[32:33], v[106:107]
	v_pk_fma_f32 v[108:109], v[78:79], v[32:33], v[108:109]
	v_add_f32_e32 v110, v106, v107
	v_add_f32_e32 v112, v108, v109
	s_nop 0
	v_add_f32_dpp v110, v110, v110 quad_perm:[1,0,3,2] row_mask:0xf bank_mask:0xf bound_ctrl:1
	v_add_f32_dpp v112, v112, v112 quad_perm:[1,0,3,2] row_mask:0xf bank_mask:0xf bound_ctrl:1
	s_nop 0
	v_add_f32_dpp v110, v110, v110 quad_perm:[2,3,0,1] row_mask:0xf bank_mask:0xf bound_ctrl:1
	v_add_f32_dpp v112, v112, v112 quad_perm:[2,3,0,1] row_mask:0xf bank_mask:0xf bound_ctrl:1
	s_nop 0
	v_add_f32_dpp v110, v110, v110 row_half_mirror row_mask:0xf bank_mask:0xf bound_ctrl:1
	v_add_f32_dpp v112, v112, v112 row_half_mirror row_mask:0xf bank_mask:0xf bound_ctrl:1
	s_nop 0
	v_add_f32_dpp v110, v110, v110 row_ror:8 row_mask:0xf bank_mask:0xf bound_ctrl:1
	v_add_f32_dpp v112, v112, v112 row_ror:8 row_mask:0xf bank_mask:0xf bound_ctrl:1
	v_pk_mul_f32 v[114:115], v[34:35], v[110:111] op_sel_hi:[1,0]
	v_pk_mul_f32 v[116:117], v[34:35], v[112:113] op_sel_hi:[1,0]
	v_pk_mul_f32 v[118:119], v[36:37], v[110:111] op_sel_hi:[1,0]
	v_pk_mul_f32 v[120:121], v[36:37], v[112:113] op_sel_hi:[1,0]
	v_pk_fma_f32 v[114:115], v[46:47], v[80:81], v[114:115] op_sel_hi:[1,0,1]
	v_pk_fma_f32 v[116:117], v[46:47], v[80:81], v[116:117] op_sel:[0,1,0]
	v_pk_fma_f32 v[118:119], v[48:49], v[80:81], v[118:119] op_sel_hi:[1,0,1]
	v_pk_fma_f32 v[120:121], v[48:49], v[80:81], v[120:121] op_sel:[0,1,0]
	v_pk_fma_f32 v[72:73], v[72:73], v[38:39], v[114:115]
	v_pk_fma_f32 v[76:77], v[76:77], v[38:39], v[116:117]
	v_pk_fma_f32 v[74:75], v[74:75], v[40:41], v[118:119]
	v_pk_fma_f32 v[78:79], v[78:79], v[40:41], v[120:121]
	v_pk_mul_f32 v[122:123], v[72:73], v[42:43]
	v_pk_mul_f32 v[124:125], v[76:77], v[42:43]
	v_pk_fma_f32 v[122:123], v[74:75], v[44:45], v[122:123]
	v_pk_fma_f32 v[124:125], v[78:79], v[44:45], v[124:125]
	v_add_f32_e32 v126, v122, v123
	v_add_f32_e32 v127, v124, v125
	ds_write_b64 v187, v[126:127] offset:45056
	ds_read_b128 v[30:33], v161 offset:14336
	ds_read_b128 v[34:37], v161 offset:22528
	ds_read_b128 v[46:49], v161 offset:30720
	ds_read_b64 v[80:81], v82 offset:47104
	ds_read_b128 v[38:41], v161 offset:6144
	ds_read_b128 v[42:45], v161 offset:38912
	s_waitcnt lgkmcnt(7)
	v_pk_mul_f32 v[106:107], v[72:73], v[84:85]
	v_pk_mul_f32 v[108:109], v[76:77], v[84:85]
	v_pk_fma_f32 v[106:107], v[74:75], v[86:87], v[106:107]
	v_pk_fma_f32 v[108:109], v[78:79], v[86:87], v[108:109]
	v_add_f32_e32 v110, v106, v107
	v_add_f32_e32 v112, v108, v109
	s_nop 0
	v_add_f32_dpp v110, v110, v110 quad_perm:[1,0,3,2] row_mask:0xf bank_mask:0xf bound_ctrl:1
	v_add_f32_dpp v112, v112, v112 quad_perm:[1,0,3,2] row_mask:0xf bank_mask:0xf bound_ctrl:1
	s_nop 0
	v_add_f32_dpp v110, v110, v110 quad_perm:[2,3,0,1] row_mask:0xf bank_mask:0xf bound_ctrl:1
	v_add_f32_dpp v112, v112, v112 quad_perm:[2,3,0,1] row_mask:0xf bank_mask:0xf bound_ctrl:1
	s_nop 0
	v_add_f32_dpp v110, v110, v110 row_half_mirror row_mask:0xf bank_mask:0xf bound_ctrl:1
	v_add_f32_dpp v112, v112, v112 row_half_mirror row_mask:0xf bank_mask:0xf bound_ctrl:1
	s_nop 0
	v_add_f32_dpp v110, v110, v110 row_ror:8 row_mask:0xf bank_mask:0xf bound_ctrl:1
	v_add_f32_dpp v112, v112, v112 row_ror:8 row_mask:0xf bank_mask:0xf bound_ctrl:1
	v_pk_mul_f32 v[114:115], v[88:89], v[110:111] op_sel_hi:[1,0]
	v_pk_mul_f32 v[116:117], v[88:89], v[112:113] op_sel_hi:[1,0]
	v_pk_mul_f32 v[118:119], v[90:91], v[110:111] op_sel_hi:[1,0]
	v_pk_mul_f32 v[120:121], v[90:91], v[112:113] op_sel_hi:[1,0]
	v_pk_fma_f32 v[114:115], v[100:101], v[104:105], v[114:115] op_sel_hi:[1,0,1]
	v_pk_fma_f32 v[116:117], v[100:101], v[104:105], v[116:117] op_sel:[0,1,0]
	v_pk_fma_f32 v[118:119], v[102:103], v[104:105], v[118:119] op_sel_hi:[1,0,1]
	v_pk_fma_f32 v[120:121], v[102:103], v[104:105], v[120:121] op_sel:[0,1,0]
	v_pk_fma_f32 v[72:73], v[72:73], v[92:93], v[114:115]
	v_pk_fma_f32 v[76:77], v[76:77], v[92:93], v[116:117]
	v_pk_fma_f32 v[74:75], v[74:75], v[94:95], v[118:119]
	v_pk_fma_f32 v[78:79], v[78:79], v[94:95], v[120:121]
	v_pk_mul_f32 v[122:123], v[72:73], v[96:97]
	v_pk_mul_f32 v[124:125], v[76:77], v[96:97]
	v_pk_fma_f32 v[122:123], v[74:75], v[98:99], v[122:123]
	v_pk_fma_f32 v[124:125], v[78:79], v[98:99], v[124:125]
	v_add_f32_e32 v126, v122, v123
	v_add_f32_e32 v127, v124, v125
	ds_write_b64 v187, v[126:127] offset:47104
	ds_read_b128 v[84:87], v161 offset:14592
	ds_read_b128 v[88:91], v161 offset:22784
	ds_read_b128 v[100:103], v161 offset:30976
	ds_read_b64 v[104:105], v82 offset:47360
	ds_read_b128 v[92:95], v161 offset:6400
	ds_read_b128 v[96:99], v161 offset:39168
	s_waitcnt lgkmcnt(7)
	v_pk_mul_f32 v[106:107], v[72:73], v[30:31]
	v_pk_mul_f32 v[108:109], v[76:77], v[30:31]
	v_pk_fma_f32 v[106:107], v[74:75], v[32:33], v[106:107]
	v_pk_fma_f32 v[108:109], v[78:79], v[32:33], v[108:109]
	v_add_f32_e32 v110, v106, v107
	v_add_f32_e32 v112, v108, v109
	s_nop 0
	v_add_f32_dpp v110, v110, v110 quad_perm:[1,0,3,2] row_mask:0xf bank_mask:0xf bound_ctrl:1
	v_add_f32_dpp v112, v112, v112 quad_perm:[1,0,3,2] row_mask:0xf bank_mask:0xf bound_ctrl:1
	s_nop 0
	v_add_f32_dpp v110, v110, v110 quad_perm:[2,3,0,1] row_mask:0xf bank_mask:0xf bound_ctrl:1
	v_add_f32_dpp v112, v112, v112 quad_perm:[2,3,0,1] row_mask:0xf bank_mask:0xf bound_ctrl:1
	s_nop 0
	v_add_f32_dpp v110, v110, v110 row_half_mirror row_mask:0xf bank_mask:0xf bound_ctrl:1
	v_add_f32_dpp v112, v112, v112 row_half_mirror row_mask:0xf bank_mask:0xf bound_ctrl:1
	s_nop 0
	v_add_f32_dpp v110, v110, v110 row_ror:8 row_mask:0xf bank_mask:0xf bound_ctrl:1
	v_add_f32_dpp v112, v112, v112 row_ror:8 row_mask:0xf bank_mask:0xf bound_ctrl:1
	v_pk_mul_f32 v[114:115], v[34:35], v[110:111] op_sel_hi:[1,0]
	v_pk_mul_f32 v[116:117], v[34:35], v[112:113] op_sel_hi:[1,0]
	v_pk_mul_f32 v[118:119], v[36:37], v[110:111] op_sel_hi:[1,0]
	v_pk_mul_f32 v[120:121], v[36:37], v[112:113] op_sel_hi:[1,0]
	v_pk_fma_f32 v[114:115], v[46:47], v[80:81], v[114:115] op_sel_hi:[1,0,1]
	v_pk_fma_f32 v[116:117], v[46:47], v[80:81], v[116:117] op_sel:[0,1,0]
	v_pk_fma_f32 v[118:119], v[48:49], v[80:81], v[118:119] op_sel_hi:[1,0,1]
	v_pk_fma_f32 v[120:121], v[48:49], v[80:81], v[120:121] op_sel:[0,1,0]
	v_pk_fma_f32 v[72:73], v[72:73], v[38:39], v[114:115]
	v_pk_fma_f32 v[76:77], v[76:77], v[38:39], v[116:117]
	v_pk_fma_f32 v[74:75], v[74:75], v[40:41], v[118:119]
	v_pk_fma_f32 v[78:79], v[78:79], v[40:41], v[120:121]
	v_pk_mul_f32 v[122:123], v[72:73], v[42:43]
	v_pk_mul_f32 v[124:125], v[76:77], v[42:43]
	v_pk_fma_f32 v[122:123], v[74:75], v[44:45], v[122:123]
	v_pk_fma_f32 v[124:125], v[78:79], v[44:45], v[124:125]
	v_add_f32_e32 v126, v122, v123
	v_add_f32_e32 v127, v124, v125
	ds_write_b64 v187, v[126:127] offset:49152
	ds_read_b128 v[30:33], v161 offset:14848
	ds_read_b128 v[34:37], v161 offset:23040
	ds_read_b128 v[46:49], v161 offset:31232
	ds_read_b64 v[80:81], v82 offset:47616
	ds_read_b128 v[38:41], v161 offset:6656
	ds_read_b128 v[42:45], v161 offset:39424
	s_waitcnt lgkmcnt(7)
	v_pk_mul_f32 v[106:107], v[72:73], v[84:85]
	v_pk_mul_f32 v[108:109], v[76:77], v[84:85]
	v_pk_fma_f32 v[106:107], v[74:75], v[86:87], v[106:107]
	v_pk_fma_f32 v[108:109], v[78:79], v[86:87], v[108:109]
	v_add_f32_e32 v110, v106, v107
	v_add_f32_e32 v112, v108, v109
	s_nop 0
	v_add_f32_dpp v110, v110, v110 quad_perm:[1,0,3,2] row_mask:0xf bank_mask:0xf bound_ctrl:1
	v_add_f32_dpp v112, v112, v112 quad_perm:[1,0,3,2] row_mask:0xf bank_mask:0xf bound_ctrl:1
	s_nop 0
	v_add_f32_dpp v110, v110, v110 quad_perm:[2,3,0,1] row_mask:0xf bank_mask:0xf bound_ctrl:1
	v_add_f32_dpp v112, v112, v112 quad_perm:[2,3,0,1] row_mask:0xf bank_mask:0xf bound_ctrl:1
	s_nop 0
	v_add_f32_dpp v110, v110, v110 row_half_mirror row_mask:0xf bank_mask:0xf bound_ctrl:1
	v_add_f32_dpp v112, v112, v112 row_half_mirror row_mask:0xf bank_mask:0xf bound_ctrl:1
	s_nop 0
	v_add_f32_dpp v110, v110, v110 row_ror:8 row_mask:0xf bank_mask:0xf bound_ctrl:1
	v_add_f32_dpp v112, v112, v112 row_ror:8 row_mask:0xf bank_mask:0xf bound_ctrl:1
	v_pk_mul_f32 v[114:115], v[88:89], v[110:111] op_sel_hi:[1,0]
	v_pk_mul_f32 v[116:117], v[88:89], v[112:113] op_sel_hi:[1,0]
	v_pk_mul_f32 v[118:119], v[90:91], v[110:111] op_sel_hi:[1,0]
	v_pk_mul_f32 v[120:121], v[90:91], v[112:113] op_sel_hi:[1,0]
	v_pk_fma_f32 v[114:115], v[100:101], v[104:105], v[114:115] op_sel_hi:[1,0,1]
	v_pk_fma_f32 v[116:117], v[100:101], v[104:105], v[116:117] op_sel:[0,1,0]
	v_pk_fma_f32 v[118:119], v[102:103], v[104:105], v[118:119] op_sel_hi:[1,0,1]
	v_pk_fma_f32 v[120:121], v[102:103], v[104:105], v[120:121] op_sel:[0,1,0]
	v_pk_fma_f32 v[72:73], v[72:73], v[92:93], v[114:115]
	v_pk_fma_f32 v[76:77], v[76:77], v[92:93], v[116:117]
	v_pk_fma_f32 v[74:75], v[74:75], v[94:95], v[118:119]
	v_pk_fma_f32 v[78:79], v[78:79], v[94:95], v[120:121]
	v_pk_mul_f32 v[122:123], v[72:73], v[96:97]
	v_pk_mul_f32 v[124:125], v[76:77], v[96:97]
	v_pk_fma_f32 v[122:123], v[74:75], v[98:99], v[122:123]
	v_pk_fma_f32 v[124:125], v[78:79], v[98:99], v[124:125]
	v_add_f32_e32 v126, v122, v123
	v_add_f32_e32 v127, v124, v125
	ds_write_b64 v187, v[126:127] offset:51200
	ds_read_b128 v[84:87], v161 offset:15104
	ds_read_b128 v[88:91], v161 offset:23296
	ds_read_b128 v[100:103], v161 offset:31488
	ds_read_b64 v[104:105], v82 offset:47872
	ds_read_b128 v[92:95], v161 offset:6912
	ds_read_b128 v[96:99], v161 offset:39680
	s_waitcnt lgkmcnt(7)
	v_pk_mul_f32 v[106:107], v[72:73], v[30:31]
	v_pk_mul_f32 v[108:109], v[76:77], v[30:31]
	v_pk_fma_f32 v[106:107], v[74:75], v[32:33], v[106:107]
	v_pk_fma_f32 v[108:109], v[78:79], v[32:33], v[108:109]
	v_add_f32_e32 v110, v106, v107
	v_add_f32_e32 v112, v108, v109
	s_nop 0
	v_add_f32_dpp v110, v110, v110 quad_perm:[1,0,3,2] row_mask:0xf bank_mask:0xf bound_ctrl:1
	v_add_f32_dpp v112, v112, v112 quad_perm:[1,0,3,2] row_mask:0xf bank_mask:0xf bound_ctrl:1
	s_nop 0
	v_add_f32_dpp v110, v110, v110 quad_perm:[2,3,0,1] row_mask:0xf bank_mask:0xf bound_ctrl:1
	v_add_f32_dpp v112, v112, v112 quad_perm:[2,3,0,1] row_mask:0xf bank_mask:0xf bound_ctrl:1
	s_nop 0
	v_add_f32_dpp v110, v110, v110 row_half_mirror row_mask:0xf bank_mask:0xf bound_ctrl:1
	v_add_f32_dpp v112, v112, v112 row_half_mirror row_mask:0xf bank_mask:0xf bound_ctrl:1
	s_nop 0
	v_add_f32_dpp v110, v110, v110 row_ror:8 row_mask:0xf bank_mask:0xf bound_ctrl:1
	v_add_f32_dpp v112, v112, v112 row_ror:8 row_mask:0xf bank_mask:0xf bound_ctrl:1
	v_pk_mul_f32 v[114:115], v[34:35], v[110:111] op_sel_hi:[1,0]
	v_pk_mul_f32 v[116:117], v[34:35], v[112:113] op_sel_hi:[1,0]
	v_pk_mul_f32 v[118:119], v[36:37], v[110:111] op_sel_hi:[1,0]
	v_pk_mul_f32 v[120:121], v[36:37], v[112:113] op_sel_hi:[1,0]
	v_pk_fma_f32 v[114:115], v[46:47], v[80:81], v[114:115] op_sel_hi:[1,0,1]
	v_pk_fma_f32 v[116:117], v[46:47], v[80:81], v[116:117] op_sel:[0,1,0]
	v_pk_fma_f32 v[118:119], v[48:49], v[80:81], v[118:119] op_sel_hi:[1,0,1]
	v_pk_fma_f32 v[120:121], v[48:49], v[80:81], v[120:121] op_sel:[0,1,0]
	v_pk_fma_f32 v[72:73], v[72:73], v[38:39], v[114:115]
	v_pk_fma_f32 v[76:77], v[76:77], v[38:39], v[116:117]
	v_pk_fma_f32 v[74:75], v[74:75], v[40:41], v[118:119]
	v_pk_fma_f32 v[78:79], v[78:79], v[40:41], v[120:121]
	v_pk_mul_f32 v[122:123], v[72:73], v[42:43]
	v_pk_mul_f32 v[124:125], v[76:77], v[42:43]
	v_pk_fma_f32 v[122:123], v[74:75], v[44:45], v[122:123]
	v_pk_fma_f32 v[124:125], v[78:79], v[44:45], v[124:125]
	v_add_f32_e32 v126, v122, v123
	v_add_f32_e32 v127, v124, v125
	ds_write_b64 v187, v[126:127] offset:53248
	ds_read_b128 v[30:33], v161 offset:15360
	ds_read_b128 v[34:37], v161 offset:23552
	ds_read_b128 v[46:49], v161 offset:31744
	ds_read_b64 v[80:81], v82 offset:48128
	ds_read_b128 v[38:41], v161 offset:7168
	ds_read_b128 v[42:45], v161 offset:39936
	s_waitcnt lgkmcnt(7)
	v_pk_mul_f32 v[106:107], v[72:73], v[84:85]
	v_pk_mul_f32 v[108:109], v[76:77], v[84:85]
	v_pk_fma_f32 v[106:107], v[74:75], v[86:87], v[106:107]
	v_pk_fma_f32 v[108:109], v[78:79], v[86:87], v[108:109]
	v_add_f32_e32 v110, v106, v107
	v_add_f32_e32 v112, v108, v109
	s_nop 0
	v_add_f32_dpp v110, v110, v110 quad_perm:[1,0,3,2] row_mask:0xf bank_mask:0xf bound_ctrl:1
	v_add_f32_dpp v112, v112, v112 quad_perm:[1,0,3,2] row_mask:0xf bank_mask:0xf bound_ctrl:1
	s_nop 0
	v_add_f32_dpp v110, v110, v110 quad_perm:[2,3,0,1] row_mask:0xf bank_mask:0xf bound_ctrl:1
	v_add_f32_dpp v112, v112, v112 quad_perm:[2,3,0,1] row_mask:0xf bank_mask:0xf bound_ctrl:1
	s_nop 0
	v_add_f32_dpp v110, v110, v110 row_half_mirror row_mask:0xf bank_mask:0xf bound_ctrl:1
	v_add_f32_dpp v112, v112, v112 row_half_mirror row_mask:0xf bank_mask:0xf bound_ctrl:1
	s_nop 0
	v_add_f32_dpp v110, v110, v110 row_ror:8 row_mask:0xf bank_mask:0xf bound_ctrl:1
	v_add_f32_dpp v112, v112, v112 row_ror:8 row_mask:0xf bank_mask:0xf bound_ctrl:1
	v_pk_mul_f32 v[114:115], v[88:89], v[110:111] op_sel_hi:[1,0]
	v_pk_mul_f32 v[116:117], v[88:89], v[112:113] op_sel_hi:[1,0]
	v_pk_mul_f32 v[118:119], v[90:91], v[110:111] op_sel_hi:[1,0]
	v_pk_mul_f32 v[120:121], v[90:91], v[112:113] op_sel_hi:[1,0]
	v_pk_fma_f32 v[114:115], v[100:101], v[104:105], v[114:115] op_sel_hi:[1,0,1]
	v_pk_fma_f32 v[116:117], v[100:101], v[104:105], v[116:117] op_sel:[0,1,0]
	v_pk_fma_f32 v[118:119], v[102:103], v[104:105], v[118:119] op_sel_hi:[1,0,1]
	v_pk_fma_f32 v[120:121], v[102:103], v[104:105], v[120:121] op_sel:[0,1,0]
	v_pk_fma_f32 v[72:73], v[72:73], v[92:93], v[114:115]
	v_pk_fma_f32 v[76:77], v[76:77], v[92:93], v[116:117]
	v_pk_fma_f32 v[74:75], v[74:75], v[94:95], v[118:119]
	v_pk_fma_f32 v[78:79], v[78:79], v[94:95], v[120:121]
	v_pk_mul_f32 v[122:123], v[72:73], v[96:97]
	v_pk_mul_f32 v[124:125], v[76:77], v[96:97]
	v_pk_fma_f32 v[122:123], v[74:75], v[98:99], v[122:123]
	v_pk_fma_f32 v[124:125], v[78:79], v[98:99], v[124:125]
	v_add_f32_e32 v126, v122, v123
	v_add_f32_e32 v127, v124, v125
	ds_write_b64 v187, v[126:127] offset:55296
	ds_read_b128 v[84:87], v161 offset:15616
	ds_read_b128 v[88:91], v161 offset:23808
	ds_read_b128 v[100:103], v161 offset:32000
	ds_read_b64 v[104:105], v82 offset:48384
	ds_read_b128 v[92:95], v161 offset:7424
	ds_read_b128 v[96:99], v161 offset:40192
	s_waitcnt lgkmcnt(7)
	v_pk_mul_f32 v[106:107], v[72:73], v[30:31]
	v_pk_mul_f32 v[108:109], v[76:77], v[30:31]
	v_pk_fma_f32 v[106:107], v[74:75], v[32:33], v[106:107]
	v_pk_fma_f32 v[108:109], v[78:79], v[32:33], v[108:109]
	v_add_f32_e32 v110, v106, v107
	v_add_f32_e32 v112, v108, v109
	s_nop 0
	v_add_f32_dpp v110, v110, v110 quad_perm:[1,0,3,2] row_mask:0xf bank_mask:0xf bound_ctrl:1
	v_add_f32_dpp v112, v112, v112 quad_perm:[1,0,3,2] row_mask:0xf bank_mask:0xf bound_ctrl:1
	s_nop 0
	v_add_f32_dpp v110, v110, v110 quad_perm:[2,3,0,1] row_mask:0xf bank_mask:0xf bound_ctrl:1
	v_add_f32_dpp v112, v112, v112 quad_perm:[2,3,0,1] row_mask:0xf bank_mask:0xf bound_ctrl:1
	s_nop 0
	v_add_f32_dpp v110, v110, v110 row_half_mirror row_mask:0xf bank_mask:0xf bound_ctrl:1
	v_add_f32_dpp v112, v112, v112 row_half_mirror row_mask:0xf bank_mask:0xf bound_ctrl:1
	s_nop 0
	v_add_f32_dpp v110, v110, v110 row_ror:8 row_mask:0xf bank_mask:0xf bound_ctrl:1
	v_add_f32_dpp v112, v112, v112 row_ror:8 row_mask:0xf bank_mask:0xf bound_ctrl:1
	v_pk_mul_f32 v[114:115], v[34:35], v[110:111] op_sel_hi:[1,0]
	v_pk_mul_f32 v[116:117], v[34:35], v[112:113] op_sel_hi:[1,0]
	v_pk_mul_f32 v[118:119], v[36:37], v[110:111] op_sel_hi:[1,0]
	v_pk_mul_f32 v[120:121], v[36:37], v[112:113] op_sel_hi:[1,0]
	v_pk_fma_f32 v[114:115], v[46:47], v[80:81], v[114:115] op_sel_hi:[1,0,1]
	v_pk_fma_f32 v[116:117], v[46:47], v[80:81], v[116:117] op_sel:[0,1,0]
	v_pk_fma_f32 v[118:119], v[48:49], v[80:81], v[118:119] op_sel_hi:[1,0,1]
	v_pk_fma_f32 v[120:121], v[48:49], v[80:81], v[120:121] op_sel:[0,1,0]
	v_pk_fma_f32 v[72:73], v[72:73], v[38:39], v[114:115]
	v_pk_fma_f32 v[76:77], v[76:77], v[38:39], v[116:117]
	v_pk_fma_f32 v[74:75], v[74:75], v[40:41], v[118:119]
	v_pk_fma_f32 v[78:79], v[78:79], v[40:41], v[120:121]
	v_pk_mul_f32 v[122:123], v[72:73], v[42:43]
	v_pk_mul_f32 v[124:125], v[76:77], v[42:43]
	v_pk_fma_f32 v[122:123], v[74:75], v[44:45], v[122:123]
	v_pk_fma_f32 v[124:125], v[78:79], v[44:45], v[124:125]
	v_add_f32_e32 v126, v122, v123
	v_add_f32_e32 v127, v124, v125
	ds_write_b64 v187, v[126:127] offset:57344
	ds_read_b128 v[30:33], v161 offset:15872
	ds_read_b128 v[34:37], v161 offset:24064
	ds_read_b128 v[46:49], v161 offset:32256
	ds_read_b64 v[80:81], v82 offset:48640
	ds_read_b128 v[38:41], v161 offset:7680
	ds_read_b128 v[42:45], v161 offset:40448
	s_waitcnt lgkmcnt(7)
	v_pk_mul_f32 v[106:107], v[72:73], v[84:85]
	v_pk_mul_f32 v[108:109], v[76:77], v[84:85]
	v_pk_fma_f32 v[106:107], v[74:75], v[86:87], v[106:107]
	v_pk_fma_f32 v[108:109], v[78:79], v[86:87], v[108:109]
	v_add_f32_e32 v110, v106, v107
	v_add_f32_e32 v112, v108, v109
	s_nop 0
	v_add_f32_dpp v110, v110, v110 quad_perm:[1,0,3,2] row_mask:0xf bank_mask:0xf bound_ctrl:1
	v_add_f32_dpp v112, v112, v112 quad_perm:[1,0,3,2] row_mask:0xf bank_mask:0xf bound_ctrl:1
	s_nop 0
	v_add_f32_dpp v110, v110, v110 quad_perm:[2,3,0,1] row_mask:0xf bank_mask:0xf bound_ctrl:1
	v_add_f32_dpp v112, v112, v112 quad_perm:[2,3,0,1] row_mask:0xf bank_mask:0xf bound_ctrl:1
	s_nop 0
	v_add_f32_dpp v110, v110, v110 row_half_mirror row_mask:0xf bank_mask:0xf bound_ctrl:1
	v_add_f32_dpp v112, v112, v112 row_half_mirror row_mask:0xf bank_mask:0xf bound_ctrl:1
	s_nop 0
	v_add_f32_dpp v110, v110, v110 row_ror:8 row_mask:0xf bank_mask:0xf bound_ctrl:1
	v_add_f32_dpp v112, v112, v112 row_ror:8 row_mask:0xf bank_mask:0xf bound_ctrl:1
	v_pk_mul_f32 v[114:115], v[88:89], v[110:111] op_sel_hi:[1,0]
	v_pk_mul_f32 v[116:117], v[88:89], v[112:113] op_sel_hi:[1,0]
	v_pk_mul_f32 v[118:119], v[90:91], v[110:111] op_sel_hi:[1,0]
	v_pk_mul_f32 v[120:121], v[90:91], v[112:113] op_sel_hi:[1,0]
	v_pk_fma_f32 v[114:115], v[100:101], v[104:105], v[114:115] op_sel_hi:[1,0,1]
	v_pk_fma_f32 v[116:117], v[100:101], v[104:105], v[116:117] op_sel:[0,1,0]
	v_pk_fma_f32 v[118:119], v[102:103], v[104:105], v[118:119] op_sel_hi:[1,0,1]
	v_pk_fma_f32 v[120:121], v[102:103], v[104:105], v[120:121] op_sel:[0,1,0]
	v_pk_fma_f32 v[72:73], v[72:73], v[92:93], v[114:115]
	v_pk_fma_f32 v[76:77], v[76:77], v[92:93], v[116:117]
	v_pk_fma_f32 v[74:75], v[74:75], v[94:95], v[118:119]
	v_pk_fma_f32 v[78:79], v[78:79], v[94:95], v[120:121]
	v_pk_mul_f32 v[122:123], v[72:73], v[96:97]
	v_pk_mul_f32 v[124:125], v[76:77], v[96:97]
	v_pk_fma_f32 v[122:123], v[74:75], v[98:99], v[122:123]
	v_pk_fma_f32 v[124:125], v[78:79], v[98:99], v[124:125]
	v_add_f32_e32 v126, v122, v123
	v_add_f32_e32 v127, v124, v125
	ds_write_b64 v187, v[126:127] offset:59392
	ds_read_b128 v[84:87], v161 offset:16128
	ds_read_b128 v[88:91], v161 offset:24320
	ds_read_b128 v[100:103], v161 offset:32512
	ds_read_b64 v[104:105], v82 offset:48896
	ds_read_b128 v[92:95], v161 offset:7936
	ds_read_b128 v[96:99], v161 offset:40704
	s_waitcnt lgkmcnt(7)
	v_pk_mul_f32 v[106:107], v[72:73], v[30:31]
	v_pk_mul_f32 v[108:109], v[76:77], v[30:31]
	v_pk_fma_f32 v[106:107], v[74:75], v[32:33], v[106:107]
	v_pk_fma_f32 v[108:109], v[78:79], v[32:33], v[108:109]
	v_add_f32_e32 v110, v106, v107
	v_add_f32_e32 v112, v108, v109
	s_nop 0
	v_add_f32_dpp v110, v110, v110 quad_perm:[1,0,3,2] row_mask:0xf bank_mask:0xf bound_ctrl:1
	v_add_f32_dpp v112, v112, v112 quad_perm:[1,0,3,2] row_mask:0xf bank_mask:0xf bound_ctrl:1
	s_nop 0
	v_add_f32_dpp v110, v110, v110 quad_perm:[2,3,0,1] row_mask:0xf bank_mask:0xf bound_ctrl:1
	v_add_f32_dpp v112, v112, v112 quad_perm:[2,3,0,1] row_mask:0xf bank_mask:0xf bound_ctrl:1
	s_nop 0
	v_add_f32_dpp v110, v110, v110 row_half_mirror row_mask:0xf bank_mask:0xf bound_ctrl:1
	v_add_f32_dpp v112, v112, v112 row_half_mirror row_mask:0xf bank_mask:0xf bound_ctrl:1
	s_nop 0
	v_add_f32_dpp v110, v110, v110 row_ror:8 row_mask:0xf bank_mask:0xf bound_ctrl:1
	v_add_f32_dpp v112, v112, v112 row_ror:8 row_mask:0xf bank_mask:0xf bound_ctrl:1
	v_pk_mul_f32 v[114:115], v[34:35], v[110:111] op_sel_hi:[1,0]
	v_pk_mul_f32 v[116:117], v[34:35], v[112:113] op_sel_hi:[1,0]
	v_pk_mul_f32 v[118:119], v[36:37], v[110:111] op_sel_hi:[1,0]
	v_pk_mul_f32 v[120:121], v[36:37], v[112:113] op_sel_hi:[1,0]
	v_pk_fma_f32 v[114:115], v[46:47], v[80:81], v[114:115] op_sel_hi:[1,0,1]
	v_pk_fma_f32 v[116:117], v[46:47], v[80:81], v[116:117] op_sel:[0,1,0]
	v_pk_fma_f32 v[118:119], v[48:49], v[80:81], v[118:119] op_sel_hi:[1,0,1]
	v_pk_fma_f32 v[120:121], v[48:49], v[80:81], v[120:121] op_sel:[0,1,0]
	v_pk_fma_f32 v[72:73], v[72:73], v[38:39], v[114:115]
	v_pk_fma_f32 v[76:77], v[76:77], v[38:39], v[116:117]
	v_pk_fma_f32 v[74:75], v[74:75], v[40:41], v[118:119]
	v_pk_fma_f32 v[78:79], v[78:79], v[40:41], v[120:121]
	v_pk_mul_f32 v[122:123], v[72:73], v[42:43]
	v_pk_mul_f32 v[124:125], v[76:77], v[42:43]
	v_pk_fma_f32 v[122:123], v[74:75], v[44:45], v[122:123]
	v_pk_fma_f32 v[124:125], v[78:79], v[44:45], v[124:125]
	v_add_f32_e32 v126, v122, v123
	v_add_f32_e32 v127, v124, v125
	ds_write_b64 v187, v[126:127] offset:61440
	s_waitcnt lgkmcnt(1)
	v_pk_mul_f32 v[106:107], v[72:73], v[84:85]
	v_pk_mul_f32 v[108:109], v[76:77], v[84:85]
	v_pk_fma_f32 v[106:107], v[74:75], v[86:87], v[106:107]
	v_pk_fma_f32 v[108:109], v[78:79], v[86:87], v[108:109]
	v_add_f32_e32 v110, v106, v107
	v_add_f32_e32 v112, v108, v109
	s_nop 0
	v_add_f32_dpp v110, v110, v110 quad_perm:[1,0,3,2] row_mask:0xf bank_mask:0xf bound_ctrl:1
	v_add_f32_dpp v112, v112, v112 quad_perm:[1,0,3,2] row_mask:0xf bank_mask:0xf bound_ctrl:1
	s_nop 0
	v_add_f32_dpp v110, v110, v110 quad_perm:[2,3,0,1] row_mask:0xf bank_mask:0xf bound_ctrl:1
	v_add_f32_dpp v112, v112, v112 quad_perm:[2,3,0,1] row_mask:0xf bank_mask:0xf bound_ctrl:1
	s_nop 0
	v_add_f32_dpp v110, v110, v110 row_half_mirror row_mask:0xf bank_mask:0xf bound_ctrl:1
	v_add_f32_dpp v112, v112, v112 row_half_mirror row_mask:0xf bank_mask:0xf bound_ctrl:1
	s_nop 0
	v_add_f32_dpp v110, v110, v110 row_ror:8 row_mask:0xf bank_mask:0xf bound_ctrl:1
	v_add_f32_dpp v112, v112, v112 row_ror:8 row_mask:0xf bank_mask:0xf bound_ctrl:1
	v_pk_mul_f32 v[114:115], v[88:89], v[110:111] op_sel_hi:[1,0]
	v_pk_mul_f32 v[116:117], v[88:89], v[112:113] op_sel_hi:[1,0]
	v_pk_mul_f32 v[118:119], v[90:91], v[110:111] op_sel_hi:[1,0]
	v_pk_mul_f32 v[120:121], v[90:91], v[112:113] op_sel_hi:[1,0]
	v_pk_fma_f32 v[114:115], v[100:101], v[104:105], v[114:115] op_sel_hi:[1,0,1]
	v_pk_fma_f32 v[116:117], v[100:101], v[104:105], v[116:117] op_sel:[0,1,0]
	v_pk_fma_f32 v[118:119], v[102:103], v[104:105], v[118:119] op_sel_hi:[1,0,1]
	v_pk_fma_f32 v[120:121], v[102:103], v[104:105], v[120:121] op_sel:[0,1,0]
	v_pk_fma_f32 v[72:73], v[72:73], v[92:93], v[114:115]
	v_pk_fma_f32 v[76:77], v[76:77], v[92:93], v[116:117]
	v_pk_fma_f32 v[74:75], v[74:75], v[94:95], v[118:119]
	v_pk_fma_f32 v[78:79], v[78:79], v[94:95], v[120:121]
	v_pk_mul_f32 v[122:123], v[72:73], v[96:97]
	v_pk_mul_f32 v[124:125], v[76:77], v[96:97]
	v_pk_fma_f32 v[122:123], v[74:75], v[98:99], v[122:123]
	v_pk_fma_f32 v[124:125], v[78:79], v[98:99], v[124:125]
	v_add_f32_e32 v126, v122, v123
	v_add_f32_e32 v127, v124, v125
	ds_write_b64 v187, v[126:127] offset:63488
